# v9: attention DPP reductions; nt hints on read-once streams (retc DMA+gates, scan, combine, phase-0 x/w loads), nt on OR/OA stores; down-GEMM row panels reversed
# speedup vs baseline: 1.0464x; 1.0279x over previous
; #define LAS __attribute__((address_space(3)))
; __device__ __forceinline__ unsigned cvt_pk_bf16(float lo, float hi) { unsigned r; asm volatile("v_cvt_pk_bf16_f32 %0, %1, %2" : "=v"(r) : "v"(lo), "v"(hi)); return r; }
; __device__ __forceinline__ void transpose_w(const int wv, LAS unsigned char* lds, const float* __restrict__ w, bf16_t* __restrict__ wt, int K, int N, const float* __restrict__ gk, int slo, int shi, float scale) {
;     const int tk = K / 64, tn = N / 64, nt = tk * tn;
;     const int t = TIDX, nl = t & 63, kg = t >> 6, n2 = t >> 3, kc = t & 7;
;     for (int tile = blockIdx.x; tile < nt; tile += gridDim.x) {
;         const int kt0 = (tile % tk) * 64, nb0 = (tile / tk) * 64;
;         const int k0 = kt0 + kg * 8, n = nb0 + nl;
;         float v[8];
; #pragma unroll
;         for (int j = 0; j < 8; ++j) { float g = gk ? gk[k0 + j] : 1.0f; v[j] = w[(size_t)(k0 + j) * N + n] * g; }
;         if (n >= slo && n < shi) {
; #pragma unroll
;             for (int j = 0; j < 8; ++j) v[j] *= scale;
;         }
;         u32x4 o; o.x = cvt_pk_bf16(v[0], v[1]); o.y = cvt_pk_bf16(v[2], v[3]); o.z = cvt_pk_bf16(v[4], v[5]); o.w = cvt_pk_bf16(v[6], v[7]);
;         *(LAS u32x4*)(lds + nl * 144 + kg * 16) = o;
;         __syncthreads();
;         *(u32x4*)(wt + (size_t)(nb0 + n2) * K + kt0 + kc * 8) = *(const LAS u32x4*)(lds + n2 * 144 + kc * 16);
;         __syncthreads();
;     }
.LBB0_7:
	v_add_u32_e32 v4, 7, v4
	v_mad_i64_i32 v[6:7], s[20:21], v4, s15, v[8:9]
	global_load_dword v29, v[6:7], off nt
	s_sub_i32 s18, 0, s18
	s_add_i32 s19, s17, 0xffffea00
	s_add_i32 s18, s13, s18
	s_waitcnt vmcnt(7)
	v_mul_f32_e32 v4, v5, v16
	s_waitcnt vmcnt(6)
	v_mul_f32_e32 v5, v15, v18
	s_waitcnt vmcnt(5)
	v_mul_f32_e32 v6, v20, v21
	s_waitcnt vmcnt(4)
	v_mul_f32_e32 v7, v19, v22
	s_cmpk_lt_u32 s19, 0x400
	s_waitcnt vmcnt(3)
	v_mul_f32_e32 v8, v24, v25
	s_waitcnt vmcnt(2)
	v_mul_f32_e32 v9, v23, v26
	s_waitcnt vmcnt(1)
	v_mul_f32_e32 v16, v27, v28
	v_pk_mul_f32 v[20:21], v[4:5], s[12:13] op_sel_hi:[1,0]
	v_pk_mul_f32 v[22:23], v[6:7], s[12:13] op_sel_hi:[1,0]
	s_cselect_b64 vcc, -1, 0
	v_pk_mul_f32 v[24:25], v[8:9], s[12:13] op_sel_hi:[1,0]
	v_cndmask_b32_e32 v6, v6, v22, vcc
	v_cndmask_b32_e32 v7, v7, v23, vcc
	v_cndmask_b32_e32 v4, v4, v20, vcc
	v_cndmask_b32_e32 v5, v5, v21, vcc
	v_add_u32_e32 v18, s17, v11
	v_cndmask_b32_e32 v8, v8, v24, vcc
	v_cndmask_b32_e32 v9, v9, v25, vcc
	v_cvt_pk_bf16_f32 v4, v4, v5
	v_cvt_pk_bf16_f32 v5, v6, v7
	v_cvt_pk_bf16_f32 v6, v8, v9
	v_ashrrev_i32_e32 v19, 31, v18
	v_lshlrev_b64 v[18:19], 11, v[18:19]
	v_lshl_add_u64 v[18:19], s[10:11], 0, v[18:19]
	s_ashr_i32 s19, s18, 31
	s_add_i32 s16, s16, s54
	v_lshl_add_u64 v[8:9], s[18:19], 1, v[18:19]
	v_lshl_add_u64 v[8:9], v[8:9], 0, v[2:3]
	s_waitcnt vmcnt(0)
	v_mul_f32_e32 v17, v17, v29
	v_pk_mul_f32 v[26:27], v[16:17], s[12:13] op_sel_hi:[1,0]
	s_add_i32 s13, s13, s14
	v_cndmask_b32_e32 v15, v16, v26, vcc
	v_cndmask_b32_e32 v16, v17, v27, vcc
	v_cvt_pk_bf16_f32 v7, v15, v16
	ds_write_b128 v13, v[4:7]
	s_waitcnt lgkmcnt(0)
	s_barrier
	ds_read_b128 v[4:7], v14
	s_cmpk_lt_i32 s16, 0xc80
	s_waitcnt lgkmcnt(0)
	global_store_dwordx4 v[8:9], v[4:7], off
	s_barrier
	s_cbranch_scc0 .LBB0_24
.LBB0_8:
	s_ashr_i32 s17, s16, 31
	s_lshr_b32 s17, s17, 28
	s_add_i32 s17, s16, s17
	s_ashr_i32 s17, s17, 4
	s_lshl_b32 s18, s17, 10
	s_sub_i32 s19, s13, s18
	v_add_u32_e32 v4, s19, v12
	v_ashrrev_i32_e32 v5, 31, v4
	v_mov_b32_e32 v15, 1.0
	s_and_b64 vcc, exec, s[0:1]
	v_lshl_add_u64 v[6:7], v[4:5], 2, s[4:5]
	v_mov_b32_e32 v5, 1.0
	s_cbranch_vccnz .LBB0_10
	global_load_dword v5, v[6:7], off nt
.LBB0_10:
	s_lshl_b32 s17, s17, 6
	v_or_b32_e32 v8, s17, v10
	v_ashrrev_i32_e32 v9, 31, v8
	v_lshl_add_u64 v[8:9], v[8:9], 2, s[6:7]
	v_mad_i64_i32 v[16:17], s[20:21], v4, s15, v[8:9]
	global_load_dword v16, v[16:17], off nt
	s_and_b64 vcc, exec, s[0:1]
	s_cbranch_vccnz .LBB0_12
	global_load_dword v15, v[6:7], off offset:4 nt
.LBB0_12:
	v_add_u32_e32 v17, 1, v4
	v_mad_i64_i32 v[18:19], s[20:21], v17, s15, v[8:9]
	global_load_dword v18, v[18:19], off nt
	v_mov_b32_e32 v19, 1.0
	s_and_b64 vcc, exec, s[0:1]
	v_mov_b32_e32 v20, 1.0
	s_cbranch_vccnz .LBB0_14
	global_load_dword v20, v[6:7], off offset:8 nt
.LBB0_14:
	v_add_u32_e32 v17, 2, v4
	v_mad_i64_i32 v[22:23], s[20:21], v17, s15, v[8:9]
	global_load_dword v21, v[22:23], off nt
	s_and_b64 vcc, exec, s[0:1]
	s_cbranch_vccnz .LBB0_16
	global_load_dword v19, v[6:7], off offset:12 nt
.LBB0_16:
	v_add_u32_e32 v17, 3, v4
	v_mad_i64_i32 v[22:23], s[20:21], v17, s15, v[8:9]
	global_load_dword v22, v[22:23], off nt
	v_mov_b32_e32 v23, 1.0
	s_and_b64 vcc, exec, s[0:1]
	v_mov_b32_e32 v24, 1.0
	s_cbranch_vccnz .LBB0_18
	global_load_dword v24, v[6:7], off offset:16 nt
.LBB0_18:
	v_add_u32_e32 v17, 4, v4
	v_mad_i64_i32 v[26:27], s[20:21], v17, s15, v[8:9]
	global_load_dword v25, v[26:27], off nt
	s_and_b64 vcc, exec, s[0:1]
	s_cbranch_vccnz .LBB0_20
	global_load_dword v23, v[6:7], off offset:20 nt
.LBB0_20:
	v_add_u32_e32 v17, 5, v4
	v_mad_i64_i32 v[26:27], s[20:21], v17, s15, v[8:9]
	global_load_dword v26, v[26:27], off nt
	v_mov_b32_e32 v17, 1.0
	s_and_b64 vcc, exec, s[0:1]
	v_mov_b32_e32 v27, 1.0
	s_cbranch_vccnz .LBB0_22
	global_load_dword v27, v[6:7], off offset:24 nt
.LBB0_22:
	v_add_u32_e32 v28, 6, v4
	v_mad_i64_i32 v[28:29], s[20:21], v28, s15, v[8:9]
	global_load_dword v28, v[28:29], off nt
	s_and_b64 vcc, exec, s[0:1]
	s_cbranch_vccnz .LBB0_7
	global_load_dword v17, v[6:7], off offset:28 nt
	s_branch .LBB0_7

; #define LAS __attribute__((address_space(3)))
; __device__ __forceinline__ unsigned cvt_pk_bf16(float lo, float hi) { unsigned r; asm volatile("v_cvt_pk_bf16_f32 %0, %1, %2" : "=v"(r) : "v"(lo), "v"(hi)); return r; }
; __device__ __forceinline__ void transpose_w(const int wv, LAS unsigned char* lds, const float* __restrict__ w, bf16_t* __restrict__ wt, int K, int N, const float* __restrict__ gk, int slo, int shi, float scale) {
;     const int tk = K / 64, tn = N / 64, nt = tk * tn;
;     const int t = TIDX, nl = t & 63, kg = t >> 6, n2 = t >> 3, kc = t & 7;
;     for (int tile = blockIdx.x; tile < nt; tile += gridDim.x) {
;         const int kt0 = (tile % tk) * 64, nb0 = (tile / tk) * 64;
;         const int k0 = kt0 + kg * 8, n = nb0 + nl;
;         float v[8];
; #pragma unroll
;         for (int j = 0; j < 8; ++j) { float g = gk ? gk[k0 + j] : 1.0f; v[j] = w[(size_t)(k0 + j) * N + n] * g; }
;         if (n >= slo && n < shi) {
; #pragma unroll
;             for (int j = 0; j < 8; ++j) v[j] *= scale;
;         }
;         u32x4 o; o.x = cvt_pk_bf16(v[0], v[1]); o.y = cvt_pk_bf16(v[2], v[3]); o.z = cvt_pk_bf16(v[4], v[5]); o.w = cvt_pk_bf16(v[6], v[7]);
;         *(LAS u32x4*)(lds + nl * 144 + kg * 16) = o;
;         __syncthreads();
;         *(u32x4*)(wt + (size_t)(nb0 + n2) * K + kt0 + kc * 8) = *(const LAS u32x4*)(lds + n2 * 144 + kc * 16);
;         __syncthreads();
;     }
.LBB0_26:
	s_ashr_i32 s6, s14, 31
	s_lshr_b32 s6, s6, 29
	s_add_i32 s6, s14, s6
	s_ashr_i32 s6, s6, 3
	s_lshl_b32 s7, s6, 9
	s_lshl_b32 s15, s6, 6
	s_sub_i32 s6, s12, s7
	v_or_b32_e32 v10, s15, v4
	v_add_u32_e32 v12, s6, v6
	v_ashrrev_i32_e32 v11, 31, v10
	v_ashrrev_i32_e32 v13, 31, v12
	v_add_u32_e32 v14, 1, v12
	v_add_u32_e32 v16, 2, v12
	v_add_u32_e32 v18, 3, v12
	v_add_u32_e32 v20, 4, v12
	v_add_u32_e32 v22, 5, v12
	v_add_u32_e32 v24, 6, v12
	v_add_u32_e32 v26, 7, v12
	v_lshl_add_u64 v[10:11], v[10:11], 2, s[0:1]
	v_lshlrev_b64 v[12:13], 12, v[12:13]
	v_ashrrev_i32_e32 v15, 31, v14
	v_ashrrev_i32_e32 v17, 31, v16
	v_ashrrev_i32_e32 v19, 31, v18
	v_ashrrev_i32_e32 v21, 31, v20
	v_ashrrev_i32_e32 v23, 31, v22
	v_ashrrev_i32_e32 v25, 31, v24
	v_ashrrev_i32_e32 v27, 31, v26
	v_lshl_add_u64 v[12:13], v[10:11], 0, v[12:13]
	v_lshlrev_b64 v[14:15], 12, v[14:15]
	v_lshlrev_b64 v[16:17], 12, v[16:17]
	v_lshlrev_b64 v[18:19], 12, v[18:19]
	v_lshlrev_b64 v[20:21], 12, v[20:21]
	v_lshlrev_b64 v[22:23], 12, v[22:23]
	v_lshlrev_b64 v[24:25], 12, v[24:25]
	v_lshlrev_b64 v[26:27], 12, v[26:27]
	v_lshl_add_u64 v[14:15], v[10:11], 0, v[14:15]
	v_lshl_add_u64 v[16:17], v[10:11], 0, v[16:17]
	v_lshl_add_u64 v[18:19], v[10:11], 0, v[18:19]
	v_lshl_add_u64 v[20:21], v[10:11], 0, v[20:21]
	v_lshl_add_u64 v[22:23], v[10:11], 0, v[22:23]
	v_lshl_add_u64 v[24:25], v[10:11], 0, v[24:25]
	v_lshl_add_u64 v[10:11], v[10:11], 0, v[26:27]
	global_load_dword v9, v[12:13], off nt
	global_load_dword v26, v[14:15], off nt
	global_load_dword v27, v[18:19], off nt
	global_load_dword v28, v[24:25], off nt
	global_load_dword v29, v[20:21], off nt
	global_load_dword v30, v[16:17], off nt
	global_load_dword v31, v[22:23], off nt
	global_load_dword v32, v[10:11], off nt
	v_add_u32_e32 v10, s15, v5
	v_ashrrev_i32_e32 v11, 31, v10
	v_lshlrev_b64 v[10:11], 10, v[10:11]
	s_ashr_i32 s7, s6, 31
	v_lshl_add_u64 v[10:11], s[4:5], 0, v[10:11]
	v_lshl_add_u64 v[14:15], s[6:7], 1, v[10:11]
	s_add_i32 s14, s14, s54
	s_add_i32 s12, s12, s13
	s_cmpk_lt_i32 s14, 0x80
	v_lshl_add_u64 v[14:15], v[14:15], 0, v[2:3]
	s_waitcnt vmcnt(6)
	v_cvt_pk_bf16_f32 v10, v9, v26
	s_waitcnt vmcnt(2)
	v_cvt_pk_bf16_f32 v11, v30, v27
	s_waitcnt vmcnt(1)
	v_cvt_pk_bf16_f32 v12, v29, v31
	s_waitcnt vmcnt(0)
	v_cvt_pk_bf16_f32 v13, v28, v32
	ds_write_b128 v7, v[10:13]
	s_waitcnt lgkmcnt(0)
	s_barrier
	ds_read_b128 v[10:13], v8
	s_waitcnt lgkmcnt(0)
	global_store_dwordx4 v[14:15], v[10:13], off
	s_barrier
	s_cbranch_scc1 .LBB0_26

; #define LAS __attribute__((address_space(3)))
; __device__ __forceinline__ unsigned cvt_pk_bf16(float lo, float hi) { unsigned r; asm volatile("v_cvt_pk_bf16_f32 %0, %1, %2" : "=v"(r) : "v"(lo), "v"(hi)); return r; }
; __device__ __forceinline__ void transpose_w(const int wv, LAS unsigned char* lds, const float* __restrict__ w, bf16_t* __restrict__ wt, int K, int N, const float* __restrict__ gk, int slo, int shi, float scale) {
;     const int tk = K / 64, tn = N / 64, nt = tk * tn;
;     const int t = TIDX, nl = t & 63, kg = t >> 6, n2 = t >> 3, kc = t & 7;
;     for (int tile = blockIdx.x; tile < nt; tile += gridDim.x) {
;         const int kt0 = (tile % tk) * 64, nb0 = (tile / tk) * 64;
;         const int k0 = kt0 + kg * 8, n = nb0 + nl;
;         float v[8];
; #pragma unroll
;         for (int j = 0; j < 8; ++j) { float g = gk ? gk[k0 + j] : 1.0f; v[j] = w[(size_t)(k0 + j) * N + n] * g; }
;         if (n >= slo && n < shi) {
; #pragma unroll
;             for (int j = 0; j < 8; ++j) v[j] *= scale;
;         }
;         u32x4 o; o.x = cvt_pk_bf16(v[0], v[1]); o.y = cvt_pk_bf16(v[2], v[3]); o.z = cvt_pk_bf16(v[4], v[5]); o.w = cvt_pk_bf16(v[6], v[7]);
;         *(LAS u32x4*)(lds + nl * 144 + kg * 16) = o;
;         __syncthreads();
;         *(u32x4*)(wt + (size_t)(nb0 + n2) * K + kt0 + kc * 8) = *(const LAS u32x4*)(lds + n2 * 144 + kc * 16);
;         __syncthreads();
;     }
.LBB0_29:
	s_ashr_i32 s6, s14, 31
	s_lshr_b32 s6, s6, 27
	s_add_i32 s6, s14, s6
	s_ashr_i32 s6, s6, 5
	s_lshl_b32 s7, s6, 11
	s_lshl_b32 s15, s6, 6
	s_sub_i32 s6, s12, s7
	v_or_b32_e32 v10, s15, v4
	v_add_u32_e32 v12, s6, v6
	v_ashrrev_i32_e32 v11, 31, v10
	v_ashrrev_i32_e32 v13, 31, v12
	v_add_u32_e32 v14, 1, v12
	v_add_u32_e32 v16, 2, v12
	v_add_u32_e32 v18, 3, v12
	v_add_u32_e32 v20, 4, v12
	v_add_u32_e32 v22, 5, v12
	v_add_u32_e32 v24, 6, v12
	v_add_u32_e32 v26, 7, v12
	v_lshl_add_u64 v[10:11], v[10:11], 2, s[0:1]
	v_lshlrev_b64 v[12:13], 12, v[12:13]
	v_ashrrev_i32_e32 v15, 31, v14
	v_ashrrev_i32_e32 v17, 31, v16
	v_ashrrev_i32_e32 v19, 31, v18
	v_ashrrev_i32_e32 v21, 31, v20
	v_ashrrev_i32_e32 v23, 31, v22
	v_ashrrev_i32_e32 v25, 31, v24
	v_ashrrev_i32_e32 v27, 31, v26
	v_lshl_add_u64 v[12:13], v[10:11], 0, v[12:13]
	v_lshlrev_b64 v[14:15], 12, v[14:15]
	v_lshlrev_b64 v[16:17], 12, v[16:17]
	v_lshlrev_b64 v[18:19], 12, v[18:19]
	v_lshlrev_b64 v[20:21], 12, v[20:21]
	v_lshlrev_b64 v[22:23], 12, v[22:23]
	v_lshlrev_b64 v[24:25], 12, v[24:25]
	v_lshlrev_b64 v[26:27], 12, v[26:27]
	v_lshl_add_u64 v[14:15], v[10:11], 0, v[14:15]
	v_lshl_add_u64 v[16:17], v[10:11], 0, v[16:17]
	v_lshl_add_u64 v[18:19], v[10:11], 0, v[18:19]
	v_lshl_add_u64 v[20:21], v[10:11], 0, v[20:21]
	v_lshl_add_u64 v[22:23], v[10:11], 0, v[22:23]
	v_lshl_add_u64 v[24:25], v[10:11], 0, v[24:25]
	v_lshl_add_u64 v[10:11], v[10:11], 0, v[26:27]
	global_load_dword v9, v[12:13], off nt
	global_load_dword v26, v[14:15], off nt
	global_load_dword v27, v[18:19], off nt
	global_load_dword v28, v[24:25], off nt
	global_load_dword v29, v[20:21], off nt
	global_load_dword v30, v[16:17], off nt
	global_load_dword v31, v[22:23], off nt
	global_load_dword v32, v[10:11], off nt
	v_add_u32_e32 v10, s15, v5
	v_ashrrev_i32_e32 v11, 31, v10
	v_lshlrev_b64 v[10:11], 12, v[10:11]
	s_ashr_i32 s7, s6, 31
	v_lshl_add_u64 v[10:11], s[4:5], 0, v[10:11]
	v_lshl_add_u64 v[14:15], s[6:7], 1, v[10:11]
	s_add_i32 s14, s14, s54
	s_add_i32 s12, s12, s13
	s_cmpk_lt_i32 s14, 0x200
	v_lshl_add_u64 v[14:15], v[14:15], 0, v[2:3]
	s_waitcnt vmcnt(6)
	v_cvt_pk_bf16_f32 v10, v9, v26
	s_waitcnt vmcnt(2)
	v_cvt_pk_bf16_f32 v11, v30, v27
	s_waitcnt vmcnt(1)
	v_cvt_pk_bf16_f32 v12, v29, v31
	s_waitcnt vmcnt(0)
	v_cvt_pk_bf16_f32 v13, v28, v32
	ds_write_b128 v7, v[10:13]
	s_waitcnt lgkmcnt(0)
	s_barrier
	ds_read_b128 v[10:13], v8
	s_waitcnt lgkmcnt(0)
	global_store_dwordx4 v[14:15], v[10:13], off
	s_barrier
	s_cbranch_scc1 .LBB0_29

; #define LAS __attribute__((address_space(3)))
; __device__ __forceinline__ unsigned cvt_pk_bf16(float lo, float hi) { unsigned r; asm volatile("v_cvt_pk_bf16_f32 %0, %1, %2" : "=v"(r) : "v"(lo), "v"(hi)); return r; }
; __device__ __forceinline__ void transpose_w(const int wv, LAS unsigned char* lds, const float* __restrict__ w, bf16_t* __restrict__ wt, int K, int N, const float* __restrict__ gk, int slo, int shi, float scale) {
;     const int tk = K / 64, tn = N / 64, nt = tk * tn;
;     const int t = TIDX, nl = t & 63, kg = t >> 6, n2 = t >> 3, kc = t & 7;
;     for (int tile = blockIdx.x; tile < nt; tile += gridDim.x) {
;         const int kt0 = (tile % tk) * 64, nb0 = (tile / tk) * 64;
;         const int k0 = kt0 + kg * 8, n = nb0 + nl;
;         float v[8];
; #pragma unroll
;         for (int j = 0; j < 8; ++j) { float g = gk ? gk[k0 + j] : 1.0f; v[j] = w[(size_t)(k0 + j) * N + n] * g; }
;         if (n >= slo && n < shi) {
; #pragma unroll
;             for (int j = 0; j < 8; ++j) v[j] *= scale;
;         }
;         u32x4 o; o.x = cvt_pk_bf16(v[0], v[1]); o.y = cvt_pk_bf16(v[2], v[3]); o.z = cvt_pk_bf16(v[4], v[5]); o.w = cvt_pk_bf16(v[6], v[7]);
;         *(LAS u32x4*)(lds + nl * 144 + kg * 16) = o;
;         __syncthreads();
;         *(u32x4*)(wt + (size_t)(nb0 + n2) * K + kt0 + kc * 8) = *(const LAS u32x4*)(lds + n2 * 144 + kc * 16);
;         __syncthreads();
;     }
.LBB0_32:
	s_ashr_i32 s6, s14, 31
	s_lshr_b32 s6, s6, 28
	s_add_i32 s6, s14, s6
	s_ashr_i32 s6, s6, 4
	s_lshl_b32 s7, s6, 10
	s_lshl_b32 s15, s6, 6
	s_sub_i32 s6, s12, s7
	v_or_b32_e32 v10, s15, v4
	v_add_u32_e32 v12, s6, v6
	v_ashrrev_i32_e32 v11, 31, v10
	v_ashrrev_i32_e32 v13, 31, v12
	v_add_u32_e32 v14, 1, v12
	v_add_u32_e32 v16, 2, v12
	v_add_u32_e32 v18, 3, v12
	v_add_u32_e32 v20, 4, v12
	v_add_u32_e32 v22, 5, v12
	v_add_u32_e32 v24, 6, v12
	v_add_u32_e32 v26, 7, v12
	v_lshl_add_u64 v[10:11], v[10:11], 2, s[0:1]
	v_lshlrev_b64 v[12:13], 12, v[12:13]
	v_ashrrev_i32_e32 v15, 31, v14
	v_ashrrev_i32_e32 v17, 31, v16
	v_ashrrev_i32_e32 v19, 31, v18
	v_ashrrev_i32_e32 v21, 31, v20
	v_ashrrev_i32_e32 v23, 31, v22
	v_ashrrev_i32_e32 v25, 31, v24
	v_ashrrev_i32_e32 v27, 31, v26
	v_lshl_add_u64 v[12:13], v[10:11], 0, v[12:13]
	v_lshlrev_b64 v[14:15], 12, v[14:15]
	v_lshlrev_b64 v[16:17], 12, v[16:17]
	v_lshlrev_b64 v[18:19], 12, v[18:19]
	v_lshlrev_b64 v[20:21], 12, v[20:21]
	v_lshlrev_b64 v[22:23], 12, v[22:23]
	v_lshlrev_b64 v[24:25], 12, v[24:25]
	v_lshlrev_b64 v[26:27], 12, v[26:27]
	v_lshl_add_u64 v[14:15], v[10:11], 0, v[14:15]
	v_lshl_add_u64 v[16:17], v[10:11], 0, v[16:17]
	v_lshl_add_u64 v[18:19], v[10:11], 0, v[18:19]
	v_lshl_add_u64 v[20:21], v[10:11], 0, v[20:21]
	v_lshl_add_u64 v[22:23], v[10:11], 0, v[22:23]
	v_lshl_add_u64 v[24:25], v[10:11], 0, v[24:25]
	v_lshl_add_u64 v[10:11], v[10:11], 0, v[26:27]
	global_load_dword v9, v[12:13], off nt
	global_load_dword v26, v[14:15], off nt
	global_load_dword v27, v[18:19], off nt
	global_load_dword v28, v[24:25], off nt
	global_load_dword v29, v[20:21], off nt
	global_load_dword v30, v[16:17], off nt
	global_load_dword v31, v[22:23], off nt
	global_load_dword v32, v[10:11], off nt
	v_add_u32_e32 v10, s15, v5
	v_ashrrev_i32_e32 v11, 31, v10
	v_lshlrev_b64 v[10:11], 11, v[10:11]
	s_ashr_i32 s7, s6, 31
	v_lshl_add_u64 v[10:11], s[4:5], 0, v[10:11]
	v_lshl_add_u64 v[14:15], s[6:7], 1, v[10:11]
	s_add_i32 s14, s14, s54
	s_add_i32 s12, s12, s13
	s_cmpk_lt_i32 s14, 0x100
	v_lshl_add_u64 v[14:15], v[14:15], 0, v[2:3]
	s_waitcnt vmcnt(6)
	v_cvt_pk_bf16_f32 v10, v9, v26
	s_waitcnt vmcnt(2)
	v_cvt_pk_bf16_f32 v11, v30, v27
	s_waitcnt vmcnt(1)
	v_cvt_pk_bf16_f32 v12, v29, v31
	s_waitcnt vmcnt(0)
	v_cvt_pk_bf16_f32 v13, v28, v32
	ds_write_b128 v7, v[10:13]
	s_waitcnt lgkmcnt(0)
	s_barrier
	ds_read_b128 v[10:13], v8
	s_waitcnt lgkmcnt(0)
	global_store_dwordx4 v[14:15], v[10:13], off
	s_barrier
	s_cbranch_scc1 .LBB0_32

; #define LAS __attribute__((address_space(3)))
; __device__ __forceinline__ unsigned cvt_pk_bf16(float lo, float hi) { unsigned r; asm volatile("v_cvt_pk_bf16_f32 %0, %1, %2" : "=v"(r) : "v"(lo), "v"(hi)); return r; }
; __device__ __forceinline__ void transpose_w(const int wv, LAS unsigned char* lds, const float* __restrict__ w, bf16_t* __restrict__ wt, int K, int N, const float* __restrict__ gk, int slo, int shi, float scale) {
;     const int tk = K / 64, tn = N / 64, nt = tk * tn;
;     const int t = TIDX, nl = t & 63, kg = t >> 6, n2 = t >> 3, kc = t & 7;
;     for (int tile = blockIdx.x; tile < nt; tile += gridDim.x) {
;         const int kt0 = (tile % tk) * 64, nb0 = (tile / tk) * 64;
;         const int k0 = kt0 + kg * 8, n = nb0 + nl;
;         float v[8];
; #pragma unroll
;         for (int j = 0; j < 8; ++j) { float g = gk ? gk[k0 + j] : 1.0f; v[j] = w[(size_t)(k0 + j) * N + n] * g; }
;         if (n >= slo && n < shi) {
; #pragma unroll
;             for (int j = 0; j < 8; ++j) v[j] *= scale;
;         }
;         u32x4 o; o.x = cvt_pk_bf16(v[0], v[1]); o.y = cvt_pk_bf16(v[2], v[3]); o.z = cvt_pk_bf16(v[4], v[5]); o.w = cvt_pk_bf16(v[6], v[7]);
;         *(LAS u32x4*)(lds + nl * 144 + kg * 16) = o;
;         __syncthreads();
;         *(u32x4*)(wt + (size_t)(nb0 + n2) * K + kt0 + kc * 8) = *(const LAS u32x4*)(lds + n2 * 144 + kc * 16);
;         __syncthreads();
;     }
.LBB0_35:
	v_add_u32_e32 v8, 7, v4
	v_ashrrev_i32_e32 v9, 31, v8
	v_lshlrev_b64 v[8:9], 14, v[8:9]
	v_lshl_add_u64 v[6:7], v[6:7], 0, v[8:9]
	global_load_dword v7, v[6:7], off nt
	v_add_u32_e32 v4, s19, v11
	s_waitcnt vmcnt(2)
	v_mul_f32_e32 v6, v23, v26
	v_mul_f32_e32 v16, v16, v5
	v_ashrrev_i32_e32 v5, 31, v4
	s_waitcnt vmcnt(1)
	v_mul_f32_e32 v27, v27, v28
	v_mul_f32_e32 v23, v24, v25
	v_mul_f32_e32 v18, v18, v22
	v_mul_f32_e32 v19, v19, v20
	v_mul_f32_e32 v15, v15, v17
	v_lshlrev_b64 v[8:9], 11, v[4:5]
	v_cvt_pk_bf16_f32 v4, v16, v15
	v_cvt_pk_bf16_f32 v5, v19, v18
	v_cvt_pk_bf16_f32 v6, v23, v6
	s_sub_i32 s20, 0, s20
	s_add_i32 s20, s16, s20
	s_ashr_i32 s21, s20, 31
	v_lshl_add_u64 v[8:9], s[14:15], 0, v[8:9]
	s_add_i32 s18, s18, s54
	s_add_i32 s16, s16, s17
	v_lshl_add_u64 v[8:9], s[20:21], 1, v[8:9]
	s_cmpk_lt_i32 s18, 0x400
	v_lshl_add_u64 v[8:9], v[8:9], 0, v[2:3]
	s_waitcnt vmcnt(0)
	v_mul_f32_e32 v7, v21, v7
	v_cvt_pk_bf16_f32 v7, v27, v7
	ds_write_b128 v13, v[4:7]
	s_waitcnt lgkmcnt(0)
	s_barrier
	ds_read_b128 v[4:7], v14
	s_waitcnt lgkmcnt(0)
	global_store_dwordx4 v[8:9], v[4:7], off
	s_barrier
	s_cbranch_scc0 .LBB0_52
.LBB0_36:
	s_ashr_i32 s19, s18, 31
	s_lshr_b32 s19, s19, 28
	s_add_i32 s19, s18, s19
	s_ashr_i32 s19, s19, 4
	s_lshl_b32 s20, s19, 10
	s_sub_i32 s21, s16, s20
	v_add_u32_e32 v4, s21, v12
	v_ashrrev_i32_e32 v5, 31, v4
	v_mov_b32_e32 v15, 1.0
	s_and_b64 vcc, exec, s[0:1]
	v_lshl_add_u64 v[8:9], v[4:5], 2, s[4:5]
	v_mov_b32_e32 v16, 1.0
	s_cbranch_vccnz .LBB0_38
	global_load_dword v16, v[8:9], off nt
.LBB0_38:
	s_lshl_b32 s19, s19, 6
	v_or_b32_e32 v6, s19, v10
	v_ashrrev_i32_e32 v7, 31, v6
	v_lshl_add_u64 v[6:7], v[6:7], 2, s[6:7]
	v_lshlrev_b64 v[18:19], 14, v[4:5]
	v_lshl_add_u64 v[18:19], v[6:7], 0, v[18:19]
	global_load_dword v5, v[18:19], off nt
	s_and_b64 vcc, exec, s[0:1]
	s_cbranch_vccnz .LBB0_40
	global_load_dword v15, v[8:9], off offset:4 nt
.LBB0_40:
	v_add_u32_e32 v18, 1, v4
	v_ashrrev_i32_e32 v19, 31, v18
	v_lshlrev_b64 v[18:19], 14, v[18:19]
	v_lshl_add_u64 v[18:19], v[6:7], 0, v[18:19]
	global_load_dword v17, v[18:19], off nt
	v_mov_b32_e32 v18, 1.0
	s_and_b64 vcc, exec, s[0:1]
	v_mov_b32_e32 v19, 1.0
	s_cbranch_vccnz .LBB0_42
	global_load_dword v19, v[8:9], off offset:8 nt
.LBB0_42:
	v_add_u32_e32 v20, 2, v4
	v_ashrrev_i32_e32 v21, 31, v20
	v_lshlrev_b64 v[20:21], 14, v[20:21]
	v_lshl_add_u64 v[20:21], v[6:7], 0, v[20:21]
	global_load_dword v20, v[20:21], off nt
	s_and_b64 vcc, exec, s[0:1]
	s_cbranch_vccnz .LBB0_44
	global_load_dword v18, v[8:9], off offset:12 nt
.LBB0_44:
	v_add_u32_e32 v22, 3, v4
	v_ashrrev_i32_e32 v23, 31, v22
	v_lshlrev_b64 v[22:23], 14, v[22:23]
	v_lshl_add_u64 v[22:23], v[6:7], 0, v[22:23]
	global_load_dword v22, v[22:23], off nt
	v_mov_b32_e32 v23, 1.0
	s_and_b64 vcc, exec, s[0:1]
	v_mov_b32_e32 v24, 1.0
	s_cbranch_vccnz .LBB0_46
	global_load_dword v24, v[8:9], off offset:16 nt
.LBB0_46:
	v_add_u32_e32 v26, 4, v4
	v_ashrrev_i32_e32 v27, 31, v26
	v_lshlrev_b64 v[26:27], 14, v[26:27]
	v_lshl_add_u64 v[26:27], v[6:7], 0, v[26:27]
	global_load_dword v25, v[26:27], off nt
	s_and_b64 vcc, exec, s[0:1]
	s_cbranch_vccnz .LBB0_48
	global_load_dword v23, v[8:9], off offset:20 nt
.LBB0_48:
	v_add_u32_e32 v26, 5, v4
	v_ashrrev_i32_e32 v27, 31, v26
	v_lshlrev_b64 v[26:27], 14, v[26:27]
	v_lshl_add_u64 v[26:27], v[6:7], 0, v[26:27]
	global_load_dword v26, v[26:27], off nt
	v_mov_b32_e32 v21, 1.0
	s_and_b64 vcc, exec, s[0:1]
	v_mov_b32_e32 v27, 1.0
	s_cbranch_vccnz .LBB0_50
	global_load_dword v27, v[8:9], off offset:24 nt
.LBB0_50:
	v_add_u32_e32 v28, 6, v4
	v_ashrrev_i32_e32 v29, 31, v28
	v_lshlrev_b64 v[28:29], 14, v[28:29]
	v_lshl_add_u64 v[28:29], v[6:7], 0, v[28:29]
	global_load_dword v28, v[28:29], off nt
	s_and_b64 vcc, exec, s[0:1]
	s_cbranch_vccnz .LBB0_35
	global_load_dword v21, v[8:9], off offset:28 nt
	s_branch .LBB0_35

; #define LAS __attribute__((address_space(3)))
; __device__ __forceinline__ unsigned cvt_pk_bf16(float lo, float hi) { unsigned r; asm volatile("v_cvt_pk_bf16_f32 %0, %1, %2" : "=v"(r) : "v"(lo), "v"(hi)); return r; }
; __device__ __forceinline__ void transpose_w(const int wv, LAS unsigned char* lds, const float* __restrict__ w, bf16_t* __restrict__ wt, int K, int N, const float* __restrict__ gk, int slo, int shi, float scale) {
;     const int tk = K / 64, tn = N / 64, nt = tk * tn;
;     const int t = TIDX, nl = t & 63, kg = t >> 6, n2 = t >> 3, kc = t & 7;
;     for (int tile = blockIdx.x; tile < nt; tile += gridDim.x) {
;         const int kt0 = (tile % tk) * 64, nb0 = (tile / tk) * 64;
;         const int k0 = kt0 + kg * 8, n = nb0 + nl;
;         float v[8];
; #pragma unroll
;         for (int j = 0; j < 8; ++j) { float g = gk ? gk[k0 + j] : 1.0f; v[j] = w[(size_t)(k0 + j) * N + n] * g; }
;         if (n >= slo && n < shi) {
; #pragma unroll
;             for (int j = 0; j < 8; ++j) v[j] *= scale;
;         }
;         u32x4 o; o.x = cvt_pk_bf16(v[0], v[1]); o.y = cvt_pk_bf16(v[2], v[3]); o.z = cvt_pk_bf16(v[4], v[5]); o.w = cvt_pk_bf16(v[6], v[7]);
;         *(LAS u32x4*)(lds + nl * 144 + kg * 16) = o;
;         __syncthreads();
;         *(u32x4*)(wt + (size_t)(nb0 + n2) * K + kt0 + kc * 8) = *(const LAS u32x4*)(lds + n2 * 144 + kc * 16);
;         __syncthreads();
;     }
.LBB0_54:
	s_ashr_i32 s6, s14, 31
	s_lshr_b32 s6, s6, 26
	s_add_i32 s6, s14, s6
	s_lshl_b32 s7, s6, 6
	s_and_b32 s15, s6, 0xffffffc0
	s_and_b32 s6, s7, 0xfffff000
	s_sub_i32 s6, s12, s6
	v_or_b32_e32 v10, s15, v4
	v_add_u32_e32 v12, s6, v6
	v_ashrrev_i32_e32 v11, 31, v10
	v_ashrrev_i32_e32 v13, 31, v12
	v_add_u32_e32 v14, 1, v12
	v_add_u32_e32 v16, 2, v12
	v_add_u32_e32 v18, 3, v12
	v_add_u32_e32 v20, 4, v12
	v_add_u32_e32 v22, 5, v12
	v_add_u32_e32 v24, 6, v12
	v_add_u32_e32 v26, 7, v12
	v_lshl_add_u64 v[10:11], v[10:11], 2, s[0:1]
	v_lshlrev_b64 v[12:13], 12, v[12:13]
	v_ashrrev_i32_e32 v15, 31, v14
	v_ashrrev_i32_e32 v17, 31, v16
	v_ashrrev_i32_e32 v19, 31, v18
	v_ashrrev_i32_e32 v21, 31, v20
	v_ashrrev_i32_e32 v23, 31, v22
	v_ashrrev_i32_e32 v25, 31, v24
	v_ashrrev_i32_e32 v27, 31, v26
	v_lshl_add_u64 v[12:13], v[10:11], 0, v[12:13]
	v_lshlrev_b64 v[14:15], 12, v[14:15]
	v_lshlrev_b64 v[16:17], 12, v[16:17]
	v_lshlrev_b64 v[18:19], 12, v[18:19]
	v_lshlrev_b64 v[20:21], 12, v[20:21]
	v_lshlrev_b64 v[22:23], 12, v[22:23]
	v_lshlrev_b64 v[24:25], 12, v[24:25]
	v_lshlrev_b64 v[26:27], 12, v[26:27]
	v_lshl_add_u64 v[14:15], v[10:11], 0, v[14:15]
	v_lshl_add_u64 v[16:17], v[10:11], 0, v[16:17]
	v_lshl_add_u64 v[18:19], v[10:11], 0, v[18:19]
	v_lshl_add_u64 v[20:21], v[10:11], 0, v[20:21]
	v_lshl_add_u64 v[22:23], v[10:11], 0, v[22:23]
	v_lshl_add_u64 v[24:25], v[10:11], 0, v[24:25]
	v_lshl_add_u64 v[10:11], v[10:11], 0, v[26:27]
	global_load_dword v9, v[12:13], off nt
	global_load_dword v26, v[14:15], off nt
	global_load_dword v27, v[18:19], off nt
	global_load_dword v28, v[24:25], off nt
	global_load_dword v29, v[20:21], off nt
	global_load_dword v30, v[16:17], off nt
	global_load_dword v31, v[22:23], off nt
	global_load_dword v32, v[10:11], off nt
	v_add_u32_e32 v10, s15, v5
	v_ashrrev_i32_e32 v11, 31, v10
	v_lshlrev_b64 v[10:11], 13, v[10:11]
	s_ashr_i32 s7, s6, 31
	v_lshl_add_u64 v[10:11], s[4:5], 0, v[10:11]
	v_lshl_add_u64 v[14:15], s[6:7], 1, v[10:11]
	s_add_i32 s14, s14, s54
	s_add_i32 s12, s12, s13
	s_cmpk_lt_i32 s14, 0x400
	v_lshl_add_u64 v[14:15], v[14:15], 0, v[2:3]
	s_waitcnt vmcnt(6)
	v_cvt_pk_bf16_f32 v10, v9, v26
	s_waitcnt vmcnt(2)
	v_cvt_pk_bf16_f32 v11, v30, v27
	s_waitcnt vmcnt(1)
	v_cvt_pk_bf16_f32 v12, v29, v31
	s_waitcnt vmcnt(0)
	v_cvt_pk_bf16_f32 v13, v28, v32
	ds_write_b128 v7, v[10:13]
	s_waitcnt lgkmcnt(0)
	s_barrier
	ds_read_b128 v[10:13], v8
	s_waitcnt lgkmcnt(0)
	global_store_dwordx4 v[14:15], v[10:13], off
	s_barrier
	s_cbranch_scc1 .LBB0_54

; __device__ __forceinline__ void prep_x(const int wv, const float* __restrict__ x, bf16_t* __restrict__ orbuf) {
;     ...
;     for (int row0 = blockIdx.x * 8 + wave; row0 < MT; row0 += 4 * rstride) {
;         f32x4 v[4][4];
; #pragma unroll
;         for (int q = 0; q < 4; ++q) { const int row = row0 + q * rstride;
;             if (row < MT) {
; #pragma unroll
;                 for (int i = 0; i < 4; ++i) v[q][i] = *(const f32x4*)(x + (size_t)row * DM + i * 256 + lane * 4);
;             } }
.LBB0_58:
	v_ashrrev_i32_e32 v79, 31, v78
	v_lshlrev_b64 v[50:51], 12, v[78:79]
	v_lshl_add_u64 v[72:73], v[70:71], 0, v[50:51]
	global_load_dwordx4 v[62:65], v[72:73], off nt
	global_load_dwordx4 v[58:61], v[72:73], off offset:1024 nt
	global_load_dwordx4 v[54:57], v[72:73], off offset:2048 nt
	global_load_dwordx4 v[50:53], v[72:73], off offset:3072 nt
	v_add_u32_e32 v72, s15, v78
	v_cmp_gt_i32_e64 s[2:3], s14, v72
	v_ashrrev_i32_e32 v73, 31, v72
	s_and_saveexec_b64 s[0:1], s[2:3]
	s_cbranch_execz .LBB0_60
	v_lshlrev_b64 v[34:35], 12, v[72:73]
	v_lshl_add_u64 v[74:75], v[70:71], 0, v[34:35]
	global_load_dwordx4 v[46:49], v[74:75], off nt
	global_load_dwordx4 v[42:45], v[74:75], off offset:1024 nt
	global_load_dwordx4 v[38:41], v[74:75], off offset:2048 nt
	global_load_dwordx4 v[34:37], v[74:75], off offset:3072 nt
.LBB0_60:
	s_or_b64 exec, exec, s[0:1]
	v_add_u32_e32 v76, s16, v78
	v_cmp_gt_i32_e64 s[0:1], s14, v76
	v_ashrrev_i32_e32 v77, 31, v76
	s_and_saveexec_b64 s[4:5], s[0:1]
	s_cbranch_execz .LBB0_62
	v_lshlrev_b64 v[18:19], 12, v[76:77]
	v_lshl_add_u64 v[74:75], v[70:71], 0, v[18:19]
	global_load_dwordx4 v[30:33], v[74:75], off nt
	global_load_dwordx4 v[26:29], v[74:75], off offset:1024 nt
	global_load_dwordx4 v[22:25], v[74:75], off offset:2048 nt
	global_load_dwordx4 v[18:21], v[74:75], off offset:3072 nt
.LBB0_62:
	s_or_b64 exec, exec, s[4:5]
	v_add_u32_e32 v74, s17, v78
	v_cmp_gt_i32_e32 vcc, s14, v74
	v_ashrrev_i32_e32 v75, 31, v74
	s_and_saveexec_b64 s[4:5], vcc
	s_cbranch_execz .LBB0_64
	v_lshlrev_b64 v[2:3], 12, v[74:75]
	v_lshl_add_u64 v[86:87], v[70:71], 0, v[2:3]
	global_load_dwordx4 v[14:17], v[86:87], off nt
	global_load_dwordx4 v[10:13], v[86:87], off offset:1024 nt
	global_load_dwordx4 v[6:9], v[86:87], off offset:2048 nt
	global_load_dwordx4 v[2:5], v[86:87], off offset:3072 nt

; __device__ __forceinline__ unsigned cvt_pk_bf16(float lo, float hi) { unsigned r; asm volatile("v_cvt_pk_bf16_f32 %0, %1, %2" : "=v"(r) : "v"(lo), "v"(hi)); return r; }
; __device__ __forceinline__ float bflo(unsigned u) { return __uint_as_float(u << 16); }
; __device__ __forceinline__ float bfhi(unsigned u) { return __uint_as_float(u & 0xffff0000u); }
; __device__ __forceinline__ void ret_scan(const int wv, bf16_t* __restrict__ kv) {
;     ...
;     for (int idx = blockIdx.x * 512 + ts_; idx < 4 * 32768; idx += gridDim.x * 512) {
;         const int h = idx >> 15, e4 = idx & 32767;
;         const float gC = exp2f(128.0f * log2f(1.0f - exp2f(-5.0f - (float)h)));
;         bf16_t* pbase = kv + (size_t)h * 64 * 131072 + (size_t)e4 * 4;
;         float s0 = 0.f, s1 = 0.f, s2 = 0.f, s3 = 0.f;
; #pragma unroll 1
;         for (int n0 = 0; n0 < 64; n0 += 8) {
;             u32x2 v[8];
; #pragma unroll
;             for (int k = 0; k < 8; ++k) v[k] = *(const u32x2*)(pbase + (size_t)(n0 + k) * 131072);
; #pragma unroll
;             for (int k = 0; k < 8; ++k) {
;                 u32x2 o; o.x = cvt_pk_bf16(s0, s1); o.y = cvt_pk_bf16(s2, s3);
;                 *(u32x2*)(pbase + (size_t)(n0 + k) * 131072) = o;
;                 s0 = (s0 + bflo(v[k].x)) * gC; s1 = (s1 + bfhi(v[k].x)) * gC; s2 = (s2 + bflo(v[k].y)) * gC; s3 = (s3 + bfhi(v[k].y)) * gC;
;             }
;         }
;     }
.LBB0_420:
	v_add_co_u32_e32 v12, vcc, 0xffe40000, v2
	s_add_i32 s6, s6, 8
	s_nop 0
	v_addc_co_u32_e32 v13, vcc, -1, v3, vcc
	v_add_co_u32_e32 v16, vcc, 0xffe80000, v2
	global_load_dwordx2 v[14:15], v[12:13], off nt
	s_nop 0
	v_addc_co_u32_e32 v17, vcc, -1, v3, vcc
	v_add_co_u32_e32 v20, vcc, 0xffec0000, v2
	global_load_dwordx2 v[18:19], v[16:17], off nt
	s_nop 0
	v_addc_co_u32_e32 v21, vcc, -1, v3, vcc
	v_add_co_u32_e32 v24, vcc, 0xfff00000, v2
	global_load_dwordx2 v[22:23], v[20:21], off nt
	s_nop 0
	v_addc_co_u32_e32 v25, vcc, -1, v3, vcc
	v_add_co_u32_e32 v28, vcc, 0xfff40000, v2
	global_load_dwordx2 v[26:27], v[24:25], off nt
	s_nop 0
	v_addc_co_u32_e32 v29, vcc, -1, v3, vcc
	v_add_co_u32_e32 v32, vcc, 0xfff80000, v2
	global_load_dwordx2 v[30:31], v[28:29], off nt
	s_nop 0
	v_addc_co_u32_e32 v33, vcc, -1, v3, vcc
	global_load_dwordx2 v[34:35], v[32:33], off nt
	v_add_co_u32_e32 v36, vcc, 0xfffc0000, v2
	s_mov_b64 s[8:9], 0x200000
	s_nop 0
	v_addc_co_u32_e32 v37, vcc, -1, v3, vcc
	global_load_dwordx2 v[38:39], v[36:37], off nt
	global_load_dwordx2 v[40:41], v[2:3], off nt
	v_cvt_pk_bf16_f32 v42, v9, v8
	v_cvt_pk_bf16_f32 v43, v7, v6
	global_store_dwordx2 v[12:13], v[42:43], off
	s_cmp_lt_u32 s6, 56
	s_waitcnt vmcnt(8)
	v_and_b32_e32 v12, 0xffff0000, v14
	v_lshlrev_b32_e32 v13, 16, v14
	v_and_b32_e32 v14, 0xffff0000, v15
	v_lshlrev_b32_e32 v15, 16, v15
	v_pk_add_f32 v[8:9], v[8:9], v[12:13]
	s_waitcnt vmcnt(7)
	v_and_b32_e32 v12, 0xffff0000, v18
	v_lshlrev_b32_e32 v13, 16, v18
	v_pk_add_f32 v[6:7], v[6:7], v[14:15]
	v_and_b32_e32 v14, 0xffff0000, v19
	v_lshlrev_b32_e32 v15, 16, v19
	v_pk_mul_f32 v[18:19], v[4:5], v[8:9]
	v_pk_fma_f32 v[8:9], v[4:5], v[8:9], v[12:13]
	s_waitcnt vmcnt(6)
	v_and_b32_e32 v12, 0xffff0000, v22
	v_lshlrev_b32_e32 v13, 16, v22
	v_pk_mul_f32 v[42:43], v[4:5], v[6:7]
	v_pk_fma_f32 v[6:7], v[4:5], v[6:7], v[14:15]
	v_and_b32_e32 v14, 0xffff0000, v23
	v_lshlrev_b32_e32 v15, 16, v23
	v_pk_mul_f32 v[22:23], v[4:5], v[8:9]
	v_pk_fma_f32 v[8:9], v[4:5], v[8:9], v[12:13]
	v_pk_mul_f32 v[12:13], v[4:5], v[6:7]
	v_pk_fma_f32 v[6:7], v[4:5], v[6:7], v[14:15]
	s_waitcnt vmcnt(5)
	v_lshlrev_b32_e32 v15, 16, v26
	v_and_b32_e32 v14, 0xffff0000, v26
	v_cvt_pk_bf16_f32 v18, v19, v18
	v_cvt_pk_bf16_f32 v19, v43, v42
	global_store_dwordx2 v[16:17], v[18:19], off
	v_cvt_pk_bf16_f32 v16, v23, v22
	v_cvt_pk_bf16_f32 v17, v13, v12
	v_pk_mul_f32 v[12:13], v[4:5], v[8:9]
	v_pk_fma_f32 v[8:9], v[4:5], v[8:9], v[14:15]
	s_waitcnt vmcnt(5)
	v_and_b32_e32 v14, 0xffff0000, v30
	v_lshlrev_b32_e32 v15, 16, v30
	global_store_dwordx2 v[20:21], v[16:17], off
	v_pk_mul_f32 v[16:17], v[4:5], v[8:9]
	v_pk_fma_f32 v[8:9], v[4:5], v[8:9], v[14:15]
	s_waitcnt vmcnt(5)
	v_and_b32_e32 v14, 0xffff0000, v34
	v_lshlrev_b32_e32 v15, 16, v34
	v_pk_mul_f32 v[18:19], v[4:5], v[8:9]
	v_pk_fma_f32 v[8:9], v[4:5], v[8:9], v[14:15]
	s_waitcnt vmcnt(4)
	v_and_b32_e32 v20, 0xffff0000, v38
	v_lshlrev_b32_e32 v21, 16, v38
	v_lshlrev_b32_e32 v43, 16, v27
	v_and_b32_e32 v42, 0xffff0000, v27
	v_pk_mul_f32 v[14:15], v[4:5], v[8:9]
	v_pk_fma_f32 v[8:9], v[4:5], v[8:9], v[20:21]
	s_waitcnt vmcnt(3)
	v_and_b32_e32 v22, 0xffff0000, v40
	v_lshlrev_b32_e32 v23, 16, v40
	v_cvt_pk_bf16_f32 v12, v13, v12
	v_pk_mul_f32 v[20:21], v[4:5], v[8:9]
	v_pk_fma_f32 v[8:9], v[4:5], v[8:9], v[22:23]
	v_pk_mul_f32 v[22:23], v[4:5], v[6:7]
	v_pk_fma_f32 v[6:7], v[4:5], v[6:7], v[42:43]
	v_cvt_pk_bf16_f32 v13, v23, v22
	global_store_dwordx2 v[24:25], v[12:13], off
	v_pk_mul_f32 v[12:13], v[4:5], v[6:7]
	v_cvt_pk_bf16_f32 v16, v17, v16
	v_pk_mul_f32 v[8:9], v[4:5], v[8:9]
	v_cvt_pk_bf16_f32 v17, v13, v12
	v_and_b32_e32 v12, 0xffff0000, v31
	v_lshlrev_b32_e32 v13, 16, v31
	v_pk_fma_f32 v[6:7], v[4:5], v[6:7], v[12:13]
	global_store_dwordx2 v[28:29], v[16:17], off
	v_pk_mul_f32 v[12:13], v[4:5], v[6:7]
	v_cvt_pk_bf16_f32 v16, v19, v18
	s_nop 0
	v_cvt_pk_bf16_f32 v17, v13, v12
	v_and_b32_e32 v12, 0xffff0000, v35
	v_lshlrev_b32_e32 v13, 16, v35
	v_pk_fma_f32 v[6:7], v[4:5], v[6:7], v[12:13]
	global_store_dwordx2 v[32:33], v[16:17], off
	v_pk_mul_f32 v[12:13], v[4:5], v[6:7]
	v_cvt_pk_bf16_f32 v14, v15, v14
	s_nop 0
	v_cvt_pk_bf16_f32 v15, v13, v12
	v_and_b32_e32 v12, 0xffff0000, v39
	v_lshlrev_b32_e32 v13, 16, v39
	v_pk_fma_f32 v[6:7], v[4:5], v[6:7], v[12:13]
	global_store_dwordx2 v[36:37], v[14:15], off
	v_pk_mul_f32 v[12:13], v[4:5], v[6:7]
	v_cvt_pk_bf16_f32 v14, v21, v20
	s_nop 0
	v_cvt_pk_bf16_f32 v15, v13, v12
	v_and_b32_e32 v12, 0xffff0000, v41
	v_lshlrev_b32_e32 v13, 16, v41
	v_pk_fma_f32 v[6:7], v[4:5], v[6:7], v[12:13]
	global_store_dwordx2 v[2:3], v[14:15], off
	v_pk_mul_f32 v[6:7], v[4:5], v[6:7]
	v_lshl_add_u64 v[2:3], v[2:3], 0, s[8:9]
	s_cbranch_scc1 .LBB0_420
	v_add_u32_e32 v1, s68, v1
	s_mov_b32 s6, 0x1ffff
	v_cmp_lt_i32_e32 vcc, s6, v1
	s_or_b64 s[4:5], vcc, s[4:5]
	v_add_u32_e32 v10, s70, v10
	s_andn2_b64 exec, exec, s[4:5]
	s_cbranch_execnz .LBB0_419

; #define LAS __attribute__((address_space(3)))
; #define MFMA16(a, b, c) __builtin_amdgcn_mfma_f32_16x16x32_bf16((a), (b), (c), 0, 0, 0)
; #define WAITV0() asm volatile("s_waitcnt vmcnt(0)" ::: "memory")
; #define LBAR() do { asm volatile("s_waitcnt lgkmcnt(0)" ::: "memory"); __builtin_amdgcn_s_barrier(); asm volatile("" ::: "memory"); } while (0)
; __device__ __forceinline__ void retc_stream(const int wv, LAS unsigned char* lds, unsigned ldsb, const float* __restrict__ gn_g, const float* __restrict__ gn_b, const bf16_t* __restrict__ qkvr, const bf16_t* __restrict__ grb, const bf16_t* __restrict__ kv, ...
;     ...
;         const float lg2 = log2f(1.0f - exp2f(-5.0f - (float)h));
;     ...
;         for (int vc = 0; vc < 4; ++vc) {
;             WAITV0(); LBAR();
;             if (vc < 3) RETC_ISSUE(item, 5 + vc);
;             unsigned img = (vc & 1) * 65536u; asm volatile("" : "+v"(img));
; #pragma unroll
;             for (int s = 0; s < 8; ++s) {
;                 bf16x8 bfr[8];
; #pragma unroll
;                 for (int c = 0; c < 8; ++c) bfr[c] = *(const LAS bf16x8*)(lds + img + c * 8192 + koff[s]);
;                 asm volatile("s_waitcnt lgkmcnt(0)" ::: "memory");
; #pragma unroll
;                 for (int c = 0; c < 8; ++c) acc[vc * 8 + c] = MFMA16(qf[s], bfr[c], acc[vc * 8 + c]);
;             }
.LBB0_500:
	v_cvt_f32_i32_e32 v1, s40
	s_mov_b32 s41, 0xc2fc0000
	s_waitcnt vmcnt(0)
	s_waitcnt lgkmcnt(0)
	v_sub_f32_e32 v1, 0xc0a00000, v1
	v_cmp_gt_f32_e32 vcc, s41, v1
	s_and_b64 s[0:1], vcc, exec
	s_cselect_b32 s0, 0xffffffc0, 0
	v_cndmask_b32_e32 v2, 0, v187, vcc
	v_add_f32_e32 v1, v1, v2
	v_exp_f32_e32 v1, v1
	s_barrier
	s_mov_b32 m0, s46
	v_ldexp_f32 v1, v1, s0
	v_sub_f32_e32 v1, 1.0, v1
	v_cmp_gt_f32_e32 vcc, s36, v1
	s_and_b64 s[0:1], vcc, exec
	s_cselect_b32 s0, 32, 0
	v_ldexp_f32 v1, v1, s0
	v_log_f32_e32 v1, v1
	v_readlane_b32 s0, v254, 2
	v_readlane_b32 s1, v254, 3
	v_cndmask_b32_e32 v2, 0, v190, vcc
	s_add_i32 s28, s28, s0
	s_mov_b64 s[0:1], 0x10000
	v_sub_f32_e32 v1, v1, v2
	v_lshl_add_u64 v[2:3], v[182:183], 0, s[0:1]
	s_mov_b64 s[0:1], 0x12000
	global_load_lds_dwordx4 v[2:3], off nt
	v_lshl_add_u64 v[2:3], v[182:183], 0, s[0:1]
	s_mov_b32 m0, s53
	s_mov_b64 s[0:1], 0x14000
	global_load_lds_dwordx4 v[2:3], off nt
	v_lshl_add_u64 v[2:3], v[182:183], 0, s[0:1]
	s_mov_b32 m0, s52
	s_mov_b64 s[0:1], 0x16000
	global_load_lds_dwordx4 v[2:3], off nt
	v_lshl_add_u64 v[2:3], v[182:183], 0, s[0:1]
	s_mov_b32 m0, s55
	s_mov_b64 s[0:1], 0x18000
	global_load_lds_dwordx4 v[2:3], off nt
	v_lshl_add_u64 v[2:3], v[182:183], 0, s[0:1]
	s_mov_b32 m0, s54
	s_mov_b64 s[0:1], 0x1a000
	global_load_lds_dwordx4 v[2:3], off nt
	v_lshl_add_u64 v[2:3], v[182:183], 0, s[0:1]
	s_mov_b32 m0, s57
	s_mov_b64 s[0:1], 0x1c000
	global_load_lds_dwordx4 v[2:3], off nt
	v_lshl_add_u64 v[2:3], v[182:183], 0, s[0:1]
	s_mov_b32 m0, s56
	s_mov_b64 s[0:1], 0x1e000
	global_load_lds_dwordx4 v[2:3], off nt
	v_lshl_add_u64 v[2:3], v[182:183], 0, s[0:1]
	s_mov_b32 m0, s59
	s_mov_b64 s[0:1], 0x20000
	global_load_lds_dwordx4 v[2:3], off nt
	v_mov_b32_e32 v2, v0
	s_mov_b32 m0, s58
	v_add_u32_e32 v242, 0, v2
	v_add_u32_e32 v2, v242, v192
	ds_read_b128 v[166:169], v2
	ds_read_b128 v[170:173], v2 offset:8192
	ds_read_b128 v[174:177], v2 offset:16384
	ds_read_b128 v[222:225], v2 offset:24576
	ds_read_b128 v[226:229], v2 offset:32768
	ds_read_b128 v[230:233], v2 offset:40960
	ds_read_b128 v[234:237], v2 offset:49152
	ds_read_b128 v[238:241], v2 offset:57344
	s_waitcnt lgkmcnt(0)
	s_waitcnt lgkmcnt(0)
	v_mfma_f32_16x16x32_bf16 v[2:5], v[62:65], v[222:225], v[4:7]
	s_lshl_b32 s2, s40, 9
	s_mov_b32 s40, 0x3b000000
	s_ashr_i32 s3, s2, 31
	v_add_u32_e32 v6, v242, v193
	v_mfma_f32_16x16x32_bf16 v[16:19], v[62:65], v[166:169], v[16:19]
	s_lshl_b64 s[12:13], s[2:3], 2
	s_add_u32 s10, s16, s12
	s_addc_u32 s11, s17, s13
	v_mfma_f32_16x16x32_bf16 v[12:15], v[62:65], v[170:173], v[12:15]
	s_lshl_b32 s29, s29, 7
	v_mfma_f32_16x16x32_bf16 v[8:11], v[62:65], v[174:177], v[8:11]
	v_mfma_f32_16x16x32_bf16 v[162:165], v[62:65], v[226:229], v[162:165]
	v_mfma_f32_16x16x32_bf16 v[28:31], v[62:65], v[230:233], v[28:31]
	v_mfma_f32_16x16x32_bf16 v[24:27], v[62:65], v[234:237], v[24:27]
	v_mfma_f32_16x16x32_bf16 v[20:23], v[62:65], v[238:241], v[20:23]
	ds_read_b128 v[166:169], v6
	ds_read_b128 v[170:173], v6 offset:8192
	ds_read_b128 v[174:177], v6 offset:16384
	ds_read_b128 v[222:225], v6 offset:24576
	ds_read_b128 v[226:229], v6 offset:32768
	ds_read_b128 v[230:233], v6 offset:40960
	ds_read_b128 v[234:237], v6 offset:49152
	ds_read_b128 v[238:241], v6 offset:57344
	s_waitcnt lgkmcnt(0)
	s_waitcnt lgkmcnt(0)
	v_mfma_f32_16x16x32_bf16 v[6:9], v[58:61], v[174:177], v[8:11]
	s_nop 2
	v_add_u32_e32 v10, v242, v194
	v_mfma_f32_16x16x32_bf16 v[16:19], v[58:61], v[166:169], v[16:19]
	v_mfma_f32_16x16x32_bf16 v[12:15], v[58:61], v[170:173], v[12:15]
	v_mfma_f32_16x16x32_bf16 v[2:5], v[58:61], v[222:225], v[2:5]
	v_mfma_f32_16x16x32_bf16 v[162:165], v[58:61], v[226:229], v[162:165]
	v_mfma_f32_16x16x32_bf16 v[28:31], v[58:61], v[230:233], v[28:31]
	v_mfma_f32_16x16x32_bf16 v[24:27], v[58:61], v[234:237], v[24:27]
	v_mfma_f32_16x16x32_bf16 v[20:23], v[58:61], v[238:241], v[20:23]
	ds_read_b128 v[166:169], v10
	ds_read_b128 v[170:173], v10 offset:8192
	ds_read_b128 v[174:177], v10 offset:16384
	ds_read_b128 v[222:225], v10 offset:24576
	ds_read_b128 v[226:229], v10 offset:32768
	ds_read_b128 v[230:233], v10 offset:40960
	ds_read_b128 v[234:237], v10 offset:49152
	ds_read_b128 v[238:241], v10 offset:57344
	s_waitcnt lgkmcnt(0)
	s_waitcnt lgkmcnt(0)
	v_mfma_f32_16x16x32_bf16 v[10:13], v[54:57], v[170:173], v[12:15]
	s_nop 2
	v_add_u32_e32 v14, v242, v195
	v_mfma_f32_16x16x32_bf16 v[16:19], v[54:57], v[166:169], v[16:19]
	v_mfma_f32_16x16x32_bf16 v[6:9], v[54:57], v[174:177], v[6:9]
	v_mfma_f32_16x16x32_bf16 v[2:5], v[54:57], v[222:225], v[2:5]
	v_mfma_f32_16x16x32_bf16 v[162:165], v[54:57], v[226:229], v[162:165]
	v_mfma_f32_16x16x32_bf16 v[28:31], v[54:57], v[230:233], v[28:31]
	v_mfma_f32_16x16x32_bf16 v[24:27], v[54:57], v[234:237], v[24:27]
	v_mfma_f32_16x16x32_bf16 v[20:23], v[54:57], v[238:241], v[20:23]
	ds_read_b128 v[166:169], v14
	ds_read_b128 v[170:173], v14 offset:8192
	ds_read_b128 v[174:177], v14 offset:16384
	ds_read_b128 v[222:225], v14 offset:24576
	ds_read_b128 v[226:229], v14 offset:32768
	ds_read_b128 v[230:233], v14 offset:40960
	ds_read_b128 v[234:237], v14 offset:49152
	ds_read_b128 v[238:241], v14 offset:57344
	s_waitcnt lgkmcnt(0)
	s_waitcnt lgkmcnt(0)
; #define LAS __attribute__((address_space(3)))
; #define MFMA16(a, b, c) __builtin_amdgcn_mfma_f32_16x16x32_bf16((a), (b), (c), 0, 0, 0)
; #define WAITV0() asm volatile("s_waitcnt vmcnt(0)" ::: "memory")
; #define LBAR() do { asm volatile("s_waitcnt lgkmcnt(0)" ::: "memory"); __builtin_amdgcn_s_barrier(); asm volatile("" ::: "memory"); } while (0)
; __device__ __forceinline__ void retc_stream(const int wv, LAS unsigned char* lds, unsigned ldsb, const float* __restrict__ gn_g, const float* __restrict__ gn_b, const bf16_t* __restrict__ qkvr, const bf16_t* __restrict__ grb, const bf16_t* __restrict__ kv, ...
;     ...
;         for (int vc = 0; vc < 4; ++vc) {
;             WAITV0(); LBAR();
;             if (vc < 3) RETC_ISSUE(item, 5 + vc);
;             unsigned img = (vc & 1) * 65536u; asm volatile("" : "+v"(img));
; #pragma unroll
;             for (int s = 0; s < 8; ++s) {
;                 bf16x8 bfr[8];
; #pragma unroll
;                 for (int c = 0; c < 8; ++c) bfr[c] = *(const LAS bf16x8*)(lds + img + c * 8192 + koff[s]);
;                 asm volatile("s_waitcnt lgkmcnt(0)" ::: "memory");
; #pragma unroll
;                 for (int c = 0; c < 8; ++c) acc[vc * 8 + c] = MFMA16(qf[s], bfr[c], acc[vc * 8 + c]);
;             }
	v_mfma_f32_16x16x32_bf16 v[14:17], v[50:53], v[166:169], v[16:19]
	v_mfma_f32_16x16x32_bf16 v[18:21], v[50:53], v[238:241], v[20:23]
	s_nop 2
	v_add_u32_e32 v22, v242, v196
	v_mfma_f32_16x16x32_bf16 v[10:13], v[50:53], v[170:173], v[10:13]
	v_mfma_f32_16x16x32_bf16 v[6:9], v[50:53], v[174:177], v[6:9]
	v_mfma_f32_16x16x32_bf16 v[2:5], v[50:53], v[222:225], v[2:5]
	v_mfma_f32_16x16x32_bf16 v[162:165], v[50:53], v[226:229], v[162:165]
	v_mfma_f32_16x16x32_bf16 v[28:31], v[50:53], v[230:233], v[28:31]
	v_mfma_f32_16x16x32_bf16 v[24:27], v[50:53], v[234:237], v[24:27]
	ds_read_b128 v[166:169], v22
	ds_read_b128 v[170:173], v22 offset:8192
	ds_read_b128 v[174:177], v22 offset:16384
	ds_read_b128 v[222:225], v22 offset:24576
	ds_read_b128 v[226:229], v22 offset:32768
	ds_read_b128 v[230:233], v22 offset:40960
	ds_read_b128 v[234:237], v22 offset:49152
	ds_read_b128 v[238:241], v22 offset:57344
	s_waitcnt lgkmcnt(0)
	s_waitcnt lgkmcnt(0)
	v_mfma_f32_16x16x32_bf16 v[22:25], v[46:49], v[234:237], v[24:27]
	s_nop 2
	v_add_u32_e32 v26, v242, v197
	v_mfma_f32_16x16x32_bf16 v[14:17], v[46:49], v[166:169], v[14:17]
	v_mfma_f32_16x16x32_bf16 v[10:13], v[46:49], v[170:173], v[10:13]
	v_mfma_f32_16x16x32_bf16 v[6:9], v[46:49], v[174:177], v[6:9]
	v_mfma_f32_16x16x32_bf16 v[2:5], v[46:49], v[222:225], v[2:5]
	v_mfma_f32_16x16x32_bf16 v[162:165], v[46:49], v[226:229], v[162:165]
	v_mfma_f32_16x16x32_bf16 v[28:31], v[46:49], v[230:233], v[28:31]
	v_mfma_f32_16x16x32_bf16 v[18:21], v[46:49], v[238:241], v[18:21]
	ds_read_b128 v[166:169], v26
	ds_read_b128 v[170:173], v26 offset:8192
	ds_read_b128 v[174:177], v26 offset:16384
	ds_read_b128 v[222:225], v26 offset:24576
	ds_read_b128 v[226:229], v26 offset:32768
	ds_read_b128 v[230:233], v26 offset:40960
	ds_read_b128 v[234:237], v26 offset:49152
	ds_read_b128 v[238:241], v26 offset:57344
	s_waitcnt lgkmcnt(0)
	s_waitcnt lgkmcnt(0)
	v_mfma_f32_16x16x32_bf16 v[14:17], v[42:45], v[166:169], v[14:17]
	v_mfma_f32_16x16x32_bf16 v[162:165], v[42:45], v[226:229], v[162:165]
	v_mfma_f32_16x16x32_bf16 v[22:25], v[42:45], v[234:237], v[22:25]
	v_add_u32_e32 v234, v242, v198
	v_mfma_f32_16x16x32_bf16 v[10:13], v[42:45], v[170:173], v[10:13]
	v_mfma_f32_16x16x32_bf16 v[6:9], v[42:45], v[174:177], v[6:9]
	v_mfma_f32_16x16x32_bf16 v[2:5], v[42:45], v[222:225], v[2:5]
	v_mfma_f32_16x16x32_bf16 v[26:29], v[42:45], v[230:233], v[28:31]
	s_nop 2
	ds_read_b128 v[30:33], v234
	ds_read_b128 v[166:169], v234 offset:8192
	ds_read_b128 v[170:173], v234 offset:16384
	ds_read_b128 v[174:177], v234 offset:24576
	ds_read_b128 v[222:225], v234 offset:32768
	ds_read_b128 v[226:229], v234 offset:40960
	ds_read_b128 v[230:233], v234 offset:49152
	ds_read_b128 v[234:237], v234 offset:57344
	s_waitcnt lgkmcnt(0)
	v_mfma_f32_16x16x32_bf16 v[18:21], v[42:45], v[238:241], v[18:21]
	s_waitcnt lgkmcnt(0)
	v_mfma_f32_16x16x32_bf16 v[14:17], v[38:41], v[30:33], v[14:17]
	v_mfma_f32_16x16x32_bf16 v[162:165], v[38:41], v[222:225], v[162:165]
	v_mfma_f32_16x16x32_bf16 v[10:13], v[38:41], v[166:169], v[10:13]
	v_mfma_f32_16x16x32_bf16 v[166:169], v[38:41], v[226:229], v[26:29]
	s_nop 2
	v_add_u32_e32 v26, v242, v199
	v_mfma_f32_16x16x32_bf16 v[6:9], v[38:41], v[170:173], v[6:9]
	v_mfma_f32_16x16x32_bf16 v[2:5], v[38:41], v[174:177], v[2:5]
	v_mfma_f32_16x16x32_bf16 v[170:173], v[38:41], v[230:233], v[22:25]
	v_mfma_f32_16x16x32_bf16 v[174:177], v[38:41], v[234:237], v[18:21]
	s_nop 2
	ds_read_b128 v[18:21], v26
	ds_read_b128 v[22:25], v26 offset:8192
	ds_read_b128 v[222:225], v26 offset:16384
	ds_read_b128 v[226:229], v26 offset:24576
	ds_read_b128 v[230:233], v26 offset:32768
	ds_read_b128 v[234:237], v26 offset:40960
	ds_read_b128 v[238:241], v26 offset:49152
	ds_read_b128 v[242:245], v26 offset:57344
	s_waitcnt lgkmcnt(0)
	s_waitcnt vmcnt(0)
	s_waitcnt lgkmcnt(0)
	v_mfma_f32_16x16x32_bf16 v[26:29], v[34:37], v[18:21], v[14:17]
	s_waitcnt lgkmcnt(0)
	s_barrier
	v_mfma_f32_16x16x32_bf16 v[14:17], v[34:37], v[230:233], v[162:165]
	s_nop 2
	v_lshl_add_u64 v[162:163], v[182:183], 0, s[0:1]
	s_mov_b64 s[0:1], 0x22000
	global_load_lds_dwordx4 v[162:163], off nt
	v_lshl_add_u64 v[162:163], v[182:183], 0, s[0:1]
	s_mov_b32 m0, s47
	s_mov_b64 s[0:1], 0x24000
	global_load_lds_dwordx4 v[162:163], off nt
	v_lshl_add_u64 v[162:163], v[182:183], 0, s[0:1]
	s_mov_b32 m0, s24
	s_mov_b64 s[0:1], 0x26000
	global_load_lds_dwordx4 v[162:163], off nt
	v_lshl_add_u64 v[162:163], v[182:183], 0, s[0:1]
	s_mov_b32 m0, s25
	s_mov_b64 s[0:1], 0x28000
	global_load_lds_dwordx4 v[162:163], off nt
	v_lshl_add_u64 v[162:163], v[182:183], 0, s[0:1]
	s_mov_b32 m0, s48
	s_mov_b64 s[0:1], 0x2a000
	global_load_lds_dwordx4 v[162:163], off nt
	v_lshl_add_u64 v[162:163], v[182:183], 0, s[0:1]
	s_mov_b32 m0, s49
	s_mov_b64 s[0:1], 0x2c000
	global_load_lds_dwordx4 v[162:163], off nt
	v_lshl_add_u64 v[162:163], v[182:183], 0, s[0:1]
	s_mov_b32 m0, s50
	s_mov_b64 s[0:1], 0x2e000
	global_load_lds_dwordx4 v[162:163], off nt
	v_lshl_add_u64 v[162:163], v[182:183], 0, s[0:1]
	s_mov_b32 m0, s51
	v_mfma_f32_16x16x32_bf16 v[30:33], v[34:37], v[22:25], v[10:13]
	global_load_lds_dwordx4 v[162:163], off nt
	v_mov_b32_e32 v162, 0x10000
	v_mfma_f32_16x16x32_bf16 v[22:25], v[34:37], v[222:225], v[6:9]
	s_mov_b64 s[0:1], 0x30000
	s_mov_b32 m0, s46
	v_mfma_f32_16x16x32_bf16 v[6:9], v[34:37], v[238:241], v[170:173]
	v_add_u32_e32 v238, 0, v162
	v_mfma_f32_16x16x32_bf16 v[10:13], v[34:37], v[234:237], v[166:169]
	v_add_u32_e32 v234, v238, v192
	v_mfma_f32_16x16x32_bf16 v[18:21], v[34:37], v[226:229], v[2:5]
	v_mfma_f32_16x16x32_bf16 v[2:5], v[34:37], v[242:245], v[174:177]
	ds_read_b128 v[162:165], v234
	ds_read_b128 v[166:169], v234 offset:8192
	ds_read_b128 v[170:173], v234 offset:16384
	ds_read_b128 v[174:177], v234 offset:24576
	ds_read_b128 v[222:225], v234 offset:32768
	ds_read_b128 v[226:229], v234 offset:40960
	ds_read_b128 v[230:233], v234 offset:49152
	ds_read_b128 v[234:237], v234 offset:57344
	s_waitcnt lgkmcnt(0)
; #define LAS __attribute__((address_space(3)))
; #define MFMA16(a, b, c) __builtin_amdgcn_mfma_f32_16x16x32_bf16((a), (b), (c), 0, 0, 0)
; #define WAITV0() asm volatile("s_waitcnt vmcnt(0)" ::: "memory")
; #define LBAR() do { asm volatile("s_waitcnt lgkmcnt(0)" ::: "memory"); __builtin_amdgcn_s_barrier(); asm volatile("" ::: "memory"); } while (0)
; __device__ __forceinline__ void retc_stream(const int wv, LAS unsigned char* lds, unsigned ldsb, const float* __restrict__ gn_g, const float* __restrict__ gn_b, const bf16_t* __restrict__ qkvr, const bf16_t* __restrict__ grb, const bf16_t* __restrict__ kv, ...
;     ...
;         for (int vc = 0; vc < 4; ++vc) {
;             WAITV0(); LBAR();
;             if (vc < 3) RETC_ISSUE(item, 5 + vc);
;             unsigned img = (vc & 1) * 65536u; asm volatile("" : "+v"(img));
; #pragma unroll
;             for (int s = 0; s < 8; ++s) {
;                 bf16x8 bfr[8];
; #pragma unroll
;                 for (int c = 0; c < 8; ++c) bfr[c] = *(const LAS bf16x8*)(lds + img + c * 8192 + koff[s]);
;                 asm volatile("s_waitcnt lgkmcnt(0)" ::: "memory");
; #pragma unroll
;                 for (int c = 0; c < 8; ++c) acc[vc * 8 + c] = MFMA16(qf[s], bfr[c], acc[vc * 8 + c]);
;             }
	s_waitcnt lgkmcnt(0)
	v_mfma_f32_16x16x32_bf16 v[82:85], v[62:65], v[234:237], v[82:85]
	v_add_u32_e32 v234, v238, v193
	v_mfma_f32_16x16x32_bf16 v[78:81], v[62:65], v[162:165], v[78:81]
	v_mfma_f32_16x16x32_bf16 v[74:77], v[62:65], v[166:169], v[74:77]
	v_mfma_f32_16x16x32_bf16 v[70:73], v[62:65], v[170:173], v[70:73]
	v_mfma_f32_16x16x32_bf16 v[66:69], v[62:65], v[174:177], v[66:69]
	v_mfma_f32_16x16x32_bf16 v[94:97], v[62:65], v[222:225], v[94:97]
	v_mfma_f32_16x16x32_bf16 v[90:93], v[62:65], v[226:229], v[90:93]
	v_mfma_f32_16x16x32_bf16 v[86:89], v[62:65], v[230:233], v[86:89]
	ds_read_b128 v[162:165], v234
	ds_read_b128 v[166:169], v234 offset:8192
	ds_read_b128 v[170:173], v234 offset:16384
	ds_read_b128 v[174:177], v234 offset:24576
	ds_read_b128 v[222:225], v234 offset:32768
	ds_read_b128 v[226:229], v234 offset:40960
	ds_read_b128 v[230:233], v234 offset:49152
	ds_read_b128 v[234:237], v234 offset:57344
	s_waitcnt lgkmcnt(0)
	s_waitcnt lgkmcnt(0)
	v_mfma_f32_16x16x32_bf16 v[82:85], v[58:61], v[234:237], v[82:85]
	v_add_u32_e32 v234, v238, v194
	v_mfma_f32_16x16x32_bf16 v[78:81], v[58:61], v[162:165], v[78:81]
	v_mfma_f32_16x16x32_bf16 v[74:77], v[58:61], v[166:169], v[74:77]
	v_mfma_f32_16x16x32_bf16 v[70:73], v[58:61], v[170:173], v[70:73]
	v_mfma_f32_16x16x32_bf16 v[66:69], v[58:61], v[174:177], v[66:69]
	v_mfma_f32_16x16x32_bf16 v[94:97], v[58:61], v[222:225], v[94:97]
	v_mfma_f32_16x16x32_bf16 v[90:93], v[58:61], v[226:229], v[90:93]
	v_mfma_f32_16x16x32_bf16 v[86:89], v[58:61], v[230:233], v[86:89]
	ds_read_b128 v[162:165], v234
	ds_read_b128 v[166:169], v234 offset:8192
	ds_read_b128 v[170:173], v234 offset:16384
	ds_read_b128 v[174:177], v234 offset:24576
	ds_read_b128 v[222:225], v234 offset:32768
	ds_read_b128 v[226:229], v234 offset:40960
	ds_read_b128 v[230:233], v234 offset:49152
	ds_read_b128 v[234:237], v234 offset:57344
	s_waitcnt lgkmcnt(0)
	s_waitcnt lgkmcnt(0)
	v_mfma_f32_16x16x32_bf16 v[82:85], v[54:57], v[234:237], v[82:85]
	v_add_u32_e32 v234, v238, v195
	v_mfma_f32_16x16x32_bf16 v[78:81], v[54:57], v[162:165], v[78:81]
	v_mfma_f32_16x16x32_bf16 v[74:77], v[54:57], v[166:169], v[74:77]
	v_mfma_f32_16x16x32_bf16 v[70:73], v[54:57], v[170:173], v[70:73]
	v_mfma_f32_16x16x32_bf16 v[66:69], v[54:57], v[174:177], v[66:69]
	v_mfma_f32_16x16x32_bf16 v[94:97], v[54:57], v[222:225], v[94:97]
	v_mfma_f32_16x16x32_bf16 v[90:93], v[54:57], v[226:229], v[90:93]
	v_mfma_f32_16x16x32_bf16 v[86:89], v[54:57], v[230:233], v[86:89]
	ds_read_b128 v[162:165], v234
	ds_read_b128 v[166:169], v234 offset:8192
	ds_read_b128 v[170:173], v234 offset:16384
	ds_read_b128 v[174:177], v234 offset:24576
	ds_read_b128 v[222:225], v234 offset:32768
	ds_read_b128 v[226:229], v234 offset:40960
	ds_read_b128 v[230:233], v234 offset:49152
	ds_read_b128 v[234:237], v234 offset:57344
	s_waitcnt lgkmcnt(0)
	s_waitcnt lgkmcnt(0)
	v_mfma_f32_16x16x32_bf16 v[82:85], v[50:53], v[234:237], v[82:85]
	v_add_u32_e32 v234, v238, v196
	v_mfma_f32_16x16x32_bf16 v[78:81], v[50:53], v[162:165], v[78:81]
	v_mfma_f32_16x16x32_bf16 v[74:77], v[50:53], v[166:169], v[74:77]
	v_mfma_f32_16x16x32_bf16 v[70:73], v[50:53], v[170:173], v[70:73]
	v_mfma_f32_16x16x32_bf16 v[66:69], v[50:53], v[174:177], v[66:69]
	v_mfma_f32_16x16x32_bf16 v[94:97], v[50:53], v[222:225], v[94:97]
	v_mfma_f32_16x16x32_bf16 v[90:93], v[50:53], v[226:229], v[90:93]
	v_mfma_f32_16x16x32_bf16 v[86:89], v[50:53], v[230:233], v[86:89]
	ds_read_b128 v[162:165], v234
	ds_read_b128 v[166:169], v234 offset:8192
	ds_read_b128 v[170:173], v234 offset:16384
	ds_read_b128 v[174:177], v234 offset:24576
	ds_read_b128 v[222:225], v234 offset:32768
	ds_read_b128 v[226:229], v234 offset:40960
	ds_read_b128 v[230:233], v234 offset:49152
	ds_read_b128 v[234:237], v234 offset:57344
	s_waitcnt lgkmcnt(0)
	s_waitcnt lgkmcnt(0)
	v_mfma_f32_16x16x32_bf16 v[82:85], v[46:49], v[234:237], v[82:85]
	v_add_u32_e32 v234, v238, v197
	v_mfma_f32_16x16x32_bf16 v[78:81], v[46:49], v[162:165], v[78:81]
	v_mfma_f32_16x16x32_bf16 v[74:77], v[46:49], v[166:169], v[74:77]
	v_mfma_f32_16x16x32_bf16 v[70:73], v[46:49], v[170:173], v[70:73]
	v_mfma_f32_16x16x32_bf16 v[66:69], v[46:49], v[174:177], v[66:69]
	v_mfma_f32_16x16x32_bf16 v[94:97], v[46:49], v[222:225], v[94:97]
	v_mfma_f32_16x16x32_bf16 v[90:93], v[46:49], v[226:229], v[90:93]
	v_mfma_f32_16x16x32_bf16 v[86:89], v[46:49], v[230:233], v[86:89]
	ds_read_b128 v[162:165], v234
	ds_read_b128 v[166:169], v234 offset:8192
	ds_read_b128 v[170:173], v234 offset:16384
	ds_read_b128 v[174:177], v234 offset:24576
	ds_read_b128 v[222:225], v234 offset:32768
	ds_read_b128 v[226:229], v234 offset:40960
	ds_read_b128 v[230:233], v234 offset:49152
	ds_read_b128 v[234:237], v234 offset:57344
	s_waitcnt lgkmcnt(0)
	s_waitcnt lgkmcnt(0)
	v_mfma_f32_16x16x32_bf16 v[78:81], v[42:45], v[162:165], v[78:81]
	v_mfma_f32_16x16x32_bf16 v[94:97], v[42:45], v[222:225], v[94:97]
	v_mfma_f32_16x16x32_bf16 v[82:85], v[42:45], v[234:237], v[82:85]
	v_add_u32_e32 v234, v238, v198
	v_mfma_f32_16x16x32_bf16 v[74:77], v[42:45], v[166:169], v[74:77]
	v_mfma_f32_16x16x32_bf16 v[70:73], v[42:45], v[170:173], v[70:73]
	v_mfma_f32_16x16x32_bf16 v[66:69], v[42:45], v[174:177], v[66:69]
	v_mfma_f32_16x16x32_bf16 v[90:93], v[42:45], v[226:229], v[90:93]
	v_mfma_f32_16x16x32_bf16 v[86:89], v[42:45], v[230:233], v[86:89]
	ds_read_b128 v[162:165], v234
	ds_read_b128 v[166:169], v234 offset:8192
	ds_read_b128 v[170:173], v234 offset:16384
	ds_read_b128 v[174:177], v234 offset:24576
	ds_read_b128 v[222:225], v234 offset:32768
	ds_read_b128 v[226:229], v234 offset:40960
	ds_read_b128 v[230:233], v234 offset:49152
	ds_read_b128 v[234:237], v234 offset:57344
	s_waitcnt lgkmcnt(0)
	s_waitcnt lgkmcnt(0)
	v_mfma_f32_16x16x32_bf16 v[78:81], v[38:41], v[162:165], v[78:81]
	v_mfma_f32_16x16x32_bf16 v[162:165], v[38:41], v[222:225], v[94:97]
	v_mfma_f32_16x16x32_bf16 v[74:77], v[38:41], v[166:169], v[74:77]
	v_mfma_f32_16x16x32_bf16 v[166:169], v[38:41], v[226:229], v[90:93]
	s_nop 2
	v_add_u32_e32 v90, v238, v199
	v_mfma_f32_16x16x32_bf16 v[70:73], v[38:41], v[170:173], v[70:73]
	v_mfma_f32_16x16x32_bf16 v[66:69], v[38:41], v[174:177], v[66:69]
	v_mfma_f32_16x16x32_bf16 v[170:173], v[38:41], v[230:233], v[86:89]
	v_mfma_f32_16x16x32_bf16 v[174:177], v[38:41], v[234:237], v[82:85]
	s_nop 2
	ds_read_b128 v[82:85], v90
	ds_read_b128 v[86:89], v90 offset:8192
	ds_read_b128 v[222:225], v90 offset:16384
	ds_read_b128 v[226:229], v90 offset:24576
	ds_read_b128 v[230:233], v90 offset:32768
	ds_read_b128 v[234:237], v90 offset:40960
	ds_read_b128 v[238:241], v90 offset:49152
	ds_read_b128 v[242:245], v90 offset:57344
	s_waitcnt lgkmcnt(0)
	s_waitcnt vmcnt(0)
	s_waitcnt lgkmcnt(0)
	v_mfma_f32_16x16x32_bf16 v[94:97], v[34:37], v[82:85], v[78:81]
	s_waitcnt lgkmcnt(0)
	s_barrier
; #define LAS __attribute__((address_space(3)))
; #define MFMA16(a, b, c) __builtin_amdgcn_mfma_f32_16x16x32_bf16((a), (b), (c), 0, 0, 0)
; #define WAITV0() asm volatile("s_waitcnt vmcnt(0)" ::: "memory")
; #define LBAR() do { asm volatile("s_waitcnt lgkmcnt(0)" ::: "memory"); __builtin_amdgcn_s_barrier(); asm volatile("" ::: "memory"); } while (0)
; __device__ __forceinline__ void retc_stream(const int wv, LAS unsigned char* lds, unsigned ldsb, const float* __restrict__ gn_g, const float* __restrict__ gn_b, const bf16_t* __restrict__ qkvr, const bf16_t* __restrict__ grb, const bf16_t* __restrict__ kv, ...
;     ...
;         for (int vc = 0; vc < 4; ++vc) {
;             WAITV0(); LBAR();
;             if (vc < 3) RETC_ISSUE(item, 5 + vc);
;             unsigned img = (vc & 1) * 65536u; asm volatile("" : "+v"(img));
; #pragma unroll
;             for (int s = 0; s < 8; ++s) {
;                 bf16x8 bfr[8];
; #pragma unroll
;                 for (int c = 0; c < 8; ++c) bfr[c] = *(const LAS bf16x8*)(lds + img + c * 8192 + koff[s]);
;                 asm volatile("s_waitcnt lgkmcnt(0)" ::: "memory");
; #pragma unroll
;                 for (int c = 0; c < 8; ++c) acc[vc * 8 + c] = MFMA16(qf[s], bfr[c], acc[vc * 8 + c]);
;             }
	v_mfma_f32_16x16x32_bf16 v[78:81], v[34:37], v[230:233], v[162:165]
	s_nop 2
	v_lshl_add_u64 v[162:163], v[182:183], 0, s[0:1]
	s_mov_b64 s[0:1], 0x32000
	global_load_lds_dwordx4 v[162:163], off nt
	v_lshl_add_u64 v[162:163], v[182:183], 0, s[0:1]
	s_mov_b32 m0, s53
	s_mov_b64 s[0:1], 0x34000
	global_load_lds_dwordx4 v[162:163], off nt
	v_lshl_add_u64 v[162:163], v[182:183], 0, s[0:1]
	s_mov_b32 m0, s52
	s_mov_b64 s[0:1], 0x36000
	global_load_lds_dwordx4 v[162:163], off nt
	v_lshl_add_u64 v[162:163], v[182:183], 0, s[0:1]
	s_mov_b32 m0, s55
	s_mov_b64 s[0:1], 0x38000
	global_load_lds_dwordx4 v[162:163], off nt
	v_lshl_add_u64 v[162:163], v[182:183], 0, s[0:1]
	s_mov_b32 m0, s54
	s_mov_b64 s[0:1], 0x3a000
	global_load_lds_dwordx4 v[162:163], off nt
	v_lshl_add_u64 v[162:163], v[182:183], 0, s[0:1]
	s_mov_b32 m0, s57
	s_mov_b64 s[0:1], 0x3c000
	global_load_lds_dwordx4 v[162:163], off nt
	v_lshl_add_u64 v[162:163], v[182:183], 0, s[0:1]
	s_mov_b32 m0, s56
	s_mov_b64 s[0:1], 0x3e000
	global_load_lds_dwordx4 v[162:163], off nt
	v_lshl_add_u64 v[162:163], v[182:183], 0, s[0:1]
	s_mov_b32 m0, s59
	v_mfma_f32_16x16x32_bf16 v[90:93], v[34:37], v[86:89], v[74:77]
	global_load_lds_dwordx4 v[162:163], off nt
	v_mov_b32_e32 v162, v0
	v_mfma_f32_16x16x32_bf16 v[86:89], v[34:37], v[222:225], v[70:73]
	s_mov_b32 s0, 0x358637bd
	v_mfma_f32_16x16x32_bf16 v[70:73], v[34:37], v[238:241], v[170:173]
	v_add_u32_e32 v238, 0, v162
	v_mfma_f32_16x16x32_bf16 v[74:77], v[34:37], v[234:237], v[166:169]
	v_add_u32_e32 v234, v238, v192
	v_mfma_f32_16x16x32_bf16 v[82:85], v[34:37], v[226:229], v[66:69]
	v_mfma_f32_16x16x32_bf16 v[66:69], v[34:37], v[242:245], v[174:177]
	ds_read_b128 v[162:165], v234
	ds_read_b128 v[166:169], v234 offset:8192
	ds_read_b128 v[170:173], v234 offset:16384
	ds_read_b128 v[174:177], v234 offset:24576
	ds_read_b128 v[222:225], v234 offset:32768
	ds_read_b128 v[226:229], v234 offset:40960
	ds_read_b128 v[230:233], v234 offset:49152
	ds_read_b128 v[234:237], v234 offset:57344
	s_waitcnt lgkmcnt(0)
	s_waitcnt lgkmcnt(0)
	v_mfma_f32_16x16x32_bf16 v[114:117], v[62:65], v[234:237], v[114:117]
	v_add_u32_e32 v234, v238, v193
	v_mfma_f32_16x16x32_bf16 v[110:113], v[62:65], v[162:165], v[110:113]
	v_mfma_f32_16x16x32_bf16 v[106:109], v[62:65], v[166:169], v[106:109]
	v_mfma_f32_16x16x32_bf16 v[102:105], v[62:65], v[170:173], v[102:105]
	v_mfma_f32_16x16x32_bf16 v[98:101], v[62:65], v[174:177], v[98:101]
	v_mfma_f32_16x16x32_bf16 v[126:129], v[62:65], v[222:225], v[126:129]
	v_mfma_f32_16x16x32_bf16 v[122:125], v[62:65], v[226:229], v[122:125]
	v_mfma_f32_16x16x32_bf16 v[118:121], v[62:65], v[230:233], v[118:121]
	ds_read_b128 v[162:165], v234
	ds_read_b128 v[166:169], v234 offset:8192
	ds_read_b128 v[170:173], v234 offset:16384
	ds_read_b128 v[174:177], v234 offset:24576
	ds_read_b128 v[222:225], v234 offset:32768
	ds_read_b128 v[226:229], v234 offset:40960
	ds_read_b128 v[230:233], v234 offset:49152
	ds_read_b128 v[234:237], v234 offset:57344
	s_waitcnt lgkmcnt(0)
	s_waitcnt lgkmcnt(0)
	v_mfma_f32_16x16x32_bf16 v[114:117], v[58:61], v[234:237], v[114:117]
	v_add_u32_e32 v234, v238, v194
	v_mfma_f32_16x16x32_bf16 v[110:113], v[58:61], v[162:165], v[110:113]
	v_mfma_f32_16x16x32_bf16 v[106:109], v[58:61], v[166:169], v[106:109]
	v_mfma_f32_16x16x32_bf16 v[102:105], v[58:61], v[170:173], v[102:105]
	v_mfma_f32_16x16x32_bf16 v[98:101], v[58:61], v[174:177], v[98:101]
	v_mfma_f32_16x16x32_bf16 v[126:129], v[58:61], v[222:225], v[126:129]
	v_mfma_f32_16x16x32_bf16 v[122:125], v[58:61], v[226:229], v[122:125]
	v_mfma_f32_16x16x32_bf16 v[118:121], v[58:61], v[230:233], v[118:121]
	ds_read_b128 v[162:165], v234
	ds_read_b128 v[166:169], v234 offset:8192
	ds_read_b128 v[170:173], v234 offset:16384
	ds_read_b128 v[174:177], v234 offset:24576
	ds_read_b128 v[222:225], v234 offset:32768
	ds_read_b128 v[226:229], v234 offset:40960
	ds_read_b128 v[230:233], v234 offset:49152
	ds_read_b128 v[234:237], v234 offset:57344
	s_waitcnt lgkmcnt(0)
	s_waitcnt lgkmcnt(0)
	v_mfma_f32_16x16x32_bf16 v[114:117], v[54:57], v[234:237], v[114:117]
	v_add_u32_e32 v234, v238, v195
	v_mfma_f32_16x16x32_bf16 v[110:113], v[54:57], v[162:165], v[110:113]
	v_mfma_f32_16x16x32_bf16 v[106:109], v[54:57], v[166:169], v[106:109]
	v_mfma_f32_16x16x32_bf16 v[102:105], v[54:57], v[170:173], v[102:105]
	v_mfma_f32_16x16x32_bf16 v[98:101], v[54:57], v[174:177], v[98:101]
	v_mfma_f32_16x16x32_bf16 v[126:129], v[54:57], v[222:225], v[126:129]
	v_mfma_f32_16x16x32_bf16 v[122:125], v[54:57], v[226:229], v[122:125]
	v_mfma_f32_16x16x32_bf16 v[118:121], v[54:57], v[230:233], v[118:121]
	ds_read_b128 v[162:165], v234
	ds_read_b128 v[166:169], v234 offset:8192
	ds_read_b128 v[170:173], v234 offset:16384
	ds_read_b128 v[174:177], v234 offset:24576
	ds_read_b128 v[222:225], v234 offset:32768
	ds_read_b128 v[226:229], v234 offset:40960
	ds_read_b128 v[230:233], v234 offset:49152
	ds_read_b128 v[234:237], v234 offset:57344
	s_waitcnt lgkmcnt(0)
	s_waitcnt lgkmcnt(0)
	v_mfma_f32_16x16x32_bf16 v[114:117], v[50:53], v[234:237], v[114:117]
	v_add_u32_e32 v234, v238, v196
	v_mfma_f32_16x16x32_bf16 v[110:113], v[50:53], v[162:165], v[110:113]
	v_mfma_f32_16x16x32_bf16 v[106:109], v[50:53], v[166:169], v[106:109]
	v_mfma_f32_16x16x32_bf16 v[102:105], v[50:53], v[170:173], v[102:105]
	v_mfma_f32_16x16x32_bf16 v[98:101], v[50:53], v[174:177], v[98:101]
	v_mfma_f32_16x16x32_bf16 v[126:129], v[50:53], v[222:225], v[126:129]
	v_mfma_f32_16x16x32_bf16 v[122:125], v[50:53], v[226:229], v[122:125]
	v_mfma_f32_16x16x32_bf16 v[118:121], v[50:53], v[230:233], v[118:121]
	ds_read_b128 v[162:165], v234
	ds_read_b128 v[166:169], v234 offset:8192
	ds_read_b128 v[170:173], v234 offset:16384
	ds_read_b128 v[174:177], v234 offset:24576
	ds_read_b128 v[222:225], v234 offset:32768
	ds_read_b128 v[226:229], v234 offset:40960
	ds_read_b128 v[230:233], v234 offset:49152
	ds_read_b128 v[234:237], v234 offset:57344
	s_waitcnt lgkmcnt(0)
; #define LAS __attribute__((address_space(3)))
; #define MFMA16(a, b, c) __builtin_amdgcn_mfma_f32_16x16x32_bf16((a), (b), (c), 0, 0, 0)
; #define WAITV0() asm volatile("s_waitcnt vmcnt(0)" ::: "memory")
; #define LBAR() do { asm volatile("s_waitcnt lgkmcnt(0)" ::: "memory"); __builtin_amdgcn_s_barrier(); asm volatile("" ::: "memory"); } while (0)
; __device__ __forceinline__ void retc_stream(const int wv, LAS unsigned char* lds, unsigned ldsb, const float* __restrict__ gn_g, const float* __restrict__ gn_b, const bf16_t* __restrict__ qkvr, const bf16_t* __restrict__ grb, const bf16_t* __restrict__ kv, ...
;     ...
;         for (int vc = 0; vc < 4; ++vc) {
;             WAITV0(); LBAR();
;             if (vc < 3) RETC_ISSUE(item, 5 + vc);
;             unsigned img = (vc & 1) * 65536u; asm volatile("" : "+v"(img));
; #pragma unroll
;             for (int s = 0; s < 8; ++s) {
;                 bf16x8 bfr[8];
; #pragma unroll
;                 for (int c = 0; c < 8; ++c) bfr[c] = *(const LAS bf16x8*)(lds + img + c * 8192 + koff[s]);
;                 asm volatile("s_waitcnt lgkmcnt(0)" ::: "memory");
; #pragma unroll
;                 for (int c = 0; c < 8; ++c) acc[vc * 8 + c] = MFMA16(qf[s], bfr[c], acc[vc * 8 + c]);
;             }
	s_waitcnt lgkmcnt(0)
	v_mfma_f32_16x16x32_bf16 v[114:117], v[46:49], v[234:237], v[114:117]
	v_add_u32_e32 v234, v238, v197
	v_mfma_f32_16x16x32_bf16 v[110:113], v[46:49], v[162:165], v[110:113]
	v_mfma_f32_16x16x32_bf16 v[106:109], v[46:49], v[166:169], v[106:109]
	v_mfma_f32_16x16x32_bf16 v[102:105], v[46:49], v[170:173], v[102:105]
	v_mfma_f32_16x16x32_bf16 v[98:101], v[46:49], v[174:177], v[98:101]
	v_mfma_f32_16x16x32_bf16 v[126:129], v[46:49], v[222:225], v[126:129]
	v_mfma_f32_16x16x32_bf16 v[122:125], v[46:49], v[226:229], v[122:125]
	v_mfma_f32_16x16x32_bf16 v[118:121], v[46:49], v[230:233], v[118:121]
	ds_read_b128 v[162:165], v234
	ds_read_b128 v[166:169], v234 offset:8192
	ds_read_b128 v[170:173], v234 offset:16384
	ds_read_b128 v[174:177], v234 offset:24576
	ds_read_b128 v[222:225], v234 offset:32768
	ds_read_b128 v[226:229], v234 offset:40960
	ds_read_b128 v[230:233], v234 offset:49152
	ds_read_b128 v[234:237], v234 offset:57344
	s_waitcnt lgkmcnt(0)
	s_waitcnt lgkmcnt(0)
	v_mfma_f32_16x16x32_bf16 v[114:117], v[42:45], v[234:237], v[114:117]
	v_add_u32_e32 v234, v238, v198
	v_mfma_f32_16x16x32_bf16 v[110:113], v[42:45], v[162:165], v[110:113]
	v_mfma_f32_16x16x32_bf16 v[106:109], v[42:45], v[166:169], v[106:109]
	v_mfma_f32_16x16x32_bf16 v[102:105], v[42:45], v[170:173], v[102:105]
	v_mfma_f32_16x16x32_bf16 v[98:101], v[42:45], v[174:177], v[98:101]
	v_mfma_f32_16x16x32_bf16 v[126:129], v[42:45], v[222:225], v[126:129]
	v_mfma_f32_16x16x32_bf16 v[122:125], v[42:45], v[226:229], v[122:125]
	v_mfma_f32_16x16x32_bf16 v[118:121], v[42:45], v[230:233], v[118:121]
	ds_read_b128 v[162:165], v234
	ds_read_b128 v[166:169], v234 offset:8192
	ds_read_b128 v[170:173], v234 offset:16384
	ds_read_b128 v[174:177], v234 offset:24576
	ds_read_b128 v[222:225], v234 offset:32768
	ds_read_b128 v[226:229], v234 offset:40960
	ds_read_b128 v[230:233], v234 offset:49152
	ds_read_b128 v[234:237], v234 offset:57344
	s_waitcnt lgkmcnt(0)
	s_waitcnt lgkmcnt(0)
	v_mfma_f32_16x16x32_bf16 v[110:113], v[38:41], v[162:165], v[110:113]
	v_mfma_f32_16x16x32_bf16 v[106:109], v[38:41], v[166:169], v[106:109]
	v_mfma_f32_16x16x32_bf16 v[162:165], v[38:41], v[170:173], v[102:105]
	s_nop 2
	v_add_u32_e32 v102, v238, v199
	v_mfma_f32_16x16x32_bf16 v[166:169], v[38:41], v[174:177], v[98:101]
	v_mfma_f32_16x16x32_bf16 v[170:173], v[38:41], v[222:225], v[126:129]
	v_mfma_f32_16x16x32_bf16 v[174:177], v[38:41], v[226:229], v[122:125]
	v_mfma_f32_16x16x32_bf16 v[222:225], v[38:41], v[230:233], v[118:121]
	v_mfma_f32_16x16x32_bf16 v[226:229], v[38:41], v[234:237], v[114:117]
	ds_read_b128 v[98:101], v102
	s_nop 1
	ds_read_b128 v[114:117], v102 offset:8192
	ds_read_b128 v[118:121], v102 offset:16384
	ds_read_b128 v[122:125], v102 offset:24576
	ds_read_b128 v[230:233], v102 offset:32768
	ds_read_b128 v[234:237], v102 offset:40960
	ds_read_b128 v[238:241], v102 offset:49152
	ds_read_b128 v[242:245], v102 offset:57344
	s_waitcnt lgkmcnt(0)
	s_waitcnt vmcnt(0)
	s_waitcnt lgkmcnt(0)
	v_mfma_f32_16x16x32_bf16 v[102:105], v[34:37], v[98:101], v[110:113]
	s_waitcnt lgkmcnt(0)
	s_barrier
	v_mfma_f32_16x16x32_bf16 v[98:101], v[34:37], v[114:117], v[106:109]
	v_mfma_f32_16x16x32_bf16 v[106:109], v[34:37], v[118:121], v[162:165]
	s_nop 2
	v_mov_b32_e32 v162, 0x10000
	v_mfma_f32_16x16x32_bf16 v[114:117], v[34:37], v[238:241], v[222:225]
	s_nop 0
	v_add_u32_e32 v238, 0, v162
	v_mfma_f32_16x16x32_bf16 v[118:121], v[34:37], v[234:237], v[174:177]
	v_add_u32_e32 v234, v238, v192
	v_mfma_f32_16x16x32_bf16 v[126:129], v[34:37], v[122:125], v[166:169]
	v_mfma_f32_16x16x32_bf16 v[122:125], v[34:37], v[230:233], v[170:173]
	v_mfma_f32_16x16x32_bf16 v[110:113], v[34:37], v[242:245], v[226:229]
	ds_read_b128 v[162:165], v234
	ds_read_b128 v[166:169], v234 offset:8192
	ds_read_b128 v[170:173], v234 offset:16384
	ds_read_b128 v[174:177], v234 offset:24576
	ds_read_b128 v[222:225], v234 offset:32768
	ds_read_b128 v[226:229], v234 offset:40960
	ds_read_b128 v[230:233], v234 offset:49152
	ds_read_b128 v[234:237], v234 offset:57344
	s_waitcnt lgkmcnt(0)
	s_waitcnt lgkmcnt(0)
	v_mfma_f32_16x16x32_bf16 v[150:153], v[62:65], v[230:233], v[150:153]
	v_add_u32_e32 v230, v238, v193
	v_mfma_f32_16x16x32_bf16 v[142:145], v[62:65], v[162:165], v[142:145]
	v_mfma_f32_16x16x32_bf16 v[138:141], v[62:65], v[166:169], v[138:141]
	v_mfma_f32_16x16x32_bf16 v[134:137], v[62:65], v[170:173], v[134:137]
	v_mfma_f32_16x16x32_bf16 v[130:133], v[62:65], v[174:177], v[130:133]
	v_mfma_f32_16x16x32_bf16 v[158:161], v[62:65], v[222:225], v[158:161]
	v_mfma_f32_16x16x32_bf16 v[154:157], v[62:65], v[226:229], v[154:157]
	v_mfma_f32_16x16x32_bf16 v[62:65], v[62:65], v[234:237], v[146:149]
	s_nop 2
	ds_read_b128 v[146:149], v230
	ds_read_b128 v[162:165], v230 offset:8192
	ds_read_b128 v[166:169], v230 offset:16384
	ds_read_b128 v[170:173], v230 offset:24576
	ds_read_b128 v[174:177], v230 offset:32768
	ds_read_b128 v[222:225], v230 offset:40960
	ds_read_b128 v[226:229], v230 offset:49152
	ds_read_b128 v[230:233], v230 offset:57344
	s_waitcnt lgkmcnt(0)
	s_waitcnt lgkmcnt(0)
	v_mfma_f32_16x16x32_bf16 v[150:153], v[58:61], v[226:229], v[150:153]
	v_add_u32_e32 v226, v238, v194
	v_mfma_f32_16x16x32_bf16 v[142:145], v[58:61], v[146:149], v[142:145]
	v_mfma_f32_16x16x32_bf16 v[138:141], v[58:61], v[162:165], v[138:141]
	v_mfma_f32_16x16x32_bf16 v[134:137], v[58:61], v[166:169], v[134:137]
	v_mfma_f32_16x16x32_bf16 v[130:133], v[58:61], v[170:173], v[130:133]
	v_mfma_f32_16x16x32_bf16 v[146:149], v[58:61], v[174:177], v[158:161]
	v_mfma_f32_16x16x32_bf16 v[154:157], v[58:61], v[222:225], v[154:157]
	v_mfma_f32_16x16x32_bf16 v[58:61], v[58:61], v[230:233], v[62:65]
	s_nop 2
	ds_read_b128 v[62:65], v226
	ds_read_b128 v[158:161], v226 offset:8192
	ds_read_b128 v[162:165], v226 offset:16384
	ds_read_b128 v[166:169], v226 offset:24576
	ds_read_b128 v[170:173], v226 offset:32768
	ds_read_b128 v[174:177], v226 offset:40960
	ds_read_b128 v[222:225], v226 offset:49152
	ds_read_b128 v[226:229], v226 offset:57344
	s_waitcnt lgkmcnt(0)
; #define LAS __attribute__((address_space(3)))
; #define MFMA16(a, b, c) __builtin_amdgcn_mfma_f32_16x16x32_bf16((a), (b), (c), 0, 0, 0)
; #define WAITV0() asm volatile("s_waitcnt vmcnt(0)" ::: "memory")
; #define LBAR() do { asm volatile("s_waitcnt lgkmcnt(0)" ::: "memory"); __builtin_amdgcn_s_barrier(); asm volatile("" ::: "memory"); } while (0)
; __device__ __forceinline__ void retc_stream(const int wv, LAS unsigned char* lds, unsigned ldsb, const float* __restrict__ gn_g, const float* __restrict__ gn_b, const bf16_t* __restrict__ qkvr, const bf16_t* __restrict__ grb, const bf16_t* __restrict__ kv, ...
;     ...
;         for (int vc = 0; vc < 4; ++vc) {
;             WAITV0(); LBAR();
;             if (vc < 3) RETC_ISSUE(item, 5 + vc);
;             unsigned img = (vc & 1) * 65536u; asm volatile("" : "+v"(img));
; #pragma unroll
;             for (int s = 0; s < 8; ++s) {
;                 bf16x8 bfr[8];
; #pragma unroll
;                 for (int c = 0; c < 8; ++c) bfr[c] = *(const LAS bf16x8*)(lds + img + c * 8192 + koff[s]);
;                 asm volatile("s_waitcnt lgkmcnt(0)" ::: "memory");
; #pragma unroll
;                 for (int c = 0; c < 8; ++c) acc[vc * 8 + c] = MFMA16(qf[s], bfr[c], acc[vc * 8 + c]);
;             }
	s_waitcnt lgkmcnt(0)
	v_mfma_f32_16x16x32_bf16 v[150:153], v[54:57], v[222:225], v[150:153]
	v_add_u32_e32 v222, v238, v195
	v_mfma_f32_16x16x32_bf16 v[62:65], v[54:57], v[62:65], v[142:145]
	v_mfma_f32_16x16x32_bf16 v[138:141], v[54:57], v[158:161], v[138:141]
	v_mfma_f32_16x16x32_bf16 v[134:137], v[54:57], v[162:165], v[134:137]
	v_mfma_f32_16x16x32_bf16 v[130:133], v[54:57], v[166:169], v[130:133]
	v_mfma_f32_16x16x32_bf16 v[142:145], v[54:57], v[170:173], v[146:149]
	v_mfma_f32_16x16x32_bf16 v[146:149], v[54:57], v[174:177], v[154:157]
	v_mfma_f32_16x16x32_bf16 v[54:57], v[54:57], v[226:229], v[58:61]
	s_nop 2
	ds_read_b128 v[58:61], v222
	ds_read_b128 v[154:157], v222 offset:8192
	ds_read_b128 v[158:161], v222 offset:16384
	ds_read_b128 v[162:165], v222 offset:24576
	ds_read_b128 v[166:169], v222 offset:32768
	ds_read_b128 v[170:173], v222 offset:40960
	ds_read_b128 v[174:177], v222 offset:49152
	ds_read_b128 v[222:225], v222 offset:57344
	s_waitcnt lgkmcnt(0)
	s_waitcnt lgkmcnt(0)
	v_mfma_f32_16x16x32_bf16 v[58:61], v[50:53], v[58:61], v[62:65]
	v_mfma_f32_16x16x32_bf16 v[62:65], v[50:53], v[154:157], v[138:141]
	v_mfma_f32_16x16x32_bf16 v[138:141], v[50:53], v[166:169], v[142:145]
	v_mfma_f32_16x16x32_bf16 v[142:145], v[50:53], v[170:173], v[146:149]
	v_mfma_f32_16x16x32_bf16 v[146:149], v[50:53], v[174:177], v[150:153]
	v_add_u32_e32 v174, v238, v196
	v_mfma_f32_16x16x32_bf16 v[134:137], v[50:53], v[158:161], v[134:137]
	v_mfma_f32_16x16x32_bf16 v[130:133], v[50:53], v[162:165], v[130:133]
	v_mfma_f32_16x16x32_bf16 v[50:53], v[50:53], v[222:225], v[54:57]
	s_nop 2
	ds_read_b128 v[54:57], v174
	ds_read_b128 v[150:153], v174 offset:8192
	ds_read_b128 v[154:157], v174 offset:16384
	ds_read_b128 v[158:161], v174 offset:24576
	ds_read_b128 v[162:165], v174 offset:32768
	ds_read_b128 v[166:169], v174 offset:40960
	ds_read_b128 v[170:173], v174 offset:49152
	ds_read_b128 v[174:177], v174 offset:57344
	s_waitcnt lgkmcnt(0)
	s_waitcnt lgkmcnt(0)
	v_mfma_f32_16x16x32_bf16 v[54:57], v[46:49], v[54:57], v[58:61]
	v_mfma_f32_16x16x32_bf16 v[58:61], v[46:49], v[150:153], v[62:65]
	v_mfma_f32_16x16x32_bf16 v[62:65], v[46:49], v[154:157], v[134:137]
	v_mfma_f32_16x16x32_bf16 v[134:137], v[46:49], v[162:165], v[138:141]
	v_mfma_f32_16x16x32_bf16 v[138:141], v[46:49], v[166:169], v[142:145]
	v_mfma_f32_16x16x32_bf16 v[142:145], v[46:49], v[170:173], v[146:149]
	v_add_u32_e32 v170, v238, v197
	v_mfma_f32_16x16x32_bf16 v[130:133], v[46:49], v[158:161], v[130:133]
	v_mfma_f32_16x16x32_bf16 v[46:49], v[46:49], v[174:177], v[50:53]
	s_nop 2
	ds_read_b128 v[50:53], v170
	ds_read_b128 v[146:149], v170 offset:8192
	ds_read_b128 v[150:153], v170 offset:16384
	ds_read_b128 v[154:157], v170 offset:24576
	ds_read_b128 v[158:161], v170 offset:32768
	ds_read_b128 v[162:165], v170 offset:40960
	ds_read_b128 v[166:169], v170 offset:49152
	ds_read_b128 v[170:173], v170 offset:57344
	s_waitcnt lgkmcnt(0)
	s_waitcnt lgkmcnt(0)
	v_mfma_f32_16x16x32_bf16 v[50:53], v[42:45], v[50:53], v[54:57]
	v_mfma_f32_16x16x32_bf16 v[54:57], v[42:45], v[146:149], v[58:61]
	v_mfma_f32_16x16x32_bf16 v[58:61], v[42:45], v[150:153], v[62:65]
	v_mfma_f32_16x16x32_bf16 v[62:65], v[42:45], v[154:157], v[130:133]
	v_mfma_f32_16x16x32_bf16 v[130:133], v[42:45], v[158:161], v[134:137]
	v_mfma_f32_16x16x32_bf16 v[134:137], v[42:45], v[162:165], v[138:141]
	v_mfma_f32_16x16x32_bf16 v[138:141], v[42:45], v[166:169], v[142:145]
	v_add_u32_e32 v166, v238, v198
	v_mfma_f32_16x16x32_bf16 v[42:45], v[42:45], v[170:173], v[46:49]
	s_nop 2
	ds_read_b128 v[46:49], v166
	ds_read_b128 v[142:145], v166 offset:8192
	ds_read_b128 v[146:149], v166 offset:16384
	ds_read_b128 v[150:153], v166 offset:24576
	ds_read_b128 v[154:157], v166 offset:32768
	ds_read_b128 v[158:161], v166 offset:40960
	ds_read_b128 v[162:165], v166 offset:49152
	ds_read_b128 v[166:169], v166 offset:57344
	s_waitcnt lgkmcnt(0)
	s_waitcnt lgkmcnt(0)
	v_mfma_f32_16x16x32_bf16 v[46:49], v[38:41], v[46:49], v[50:53]
	v_mfma_f32_16x16x32_bf16 v[50:53], v[38:41], v[142:145], v[54:57]
	v_mfma_f32_16x16x32_bf16 v[54:57], v[38:41], v[146:149], v[58:61]
	v_mfma_f32_16x16x32_bf16 v[58:61], v[38:41], v[150:153], v[62:65]
	v_mfma_f32_16x16x32_bf16 v[62:65], v[38:41], v[154:157], v[130:133]
	v_mfma_f32_16x16x32_bf16 v[130:133], v[38:41], v[158:161], v[134:137]
	v_mfma_f32_16x16x32_bf16 v[134:137], v[38:41], v[162:165], v[138:141]
	v_add_u32_e32 v162, v238, v199
	v_mfma_f32_16x16x32_bf16 v[138:141], v[38:41], v[166:169], v[42:45]
	ds_read_b128 v[38:41], v162
	s_nop 1
	ds_read_b128 v[42:45], v162 offset:8192
	ds_read_b128 v[142:145], v162 offset:16384
	ds_read_b128 v[146:149], v162 offset:24576
	ds_read_b128 v[150:153], v162 offset:32768
	ds_read_b128 v[154:157], v162 offset:40960
	ds_read_b128 v[158:161], v162 offset:49152
	ds_read_b128 v[162:165], v162 offset:57344
	s_waitcnt lgkmcnt(0)
	s_waitcnt lgkmcnt(0)
	s_waitcnt lgkmcnt(0)
	v_mfma_f32_16x16x32_bf16 v[46:49], v[34:37], v[38:41], v[46:49]
	s_barrier
; __device__ __forceinline__ float shx(float v, int lane, int mask) { return __int_as_float(__builtin_amdgcn_ds_bpermute((lane ^ mask) << 2, __float_as_int(v))); }
; #define MFMA16(a, b, c) __builtin_amdgcn_mfma_f32_16x16x32_bf16((a), (b), (c), 0, 0, 0)
; __device__ __forceinline__ void retc_stream(const int wv, LAS unsigned char* lds, unsigned ldsb, const float* __restrict__ gn_g, const float* __restrict__ gn_b, const bf16_t* __restrict__ qkvr, const bf16_t* __restrict__ grb, const bf16_t* __restrict__ kv, ...
;     ...
;                 for (int c = 0; c < 8; ++c) acc[vc * 8 + c] = MFMA16(qf[s], bfr[c], acc[vc * 8 + c]);
;             }
;         }
;         const float* gng = gn_g + h * 512; const float* gnb = gn_b + h * 512;
;         float mu4[4], rs4[4];
; #pragma unroll
;         for (int e = 0; e < 4; ++e) {
;             const int q = 16 * w + 4 * g + e;
;             const float xi = exp2f(lg2 * (float)(q - 127));
;             float sum = 0.f;
; #pragma unroll
;             for (int c = 0; c < 32; ++c) { acc[c][e] *= xi; sum += acc[c][e]; }
;             sum += shx(sum, lane, 1); sum += shx(sum, lane, 2); sum += shx(sum, lane, 4); sum += shx(sum, lane, 8);
	v_mfma_f32_16x16x32_bf16 v[42:45], v[34:37], v[42:45], v[50:53]
	v_mfma_f32_16x16x32_bf16 v[38:41], v[34:37], v[142:145], v[54:57]
	v_mfma_f32_16x16x32_bf16 v[58:61], v[34:37], v[146:149], v[58:61]
	v_mfma_f32_16x16x32_bf16 v[50:53], v[34:37], v[150:153], v[62:65]
	v_mfma_f32_16x16x32_bf16 v[62:65], v[34:37], v[154:157], v[130:133]
	v_mfma_f32_16x16x32_bf16 v[54:57], v[34:37], v[158:161], v[134:137]
	s_nop 1
	v_mul_f32_e32 v130, v1, v213
	v_cmp_gt_f32_e32 vcc, s41, v130
	v_mfma_f32_16x16x32_bf16 v[34:37], v[34:37], v[162:165], v[138:141]
	s_nop 0
	v_cndmask_b32_e32 v130, 0, v187, vcc
	v_cndmask_b32_e32 v131, 0, v189, vcc
	v_fmac_f32_e32 v130, v1, v213
	v_exp_f32_e32 v130, v130
	v_mov_b32_e32 v133, v54
	s_nop 1
	v_mov_b32_e32 v132, v34
	v_mul_f32_e32 v34, v1, v214
	v_cmp_gt_f32_e32 vcc, s41, v34
	v_ldexp_f32 v130, v130, v131
	v_mov_b32_e32 v134, v62
	v_cndmask_b32_e32 v34, 0, v187, vcc
	v_fmac_f32_e32 v34, v1, v214
	v_exp_f32_e32 v34, v34
	v_mov_b32_e32 v135, v50
	v_mov_b32_e32 v136, v58
	v_mov_b32_e32 v137, v38
	v_cndmask_b32_e32 v38, 0, v189, vcc
	v_pk_mul_f32 v[138:139], v[130:131], v[132:133] op_sel_hi:[0,1]
	v_pk_mul_f32 v[140:141], v[130:131], v[134:135] op_sel_hi:[0,1]
	v_pk_mul_f32 v[142:143], v[130:131], v[136:137] op_sel_hi:[0,1]
	v_ldexp_f32 v131, v34, v38
	v_mov_b32_e32 v158, v131
	v_mov_b32_e32 v54, v35
	v_mov_b32_e32 v50, v63
	v_mov_b32_e32 v38, v59
	v_pk_mul_f32 v[34:35], v[158:159], v[54:55] op_sel_hi:[0,1]
	v_pk_mul_f32 v[62:63], v[158:159], v[50:51] op_sel_hi:[0,1]
	v_pk_mul_f32 v[58:59], v[158:159], v[38:39] op_sel_hi:[0,1]
	v_mov_b32_e32 v144, v139
	v_mov_b32_e32 v145, v35
	v_mov_b32_e32 v139, v34
	v_mov_b32_e32 v34, v143
	v_mov_b32_e32 v35, v59
	v_mov_b32_e32 v143, v58
	v_mov_b32_e32 v58, v141
	v_mov_b32_e32 v59, v63
	v_mov_b32_e32 v141, v62
	v_pk_fma_f32 v[62:63], v[130:131], v[26:27], 0 op_sel_hi:[1,1,0]
	s_nop 0
	v_pk_fma_f32 v[62:63], v[130:131], v[30:31], v[62:63]
	s_nop 0
	v_pk_fma_f32 v[62:63], v[130:131], v[22:23], v[62:63]
	s_nop 0
	v_pk_fma_f32 v[62:63], v[130:131], v[18:19], v[62:63]
	s_nop 0
	v_pk_fma_f32 v[62:63], v[130:131], v[14:15], v[62:63]
	s_nop 0
	v_pk_fma_f32 v[62:63], v[130:131], v[10:11], v[62:63]
	s_nop 0
	v_pk_fma_f32 v[62:63], v[130:131], v[6:7], v[62:63]
	s_nop 0
	v_pk_fma_f32 v[62:63], v[130:131], v[2:3], v[62:63]
	s_nop 0
	v_pk_fma_f32 v[62:63], v[130:131], v[94:95], v[62:63]
	s_nop 0
	v_pk_fma_f32 v[62:63], v[130:131], v[90:91], v[62:63]
	s_nop 0
	v_pk_fma_f32 v[62:63], v[130:131], v[86:87], v[62:63]
	s_nop 0
	v_pk_fma_f32 v[62:63], v[130:131], v[82:83], v[62:63]
	s_nop 0
	v_pk_fma_f32 v[62:63], v[130:131], v[78:79], v[62:63]
	s_nop 0
	v_pk_fma_f32 v[62:63], v[130:131], v[74:75], v[62:63]
	s_nop 0
	v_pk_fma_f32 v[62:63], v[130:131], v[70:71], v[62:63]
	s_nop 0
	v_pk_fma_f32 v[62:63], v[130:131], v[66:67], v[62:63]
	s_nop 0
	v_pk_fma_f32 v[62:63], v[130:131], v[102:103], v[62:63]
	s_nop 0
	v_pk_fma_f32 v[62:63], v[130:131], v[98:99], v[62:63]
	s_nop 0
	v_pk_fma_f32 v[62:63], v[130:131], v[106:107], v[62:63]
	s_nop 0
	v_pk_fma_f32 v[62:63], v[130:131], v[126:127], v[62:63]
	s_nop 0
	v_pk_fma_f32 v[62:63], v[130:131], v[122:123], v[62:63]
	s_nop 0
	v_pk_fma_f32 v[62:63], v[130:131], v[118:119], v[62:63]
	s_nop 0
	v_pk_fma_f32 v[62:63], v[130:131], v[114:115], v[62:63]
	s_nop 0
	v_pk_fma_f32 v[62:63], v[130:131], v[110:111], v[62:63]
	s_nop 0
	v_pk_fma_f32 v[62:63], v[130:131], v[46:47], v[62:63]
	s_nop 0
	v_pk_fma_f32 v[62:63], v[130:131], v[42:43], v[62:63]
	s_nop 0
	v_pk_add_f32 v[34:35], v[62:63], v[34:35]
	s_nop 0
	v_pk_add_f32 v[34:35], v[34:35], v[142:143]
	s_nop 0
	v_pk_add_f32 v[34:35], v[34:35], v[58:59]
	s_nop 0
	v_pk_add_f32 v[34:35], v[34:35], v[140:141]
	s_nop 0
	v_pk_add_f32 v[34:35], v[34:35], v[144:145]
	s_nop 0
	v_pk_add_f32 v[34:35], v[34:35], v[138:139]
	ds_bpermute_b32 v58, v208, v34
	ds_bpermute_b32 v59, v208, v35
	s_waitcnt lgkmcnt(0)
	v_pk_add_f32 v[34:35], v[34:35], v[58:59]
	ds_bpermute_b32 v58, v209, v34
	ds_bpermute_b32 v59, v209, v35
	s_waitcnt lgkmcnt(0)
	v_pk_add_f32 v[34:35], v[34:35], v[58:59]
	ds_bpermute_b32 v58, v210, v34
	ds_bpermute_b32 v59, v210, v35
	s_waitcnt lgkmcnt(0)
	v_pk_add_f32 v[34:35], v[34:35], v[58:59]
	ds_bpermute_b32 v58, v211, v34
	ds_bpermute_b32 v59, v211, v35
	s_waitcnt lgkmcnt(0)
; __device__ __forceinline__ float shx(float v, int lane, int mask) { return __int_as_float(__builtin_amdgcn_ds_bpermute((lane ^ mask) << 2, __float_as_int(v))); }
; __device__ __forceinline__ void retc_stream(const int wv, LAS unsigned char* lds, unsigned ldsb, const float* __restrict__ gn_g, const float* __restrict__ gn_b, const bf16_t* __restrict__ qkvr, const bf16_t* __restrict__ grb, const bf16_t* __restrict__ kv, ...
;     ...
;         for (int e = 0; e < 4; ++e) {
;             const int q = 16 * w + 4 * g + e;
;             const float xi = exp2f(lg2 * (float)(q - 127));
;             float sum = 0.f;
; #pragma unroll
;             for (int c = 0; c < 32; ++c) { acc[c][e] *= xi; sum += acc[c][e]; }
;             sum += shx(sum, lane, 1); sum += shx(sum, lane, 2); sum += shx(sum, lane, 4); sum += shx(sum, lane, 8);
;             const float mu = sum * (1.0f / 512.0f);
;             float var = 0.f;
; #pragma unroll
;             for (int c = 0; c < 32; ++c) { const float d = acc[c][e] - mu; var += d * d; }
;             var += shx(var, lane, 1); var += shx(var, lane, 2); var += shx(var, lane, 4); var += shx(var, lane, 8);
	v_pk_add_f32 v[34:35], v[34:35], v[58:59]
	s_nop 0
	v_pk_mul_f32 v[160:161], v[34:35], s[40:41] op_sel_hi:[1,0]
	s_nop 0
	v_pk_fma_f32 v[154:155], v[130:131], v[30:31], v[160:161] neg_lo:[0,0,1] neg_hi:[0,0,1]
	v_pk_fma_f32 v[156:157], v[130:131], v[26:27], v[160:161] neg_lo:[0,0,1] neg_hi:[0,0,1]
	v_pk_mul_f32 v[26:27], v[154:155], v[154:155]
	v_pk_fma_f32 v[152:153], v[130:131], v[22:23], v[160:161] neg_lo:[0,0,1] neg_hi:[0,0,1]
	v_pk_fma_f32 v[26:27], v[156:157], v[156:157], v[26:27]
	v_pk_fma_f32 v[150:151], v[130:131], v[18:19], v[160:161] neg_lo:[0,0,1] neg_hi:[0,0,1]
	v_pk_fma_f32 v[22:23], v[152:153], v[152:153], v[26:27]
	v_pk_fma_f32 v[148:149], v[130:131], v[14:15], v[160:161] neg_lo:[0,0,1] neg_hi:[0,0,1]
	v_pk_fma_f32 v[18:19], v[150:151], v[150:151], v[22:23]
	v_pk_fma_f32 v[146:147], v[130:131], v[10:11], v[160:161] neg_lo:[0,0,1] neg_hi:[0,0,1]
	v_pk_fma_f32 v[14:15], v[148:149], v[148:149], v[18:19]
	v_pk_fma_f32 v[144:145], v[130:131], v[6:7], v[160:161] neg_lo:[0,0,1] neg_hi:[0,0,1]
	v_pk_fma_f32 v[10:11], v[146:147], v[146:147], v[14:15]
	v_pk_fma_f32 v[142:143], v[130:131], v[2:3], v[160:161] neg_lo:[0,0,1] neg_hi:[0,0,1]
	v_pk_fma_f32 v[6:7], v[144:145], v[144:145], v[10:11]
	v_pk_fma_f32 v[140:141], v[130:131], v[94:95], v[160:161] neg_lo:[0,0,1] neg_hi:[0,0,1]
	v_pk_fma_f32 v[2:3], v[142:143], v[142:143], v[6:7]
	v_pk_fma_f32 v[138:139], v[130:131], v[90:91], v[160:161] neg_lo:[0,0,1] neg_hi:[0,0,1]
	v_pk_fma_f32 v[2:3], v[140:141], v[140:141], v[2:3]
	v_pk_fma_f32 v[62:63], v[130:131], v[136:137], v[160:161] op_sel_hi:[0,1,0] neg_lo:[0,0,1] neg_hi:[0,0,1]
	v_pk_fma_f32 v[2:3], v[138:139], v[138:139], v[2:3]
	v_pk_fma_f32 v[136:137], v[130:131], v[86:87], v[160:161] neg_lo:[0,0,1] neg_hi:[0,0,1]
	v_pk_fma_f32 v[58:59], v[130:131], v[134:135], v[160:161] op_sel_hi:[0,1,0] neg_lo:[0,0,1] neg_hi:[0,0,1]
	v_pk_fma_f32 v[2:3], v[136:137], v[136:137], v[2:3]
	v_pk_fma_f32 v[134:135], v[130:131], v[82:83], v[160:161] neg_lo:[0,0,1] neg_hi:[0,0,1]
	v_pk_fma_f32 v[34:35], v[130:131], v[132:133], v[160:161] op_sel_hi:[0,1,0] neg_lo:[0,0,1] neg_hi:[0,0,1]
	v_pk_fma_f32 v[2:3], v[134:135], v[134:135], v[2:3]
	v_pk_fma_f32 v[132:133], v[130:131], v[78:79], v[160:161] neg_lo:[0,0,1] neg_hi:[0,0,1]
	v_pk_fma_f32 v[94:95], v[130:131], v[74:75], v[160:161] neg_lo:[0,0,1] neg_hi:[0,0,1]
	v_pk_fma_f32 v[2:3], v[132:133], v[132:133], v[2:3]
	v_pk_fma_f32 v[90:91], v[130:131], v[70:71], v[160:161] neg_lo:[0,0,1] neg_hi:[0,0,1]
	v_pk_fma_f32 v[2:3], v[94:95], v[94:95], v[2:3]
	v_pk_fma_f32 v[86:87], v[130:131], v[66:67], v[160:161] neg_lo:[0,0,1] neg_hi:[0,0,1]
	v_pk_fma_f32 v[2:3], v[90:91], v[90:91], v[2:3]
	v_pk_fma_f32 v[82:83], v[130:131], v[102:103], v[160:161] neg_lo:[0,0,1] neg_hi:[0,0,1]
	v_pk_fma_f32 v[2:3], v[86:87], v[86:87], v[2:3]
	v_pk_fma_f32 v[78:79], v[130:131], v[98:99], v[160:161] neg_lo:[0,0,1] neg_hi:[0,0,1]
	v_pk_fma_f32 v[2:3], v[82:83], v[82:83], v[2:3]
	v_pk_fma_f32 v[74:75], v[130:131], v[106:107], v[160:161] neg_lo:[0,0,1] neg_hi:[0,0,1]
	v_pk_fma_f32 v[2:3], v[78:79], v[78:79], v[2:3]
	v_pk_fma_f32 v[70:71], v[130:131], v[126:127], v[160:161] neg_lo:[0,0,1] neg_hi:[0,0,1]
	v_pk_fma_f32 v[2:3], v[74:75], v[74:75], v[2:3]
	v_pk_fma_f32 v[66:67], v[130:131], v[122:123], v[160:161] neg_lo:[0,0,1] neg_hi:[0,0,1]
	v_pk_fma_f32 v[2:3], v[70:71], v[70:71], v[2:3]
	v_pk_fma_f32 v[30:31], v[130:131], v[118:119], v[160:161] neg_lo:[0,0,1] neg_hi:[0,0,1]
	v_pk_fma_f32 v[2:3], v[66:67], v[66:67], v[2:3]
	v_pk_fma_f32 v[26:27], v[130:131], v[114:115], v[160:161] neg_lo:[0,0,1] neg_hi:[0,0,1]
	v_pk_fma_f32 v[2:3], v[30:31], v[30:31], v[2:3]
	v_pk_fma_f32 v[22:23], v[130:131], v[110:111], v[160:161] neg_lo:[0,0,1] neg_hi:[0,0,1]
	v_pk_fma_f32 v[2:3], v[26:27], v[26:27], v[2:3]
	v_pk_fma_f32 v[18:19], v[130:131], v[46:47], v[160:161] neg_lo:[0,0,1] neg_hi:[0,0,1]
	v_pk_fma_f32 v[2:3], v[22:23], v[22:23], v[2:3]
	v_pk_fma_f32 v[10:11], v[158:159], v[38:39], v[160:161] op_sel:[0,0,1] op_sel_hi:[0,1,1] neg_lo:[0,0,1] neg_hi:[0,0,1]
	v_pk_mul_f32 v[162:163], v[62:63], v[62:63]
	v_pk_fma_f32 v[2:3], v[18:19], v[18:19], v[2:3]
	v_pk_fma_f32 v[14:15], v[130:131], v[42:43], v[160:161] neg_lo:[0,0,1] neg_hi:[0,0,1]
	v_pk_mul_f32 v[38:39], v[10:11], v[10:11]
	v_pk_fma_f32 v[42:43], v[14:15], v[14:15], v[2:3]
	v_pk_fma_f32 v[6:7], v[158:159], v[50:51], v[160:161] op_sel:[0,0,1] op_sel_hi:[0,1,1] neg_lo:[0,0,1] neg_hi:[0,0,1]
	v_pk_fma_f32 v[2:3], v[158:159], v[54:55], v[160:161] op_sel:[0,0,1] op_sel_hi:[0,1,1] neg_lo:[0,0,1] neg_hi:[0,0,1]
	v_mov_b32_e32 v55, v162
	v_mov_b32_e32 v162, v39
	v_pk_mul_f32 v[164:165], v[58:59], v[58:59]
	v_pk_mul_f32 v[46:47], v[6:7], v[6:7]
	v_mov_b32_e32 v54, v38
	v_pk_add_f32 v[38:39], v[162:163], v[42:43] op_sel:[0,1] op_sel_hi:[1,0]
	v_mov_b32_e32 v42, v47
	v_pk_add_f32 v[38:39], v[54:55], v[38:39]
	v_mov_b32_e32 v43, v165
	v_pk_mul_f32 v[166:167], v[34:35], v[34:35]
	v_pk_mul_f32 v[50:51], v[2:3], v[2:3]
	v_pk_add_f32 v[38:39], v[42:43], v[38:39]
	v_mov_b32_e32 v47, v164
	v_pk_add_f32 v[38:39], v[46:47], v[38:39]
	v_mov_b32_e32 v42, v51
	v_mov_b32_e32 v43, v167
	v_pk_add_f32 v[38:39], v[42:43], v[38:39]
	v_mov_b32_e32 v51, v166
	v_pk_add_f32 v[38:39], v[50:51], v[38:39]
	ds_bpermute_b32 v43, v208, v39
	ds_bpermute_b32 v42, v208, v38
	v_mov_b64_e32 v[46:47], s[0:1]
	v_mov_b32_e32 v50, v36
	v_mul_f32_e32 v36, v1, v216
	v_mov_b32_e32 v51, v56
	s_waitcnt lgkmcnt(0)
	v_pk_add_f32 v[38:39], v[38:39], v[42:43]
	ds_bpermute_b32 v43, v209, v39
	ds_bpermute_b32 v42, v209, v38
	v_mov_b32_e32 v102, v60
	v_mov_b32_e32 v103, v40
	v_mov_b32_e32 v56, v37
	v_mov_b32_e32 v40, v61
	s_waitcnt lgkmcnt(0)
; __device__ __forceinline__ float shx(float v, int lane, int mask) { return __int_as_float(__builtin_amdgcn_ds_bpermute((lane ^ mask) << 2, __float_as_int(v))); }
; __device__ __forceinline__ void retc_stream(const int wv, LAS unsigned char* lds, unsigned ldsb, const float* __restrict__ gn_g, const float* __restrict__ gn_b, const bf16_t* __restrict__ qkvr, const bf16_t* __restrict__ grb, const bf16_t* __restrict__ kv, ...
;     ...
;         for (int e = 0; e < 4; ++e) {
;             const int q = 16 * w + 4 * g + e;
;             const float xi = exp2f(lg2 * (float)(q - 127));
;             float sum = 0.f;
; #pragma unroll
;             for (int c = 0; c < 32; ++c) { acc[c][e] *= xi; sum += acc[c][e]; }
;             sum += shx(sum, lane, 1); sum += shx(sum, lane, 2); sum += shx(sum, lane, 4); sum += shx(sum, lane, 8);
;             const float mu = sum * (1.0f / 512.0f);
;             float var = 0.f;
; #pragma unroll
;             for (int c = 0; c < 32; ++c) { const float d = acc[c][e] - mu; var += d * d; }
;             var += shx(var, lane, 1); var += shx(var, lane, 2); var += shx(var, lane, 4); var += shx(var, lane, 8);
;             mu4[e] = mu; rs4[e] = rsqrtf(var * (1.0f / 512.0f) + EPS);
	v_pk_add_f32 v[38:39], v[38:39], v[42:43]
	ds_bpermute_b32 v43, v210, v39
	ds_bpermute_b32 v42, v210, v38
	s_waitcnt lgkmcnt(0)
	v_pk_add_f32 v[38:39], v[38:39], v[42:43]
	ds_bpermute_b32 v43, v211, v39
	ds_bpermute_b32 v42, v211, v38
	s_waitcnt lgkmcnt(0)
	v_pk_add_f32 v[38:39], v[38:39], v[42:43]
	s_nop 0
	v_pk_fma_f32 v[38:39], v[38:39], s[40:41], v[46:47] op_sel_hi:[1,0,0]
	s_nop 0
	v_mul_f32_e32 v42, 0x4b800000, v39
	v_cmp_gt_f32_e64 s[0:1], s36, v39
	v_cmp_gt_f32_e32 vcc, s36, v38
	s_nop 0
	v_cndmask_b32_e64 v39, v39, v42, s[0:1]
	v_rsq_f32_e32 v39, v39
	s_nop 0
	v_mul_f32_e32 v42, 0x45800000, v39
	v_cndmask_b32_e64 v110, v39, v42, s[0:1]
	v_mul_f32_e32 v39, 0x4b800000, v38
	v_cndmask_b32_e32 v38, v38, v39, vcc
	v_rsq_f32_e32 v38, v38
	v_mul_f32_e32 v30, v30, v110
	v_mul_f32_e32 v26, v26, v110
	v_mul_f32_e32 v22, v22, v110
	v_mul_f32_e32 v39, 0x45800000, v38
	v_cndmask_b32_e32 v111, v38, v39, vcc
	v_mul_f32_e32 v38, v1, v215
	v_cmp_gt_f32_e32 vcc, s41, v38
	v_mul_f32_e32 v18, v18, v110
	v_mul_f32_e32 v14, v14, v110
	v_cndmask_b32_e32 v38, 0, v187, vcc
	v_cndmask_b32_e32 v39, 0, v189, vcc
	v_cmp_gt_f32_e32 vcc, s41, v36
	v_fmac_f32_e32 v38, v1, v215
	v_exp_f32_e32 v38, v38
	v_cndmask_b32_e32 v36, 0, v187, vcc
	v_fmac_f32_e32 v36, v1, v216
	v_exp_f32_e32 v1, v36
	v_ldexp_f32 v98, v38, v39
	v_mov_b32_e32 v38, v64
	v_mov_b32_e32 v39, v52
	v_cndmask_b32_e32 v36, 0, v189, vcc
	v_pk_mul_f32 v[42:43], v[98:99], v[50:51] op_sel_hi:[0,1]
	v_pk_mul_f32 v[54:55], v[98:99], v[38:39] op_sel_hi:[0,1]
	v_pk_mul_f32 v[106:107], v[98:99], v[102:103] op_sel_hi:[0,1]
	v_ldexp_f32 v99, v1, v36
	v_mov_b32_e32 v114, v99
	v_mov_b32_e32 v52, v65
	v_pk_mul_f32 v[36:37], v[114:115], v[56:57] op_sel_hi:[0,1]
	v_pk_mul_f32 v[64:65], v[114:115], v[52:53] op_sel_hi:[0,1]
	v_pk_mul_f32 v[60:61], v[114:115], v[40:41] op_sel_hi:[0,1]
	v_mov_b32_e32 v118, v43
	v_mov_b32_e32 v119, v37
	v_mov_b32_e32 v43, v36
	v_mov_b32_e32 v36, v107
	v_mov_b32_e32 v37, v61
	v_mov_b32_e32 v107, v60
	v_mov_b32_e32 v60, v55
	v_mov_b32_e32 v61, v65
	v_mov_b32_e32 v55, v64
	v_pk_fma_f32 v[64:65], v[98:99], v[28:29], 0 op_sel_hi:[1,1,0]
	v_mul_f32_e32 v11, v11, v111
	v_pk_fma_f32 v[64:65], v[98:99], v[32:33], v[64:65]
	v_mul_f32_e32 v10, v10, v111
	v_pk_fma_f32 v[64:65], v[98:99], v[24:25], v[64:65]
	v_mul_f32_e32 v7, v7, v111
	v_pk_fma_f32 v[64:65], v[98:99], v[20:21], v[64:65]
	v_mul_f32_e32 v6, v6, v111
	v_pk_fma_f32 v[64:65], v[98:99], v[16:17], v[64:65]
	v_mul_f32_e32 v3, v3, v111
	v_pk_fma_f32 v[64:65], v[98:99], v[12:13], v[64:65]
	v_mul_f32_e32 v2, v2, v111
	v_pk_fma_f32 v[64:65], v[98:99], v[8:9], v[64:65]
	s_nop 0
	v_pk_fma_f32 v[64:65], v[98:99], v[4:5], v[64:65]
	s_nop 0
	v_pk_fma_f32 v[64:65], v[98:99], v[96:97], v[64:65]
	s_nop 0
	v_pk_fma_f32 v[64:65], v[98:99], v[92:93], v[64:65]
	s_nop 0
	v_pk_fma_f32 v[64:65], v[98:99], v[88:89], v[64:65]
	s_nop 0
	v_pk_fma_f32 v[64:65], v[98:99], v[84:85], v[64:65]
	s_nop 0
	v_pk_fma_f32 v[64:65], v[98:99], v[80:81], v[64:65]
	s_nop 0
	v_pk_fma_f32 v[64:65], v[98:99], v[76:77], v[64:65]
	s_nop 0
	v_pk_fma_f32 v[64:65], v[98:99], v[72:73], v[64:65]
	s_nop 0
	v_pk_fma_f32 v[64:65], v[98:99], v[68:69], v[64:65]
	s_nop 0
	v_pk_fma_f32 v[64:65], v[98:99], v[104:105], v[64:65]
	s_nop 0
	v_pk_fma_f32 v[64:65], v[98:99], v[100:101], v[64:65]
	s_nop 0
	v_pk_fma_f32 v[64:65], v[98:99], v[108:109], v[64:65]
	s_nop 0
	v_pk_fma_f32 v[64:65], v[98:99], v[128:129], v[64:65]
	s_nop 0
	v_pk_fma_f32 v[64:65], v[98:99], v[124:125], v[64:65]
	s_nop 0
	v_pk_fma_f32 v[64:65], v[98:99], v[120:121], v[64:65]
	s_nop 0
	v_pk_fma_f32 v[64:65], v[98:99], v[116:117], v[64:65]
	s_nop 0
	v_pk_fma_f32 v[64:65], v[98:99], v[112:113], v[64:65]
	s_nop 0
	v_pk_fma_f32 v[64:65], v[98:99], v[48:49], v[64:65]
	s_nop 0
	v_pk_fma_f32 v[64:65], v[98:99], v[44:45], v[64:65]
	s_nop 0
	v_pk_add_f32 v[36:37], v[64:65], v[36:37]
	s_nop 0
	v_pk_add_f32 v[36:37], v[36:37], v[106:107]
	s_nop 0
	v_pk_add_f32 v[36:37], v[36:37], v[60:61]
	s_nop 0
	v_pk_add_f32 v[36:37], v[36:37], v[54:55]
	s_nop 0
	v_pk_add_f32 v[36:37], v[36:37], v[118:119]
	s_nop 0
	v_pk_add_f32 v[36:37], v[36:37], v[42:43]
	ds_bpermute_b32 v42, v208, v36
	ds_bpermute_b32 v43, v208, v37
	s_waitcnt lgkmcnt(0)
	v_pk_add_f32 v[36:37], v[36:37], v[42:43]
	ds_bpermute_b32 v42, v209, v36
	ds_bpermute_b32 v43, v209, v37
	s_waitcnt lgkmcnt(0)
	v_pk_add_f32 v[36:37], v[36:37], v[42:43]
	ds_bpermute_b32 v42, v210, v36
	ds_bpermute_b32 v43, v210, v37
	s_waitcnt lgkmcnt(0)
	v_pk_add_f32 v[36:37], v[36:37], v[42:43]
	ds_bpermute_b32 v42, v211, v36
	ds_bpermute_b32 v43, v211, v37
	s_waitcnt lgkmcnt(0)
; __device__ __forceinline__ float shx(float v, int lane, int mask) { return __int_as_float(__builtin_amdgcn_ds_bpermute((lane ^ mask) << 2, __float_as_int(v))); }
; __device__ __forceinline__ void retc_stream(const int wv, LAS unsigned char* lds, unsigned ldsb, const float* __restrict__ gn_g, const float* __restrict__ gn_b, const bf16_t* __restrict__ qkvr, const bf16_t* __restrict__ grb, const bf16_t* __restrict__ kv, ...
;     ...
;             for (int c = 0; c < 32; ++c) { acc[c][e] *= xi; sum += acc[c][e]; }
;             sum += shx(sum, lane, 1); sum += shx(sum, lane, 2); sum += shx(sum, lane, 4); sum += shx(sum, lane, 8);
;             const float mu = sum * (1.0f / 512.0f);
;             float var = 0.f;
; #pragma unroll
;             for (int c = 0; c < 32; ++c) { const float d = acc[c][e] - mu; var += d * d; }
;             var += shx(var, lane, 1); var += shx(var, lane, 2); var += shx(var, lane, 4); var += shx(var, lane, 8);
	v_pk_add_f32 v[36:37], v[36:37], v[42:43]
	s_nop 0
	v_pk_mul_f32 v[118:119], v[36:37], s[40:41] op_sel_hi:[1,0]
	s_nop 0
	v_pk_fma_f32 v[160:161], v[98:99], v[32:33], v[118:119] neg_lo:[0,0,1] neg_hi:[0,0,1]
	v_pk_fma_f32 v[158:159], v[98:99], v[28:29], v[118:119] neg_lo:[0,0,1] neg_hi:[0,0,1]
	v_pk_mul_f32 v[28:29], v[160:161], v[160:161]
	v_pk_fma_f32 v[162:163], v[98:99], v[24:25], v[118:119] neg_lo:[0,0,1] neg_hi:[0,0,1]
	v_pk_fma_f32 v[28:29], v[158:159], v[158:159], v[28:29]
	v_pk_fma_f32 v[164:165], v[98:99], v[20:21], v[118:119] neg_lo:[0,0,1] neg_hi:[0,0,1]
	v_pk_fma_f32 v[24:25], v[162:163], v[162:163], v[28:29]
	v_pk_fma_f32 v[166:167], v[98:99], v[16:17], v[118:119] neg_lo:[0,0,1] neg_hi:[0,0,1]
	v_pk_fma_f32 v[20:21], v[164:165], v[164:165], v[24:25]
	v_pk_fma_f32 v[168:169], v[98:99], v[12:13], v[118:119] neg_lo:[0,0,1] neg_hi:[0,0,1]
	v_pk_fma_f32 v[16:17], v[166:167], v[166:167], v[20:21]
	v_pk_fma_f32 v[170:171], v[98:99], v[8:9], v[118:119] neg_lo:[0,0,1] neg_hi:[0,0,1]
	v_pk_fma_f32 v[12:13], v[168:169], v[168:169], v[16:17]
	v_pk_fma_f32 v[106:107], v[98:99], v[4:5], v[118:119] neg_lo:[0,0,1] neg_hi:[0,0,1]
	v_pk_fma_f32 v[8:9], v[170:171], v[170:171], v[12:13]
	v_pk_fma_f32 v[42:43], v[98:99], v[102:103], v[118:119] op_sel_hi:[0,1,0] neg_lo:[0,0,1] neg_hi:[0,0,1]
	v_pk_fma_f32 v[4:5], v[106:107], v[106:107], v[8:9]
	v_pk_fma_f32 v[102:103], v[98:99], v[96:97], v[118:119] neg_lo:[0,0,1] neg_hi:[0,0,1]
	v_pk_fma_f32 v[96:97], v[98:99], v[92:93], v[118:119] neg_lo:[0,0,1] neg_hi:[0,0,1]
	v_pk_fma_f32 v[4:5], v[102:103], v[102:103], v[4:5]
	v_pk_fma_f32 v[92:93], v[98:99], v[88:89], v[118:119] neg_lo:[0,0,1] neg_hi:[0,0,1]
	v_pk_fma_f32 v[4:5], v[96:97], v[96:97], v[4:5]
	v_pk_fma_f32 v[88:89], v[98:99], v[84:85], v[118:119] neg_lo:[0,0,1] neg_hi:[0,0,1]
	v_pk_fma_f32 v[4:5], v[92:93], v[92:93], v[4:5]
	v_pk_fma_f32 v[84:85], v[98:99], v[80:81], v[118:119] neg_lo:[0,0,1] neg_hi:[0,0,1]
	v_pk_fma_f32 v[4:5], v[88:89], v[88:89], v[4:5]
	v_pk_fma_f32 v[80:81], v[98:99], v[76:77], v[118:119] neg_lo:[0,0,1] neg_hi:[0,0,1]
	v_pk_fma_f32 v[4:5], v[84:85], v[84:85], v[4:5]
	v_pk_fma_f32 v[76:77], v[98:99], v[72:73], v[118:119] neg_lo:[0,0,1] neg_hi:[0,0,1]
	v_pk_fma_f32 v[4:5], v[80:81], v[80:81], v[4:5]
	v_pk_fma_f32 v[72:73], v[98:99], v[68:69], v[118:119] neg_lo:[0,0,1] neg_hi:[0,0,1]
	v_pk_fma_f32 v[4:5], v[76:77], v[76:77], v[4:5]
	v_pk_fma_f32 v[68:69], v[98:99], v[104:105], v[118:119] neg_lo:[0,0,1] neg_hi:[0,0,1]
	v_pk_fma_f32 v[4:5], v[72:73], v[72:73], v[4:5]
	v_pk_fma_f32 v[64:65], v[98:99], v[100:101], v[118:119] neg_lo:[0,0,1] neg_hi:[0,0,1]
	v_pk_fma_f32 v[4:5], v[68:69], v[68:69], v[4:5]
	v_pk_fma_f32 v[60:61], v[98:99], v[108:109], v[118:119] neg_lo:[0,0,1] neg_hi:[0,0,1]
	v_pk_fma_f32 v[4:5], v[64:65], v[64:65], v[4:5]
	v_pk_fma_f32 v[54:55], v[98:99], v[128:129], v[118:119] neg_lo:[0,0,1] neg_hi:[0,0,1]
	v_pk_fma_f32 v[4:5], v[60:61], v[60:61], v[4:5]
	v_pk_fma_f32 v[36:37], v[98:99], v[50:51], v[118:119] op_sel_hi:[0,1,0] neg_lo:[0,0,1] neg_hi:[0,0,1]
	v_pk_fma_f32 v[4:5], v[54:55], v[54:55], v[4:5]
	v_pk_fma_f32 v[50:51], v[98:99], v[124:125], v[118:119] neg_lo:[0,0,1] neg_hi:[0,0,1]
	v_pk_fma_f32 v[32:33], v[98:99], v[120:121], v[118:119] neg_lo:[0,0,1] neg_hi:[0,0,1]
	v_pk_fma_f32 v[4:5], v[50:51], v[50:51], v[4:5]
	v_pk_fma_f32 v[28:29], v[98:99], v[116:117], v[118:119] neg_lo:[0,0,1] neg_hi:[0,0,1]
	v_pk_fma_f32 v[4:5], v[32:33], v[32:33], v[4:5]
	v_pk_fma_f32 v[24:25], v[98:99], v[112:113], v[118:119] neg_lo:[0,0,1] neg_hi:[0,0,1]
	v_pk_fma_f32 v[4:5], v[28:29], v[28:29], v[4:5]
	v_pk_fma_f32 v[20:21], v[98:99], v[48:49], v[118:119] neg_lo:[0,0,1] neg_hi:[0,0,1]
	v_pk_fma_f32 v[4:5], v[24:25], v[24:25], v[4:5]
	v_pk_fma_f32 v[12:13], v[114:115], v[40:41], v[118:119] op_sel:[0,0,1] op_sel_hi:[0,1,1] neg_lo:[0,0,1] neg_hi:[0,0,1]
	v_pk_mul_f32 v[122:123], v[42:43], v[42:43]
	v_pk_fma_f32 v[4:5], v[20:21], v[20:21], v[4:5]
	v_pk_fma_f32 v[16:17], v[98:99], v[44:45], v[118:119] neg_lo:[0,0,1] neg_hi:[0,0,1]
	v_pk_mul_f32 v[40:41], v[12:13], v[12:13]
	v_pk_fma_f32 v[38:39], v[98:99], v[38:39], v[118:119] op_sel_hi:[0,1,0] neg_lo:[0,0,1] neg_hi:[0,0,1]
	v_pk_fma_f32 v[44:45], v[16:17], v[16:17], v[4:5]
	v_pk_fma_f32 v[8:9], v[114:115], v[52:53], v[118:119] op_sel:[0,0,1] op_sel_hi:[0,1,1] neg_lo:[0,0,1] neg_hi:[0,0,1]
	v_pk_fma_f32 v[4:5], v[114:115], v[56:57], v[118:119] op_sel:[0,0,1] op_sel_hi:[0,1,1] neg_lo:[0,0,1] neg_hi:[0,0,1]
	v_mov_b32_e32 v57, v122
	v_mov_b32_e32 v122, v41
	v_pk_mul_f32 v[126:127], v[38:39], v[38:39]
	v_pk_mul_f32 v[48:49], v[8:9], v[8:9]
	v_mov_b32_e32 v56, v40
	v_pk_add_f32 v[40:41], v[122:123], v[44:45] op_sel:[0,1] op_sel_hi:[1,0]
	v_mov_b32_e32 v44, v49
	v_pk_add_f32 v[40:41], v[56:57], v[40:41]
	v_mov_b32_e32 v45, v127
	v_pk_mul_f32 v[130:131], v[36:37], v[36:37]
	v_pk_mul_f32 v[52:53], v[4:5], v[4:5]
	v_pk_add_f32 v[40:41], v[44:45], v[40:41]
	v_mov_b32_e32 v49, v126
	v_pk_add_f32 v[40:41], v[48:49], v[40:41]
	v_mov_b32_e32 v44, v53
	v_mov_b32_e32 v45, v131
	v_pk_add_f32 v[40:41], v[44:45], v[40:41]
	v_mov_b32_e32 v53, v130
	v_pk_add_f32 v[40:41], v[52:53], v[40:41]
	ds_bpermute_b32 v45, v208, v41
	ds_bpermute_b32 v44, v208, v40
	s_waitcnt lgkmcnt(0)
	v_pk_add_f32 v[40:41], v[40:41], v[44:45]
	ds_bpermute_b32 v45, v209, v41
	ds_bpermute_b32 v44, v209, v40
	s_waitcnt lgkmcnt(0)
	v_pk_add_f32 v[40:41], v[40:41], v[44:45]
	ds_bpermute_b32 v45, v210, v41
	ds_bpermute_b32 v44, v210, v40
	s_waitcnt lgkmcnt(0)
	v_pk_add_f32 v[40:41], v[40:41], v[44:45]
	ds_bpermute_b32 v45, v211, v41
	ds_bpermute_b32 v44, v211, v40
	s_waitcnt lgkmcnt(0)
; #define LAS __attribute__((address_space(3)))
; __device__ __forceinline__ float shx(float v, int lane, int mask) { return __int_as_float(__builtin_amdgcn_ds_bpermute((lane ^ mask) << 2, __float_as_int(v))); }
; __device__ __forceinline__ bf16_t f2bf(float f) { return (bf16_t)(cvt_pk_bf16(f, 0.f) & 0xffffu); }
; #define LBAR() do { asm volatile("s_waitcnt lgkmcnt(0)" ::: "memory"); __builtin_amdgcn_s_barrier(); asm volatile("" ::: "memory"); } while (0)
; __device__ __forceinline__ void retc_stream(const int wv, LAS unsigned char* lds, unsigned ldsb, const float* __restrict__ gn_g, const float* __restrict__ gn_b, const bf16_t* __restrict__ qkvr, const bf16_t* __restrict__ grb, const bf16_t* __restrict__ kv, ...
;     ...
;             var += shx(var, lane, 1); var += shx(var, lane, 2); var += shx(var, lane, 4); var += shx(var, lane, 8);
;             mu4[e] = mu; rs4[e] = rsqrtf(var * (1.0f / 512.0f) + EPS);
;         }
;         LBAR();
;         {
;             unsigned wb = (unsigned)(16 * w + 4 * g) * 1024u + (unsigned)li * 2u; asm volatile("" : "+v"(wb));
; #pragma unroll
;             for (int c = 0; c < 32; ++c) {
;                 const unsigned co = (unsigned)(((2 * c) ^ (2 * g)) * 16);
; #pragma unroll
;                 for (int e = 0; e < 4; ++e)
;                     *(LAS bf16_t*)(lds + wb + e * 1024 + co) = f2bf((acc[c][e] - mu4[e]) * rs4[e]);
	v_pk_add_f32 v[40:41], v[40:41], v[44:45]
	s_nop 0
	v_pk_fma_f32 v[40:41], v[40:41], s[40:41], v[46:47] op_sel_hi:[1,0,0]
	v_mul_f32_e32 v45, v156, v110
	v_mul_f32_e32 v1, 0x4b800000, v41
	v_cmp_gt_f32_e64 s[0:1], s36, v41
	v_cmp_gt_f32_e32 vcc, s36, v40
	v_mul_f32_e32 v46, v154, v110
	v_cndmask_b32_e64 v1, v41, v1, s[0:1]
	v_rsq_f32_e32 v1, v1
	v_mul_f32_e32 v47, v152, v110
	v_mul_f32_e32 v41, 0x45800000, v1
	v_cndmask_b32_e64 v1, v1, v41, s[0:1]
	v_mul_f32_e32 v41, 0x4b800000, v40
	v_cndmask_b32_e32 v40, v40, v41, vcc
	v_rsq_f32_e32 v40, v40
	s_add_u32 s0, s18, s12
	s_addc_u32 s1, s19, s13
	v_mul_f32_e32 v41, 0x45800000, v40
	v_cndmask_b32_e32 v40, v40, v41, vcc
	v_mov_b32_e32 v41, v212
	v_cvt_pk_bf16_f32 v45, v45, v0
	s_nop 0
	v_add_u32_e32 v41, 0, v41
	v_add_u32_e32 v44, v41, v217
	ds_write_b16 v44, v45
	v_mul_f32_e32 v45, v157, v111
	v_cvt_pk_bf16_f32 v45, v45, v0
	ds_write_b16 v44, v45 offset:1024
	v_mul_f32_e32 v45, v158, v1
	v_cvt_pk_bf16_f32 v45, v45, v0
	ds_write_b16 v44, v45 offset:2048
	v_mul_f32_e32 v45, v159, v40
	v_cvt_pk_bf16_f32 v45, v45, v0
	ds_write_b16 v44, v45 offset:3072
	v_add_u32_e32 v45, v41, v218
	v_cvt_pk_bf16_f32 v46, v46, v0
	ds_write_b16 v45, v46
	v_mul_f32_e32 v46, v155, v111
	v_cvt_pk_bf16_f32 v46, v46, v0
	ds_write_b16 v45, v46 offset:1024
	v_mul_f32_e32 v46, v160, v1
	v_cvt_pk_bf16_f32 v46, v46, v0
	ds_write_b16 v45, v46 offset:2048
	v_mul_f32_e32 v46, v161, v40
	v_cvt_pk_bf16_f32 v46, v46, v0
	ds_write_b16 v45, v46 offset:3072
	v_add_u32_e32 v46, v41, v219
	v_cvt_pk_bf16_f32 v47, v47, v0
	ds_write_b16 v46, v47
	v_mul_f32_e32 v47, v153, v111
	v_cvt_pk_bf16_f32 v47, v47, v0
	ds_write_b16 v46, v47 offset:1024
	v_mul_f32_e32 v47, v162, v1
	v_cvt_pk_bf16_f32 v47, v47, v0
	ds_write_b16 v46, v47 offset:2048
	v_mul_f32_e32 v47, v163, v40
	v_cvt_pk_bf16_f32 v47, v47, v0
	ds_write_b16 v46, v47 offset:3072
	v_mul_f32_e32 v47, v150, v110
	v_add_u32_e32 v41, v41, v220
	v_cvt_pk_bf16_f32 v47, v47, v0
	ds_write_b16 v41, v47
	v_mul_f32_e32 v47, v151, v111
	v_cvt_pk_bf16_f32 v47, v47, v0
	ds_write_b16 v41, v47 offset:1024
	v_mul_f32_e32 v47, v164, v1
	v_cvt_pk_bf16_f32 v47, v47, v0
	ds_write_b16 v41, v47 offset:2048
	v_mul_f32_e32 v47, v165, v40
	v_cvt_pk_bf16_f32 v47, v47, v0
	ds_write_b16 v41, v47 offset:3072
	v_mul_f32_e32 v47, v148, v110
	v_cvt_pk_bf16_f32 v47, v47, v0
	ds_write_b16 v44, v47 offset:128
	v_mul_f32_e32 v47, v149, v111
	v_cvt_pk_bf16_f32 v47, v47, v0
	ds_write_b16 v44, v47 offset:1152
	v_mul_f32_e32 v47, v166, v1
	v_cvt_pk_bf16_f32 v47, v47, v0
	ds_write_b16 v44, v47 offset:2176
	v_mul_f32_e32 v47, v167, v40
	v_cvt_pk_bf16_f32 v47, v47, v0
	ds_write_b16 v44, v47 offset:3200
	v_mul_f32_e32 v47, v146, v110
	v_cvt_pk_bf16_f32 v47, v47, v0
	ds_write_b16 v45, v47 offset:128
	v_mul_f32_e32 v47, v147, v111
	v_cvt_pk_bf16_f32 v47, v47, v0
	ds_write_b16 v45, v47 offset:1152
	v_mul_f32_e32 v47, v168, v1
	v_cvt_pk_bf16_f32 v47, v47, v0
	ds_write_b16 v45, v47 offset:2176
	v_mul_f32_e32 v47, v169, v40
	v_cvt_pk_bf16_f32 v47, v47, v0
	ds_write_b16 v45, v47 offset:3200
	v_mul_f32_e32 v47, v144, v110
	v_cvt_pk_bf16_f32 v47, v47, v0
	ds_write_b16 v46, v47 offset:128
	v_mul_f32_e32 v47, v145, v111
	v_cvt_pk_bf16_f32 v47, v47, v0
	ds_write_b16 v46, v47 offset:1152
	v_mul_f32_e32 v47, v170, v1
	v_cvt_pk_bf16_f32 v47, v47, v0
	ds_write_b16 v46, v47 offset:2176
	v_mul_f32_e32 v47, v171, v40
	v_cvt_pk_bf16_f32 v47, v47, v0
	ds_write_b16 v46, v47 offset:3200
	v_mul_f32_e32 v47, v142, v110
	v_cvt_pk_bf16_f32 v47, v47, v0
	ds_write_b16 v41, v47 offset:128
	v_mul_f32_e32 v47, v143, v111
	v_cvt_pk_bf16_f32 v47, v47, v0
	ds_write_b16 v41, v47 offset:1152
	v_mul_f32_e32 v47, v106, v1
	v_cvt_pk_bf16_f32 v47, v47, v0
	ds_write_b16 v41, v47 offset:2176
	v_mul_f32_e32 v47, v107, v40
	v_cvt_pk_bf16_f32 v47, v47, v0
	ds_write_b16 v41, v47 offset:3200
	v_mul_f32_e32 v47, v140, v110
	v_cvt_pk_bf16_f32 v47, v47, v0
	ds_write_b16 v44, v47 offset:256
	v_mul_f32_e32 v47, v141, v111
	v_cvt_pk_bf16_f32 v47, v47, v0
	ds_write_b16 v44, v47 offset:1280
	v_mul_f32_e32 v47, v102, v1
	v_cvt_pk_bf16_f32 v47, v47, v0
	ds_write_b16 v44, v47 offset:2304
	v_mul_f32_e32 v47, v103, v40
	v_cvt_pk_bf16_f32 v47, v47, v0
	ds_write_b16 v44, v47 offset:3328
	v_mul_f32_e32 v47, v138, v110
	v_cvt_pk_bf16_f32 v47, v47, v0
	ds_write_b16 v45, v47 offset:256
	v_mul_f32_e32 v47, v139, v111
	v_cvt_pk_bf16_f32 v47, v47, v0
	ds_write_b16 v45, v47 offset:1280
	v_mul_f32_e32 v47, v96, v1
	v_cvt_pk_bf16_f32 v47, v47, v0
	ds_write_b16 v45, v47 offset:2304
	v_mul_f32_e32 v47, v97, v40
	v_cvt_pk_bf16_f32 v47, v47, v0
	ds_write_b16 v45, v47 offset:3328
	v_mul_f32_e32 v47, v136, v110
	v_cvt_pk_bf16_f32 v47, v47, v0
	ds_write_b16 v46, v47 offset:256
	v_mul_f32_e32 v47, v137, v111
	v_cvt_pk_bf16_f32 v47, v47, v0
	ds_write_b16 v46, v47 offset:1280
	v_mul_f32_e32 v47, v92, v1
	v_cvt_pk_bf16_f32 v47, v47, v0
	ds_write_b16 v46, v47 offset:2304
	v_mul_f32_e32 v47, v93, v40
	v_cvt_pk_bf16_f32 v47, v47, v0
	ds_write_b16 v46, v47 offset:3328
	v_mul_f32_e32 v47, v134, v110
	v_cvt_pk_bf16_f32 v47, v47, v0
	ds_write_b16 v41, v47 offset:256
	v_mul_f32_e32 v47, v135, v111
	v_cvt_pk_bf16_f32 v47, v47, v0
	ds_write_b16 v41, v47 offset:1280
	v_mul_f32_e32 v47, v88, v1
	v_cvt_pk_bf16_f32 v47, v47, v0
	ds_write_b16 v41, v47 offset:2304
	v_mul_f32_e32 v47, v89, v40
	v_cvt_pk_bf16_f32 v47, v47, v0
	ds_write_b16 v41, v47 offset:3328
	v_mul_f32_e32 v47, v132, v110
	v_cvt_pk_bf16_f32 v47, v47, v0
	ds_write_b16 v44, v47 offset:384
	v_mul_f32_e32 v47, v133, v111
	v_cvt_pk_bf16_f32 v47, v47, v0
	ds_write_b16 v44, v47 offset:1408
	v_mul_f32_e32 v47, v84, v1
	v_cvt_pk_bf16_f32 v47, v47, v0
; #define LAS __attribute__((address_space(3)))
; __device__ __forceinline__ bf16_t f2bf(float f) { return (bf16_t)(cvt_pk_bf16(f, 0.f) & 0xffffu); }
; __device__ __forceinline__ void retc_stream(const int wv, LAS unsigned char* lds, unsigned ldsb, const float* __restrict__ gn_g, const float* __restrict__ gn_b, const bf16_t* __restrict__ qkvr, const bf16_t* __restrict__ grb, const bf16_t* __restrict__ kv, ...
;     ...
;             for (int c = 0; c < 32; ++c) {
;                 const unsigned co = (unsigned)(((2 * c) ^ (2 * g)) * 16);
; #pragma unroll
;                 for (int e = 0; e < 4; ++e)
;                     *(LAS bf16_t*)(lds + wb + e * 1024 + co) = f2bf((acc[c][e] - mu4[e]) * rs4[e]);
	ds_write_b16 v44, v47 offset:2432
	v_mul_f32_e32 v47, v85, v40
	v_cvt_pk_bf16_f32 v47, v47, v0
	ds_write_b16 v44, v47 offset:3456
	v_mul_f32_e32 v47, v94, v110
	v_cvt_pk_bf16_f32 v47, v47, v0
	ds_write_b16 v45, v47 offset:384
	v_mul_f32_e32 v47, v95, v111
	v_cvt_pk_bf16_f32 v47, v47, v0
	ds_write_b16 v45, v47 offset:1408
	v_mul_f32_e32 v47, v80, v1
	v_cvt_pk_bf16_f32 v47, v47, v0
	ds_write_b16 v45, v47 offset:2432
	v_mul_f32_e32 v47, v81, v40
	v_cvt_pk_bf16_f32 v47, v47, v0
	ds_write_b16 v45, v47 offset:3456
	v_mul_f32_e32 v47, v90, v110
	v_cvt_pk_bf16_f32 v47, v47, v0
	ds_write_b16 v46, v47 offset:384
	v_mul_f32_e32 v47, v91, v111
	v_cvt_pk_bf16_f32 v47, v47, v0
	ds_write_b16 v46, v47 offset:1408
	v_mul_f32_e32 v47, v76, v1
	v_cvt_pk_bf16_f32 v47, v47, v0
	ds_write_b16 v46, v47 offset:2432
	v_mul_f32_e32 v47, v77, v40
	v_cvt_pk_bf16_f32 v47, v47, v0
	ds_write_b16 v46, v47 offset:3456
	v_mul_f32_e32 v47, v86, v110
	v_cvt_pk_bf16_f32 v47, v47, v0
	ds_write_b16 v41, v47 offset:384
	v_mul_f32_e32 v47, v87, v111
	v_cvt_pk_bf16_f32 v47, v47, v0
	ds_write_b16 v41, v47 offset:1408
	v_mul_f32_e32 v47, v72, v1
	v_cvt_pk_bf16_f32 v47, v47, v0
	ds_write_b16 v41, v47 offset:2432
	v_mul_f32_e32 v47, v73, v40
	v_cvt_pk_bf16_f32 v47, v47, v0
	ds_write_b16 v41, v47 offset:3456
	v_mul_f32_e32 v47, v82, v110
	v_cvt_pk_bf16_f32 v47, v47, v0
	ds_write_b16 v44, v47 offset:512
	v_mul_f32_e32 v47, v83, v111
	v_cvt_pk_bf16_f32 v47, v47, v0
	ds_write_b16 v44, v47 offset:1536
	v_mul_f32_e32 v47, v68, v1
	v_cvt_pk_bf16_f32 v47, v47, v0
	ds_write_b16 v44, v47 offset:2560
	v_mul_f32_e32 v47, v69, v40
	v_cvt_pk_bf16_f32 v47, v47, v0
	ds_write_b16 v44, v47 offset:3584
	v_mul_f32_e32 v47, v78, v110
	v_cvt_pk_bf16_f32 v47, v47, v0
	ds_write_b16 v45, v47 offset:512
	v_mul_f32_e32 v47, v79, v111
	v_cvt_pk_bf16_f32 v47, v47, v0
	ds_write_b16 v45, v47 offset:1536
	v_mul_f32_e32 v47, v64, v1
	v_cvt_pk_bf16_f32 v47, v47, v0
	ds_write_b16 v45, v47 offset:2560
	v_mul_f32_e32 v47, v65, v40
	v_cvt_pk_bf16_f32 v47, v47, v0
	ds_write_b16 v45, v47 offset:3584
	v_mul_f32_e32 v47, v74, v110
	v_cvt_pk_bf16_f32 v47, v47, v0
	ds_write_b16 v46, v47 offset:512
	v_mul_f32_e32 v47, v75, v111
	v_cvt_pk_bf16_f32 v47, v47, v0
	ds_write_b16 v46, v47 offset:1536
	v_mul_f32_e32 v47, v60, v1
	v_cvt_pk_bf16_f32 v47, v47, v0
	ds_write_b16 v46, v47 offset:2560
	v_mul_f32_e32 v47, v61, v40
	v_cvt_pk_bf16_f32 v47, v47, v0
	ds_write_b16 v46, v47 offset:3584
	v_mul_f32_e32 v47, v70, v110
	v_cvt_pk_bf16_f32 v47, v47, v0
	ds_write_b16 v41, v47 offset:512
	v_mul_f32_e32 v47, v71, v111
	v_cvt_pk_bf16_f32 v47, v47, v0
	ds_write_b16 v41, v47 offset:1536
	v_mul_f32_e32 v47, v54, v1
	v_cvt_pk_bf16_f32 v47, v47, v0
	ds_write_b16 v41, v47 offset:2560
	v_mul_f32_e32 v47, v55, v40
	v_cvt_pk_bf16_f32 v47, v47, v0
	ds_write_b16 v41, v47 offset:3584
	v_mul_f32_e32 v47, v66, v110
	v_cvt_pk_bf16_f32 v47, v47, v0
	ds_write_b16 v44, v47 offset:640
	v_mul_f32_e32 v47, v67, v111
	v_cvt_pk_bf16_f32 v47, v47, v0
	ds_write_b16 v44, v47 offset:1664
	v_mul_f32_e32 v47, v50, v1
	v_cvt_pk_bf16_f32 v47, v47, v0
	ds_write_b16 v44, v47 offset:2688
	v_mul_f32_e32 v47, v51, v40
	v_cvt_pk_bf16_f32 v47, v47, v0
	ds_write_b16 v44, v47 offset:3712
	v_cvt_pk_bf16_f32 v30, v30, v0
	ds_write_b16 v45, v30 offset:640
	v_mul_f32_e32 v30, v31, v111
	v_cvt_pk_bf16_f32 v30, v30, v0
	ds_write_b16 v45, v30 offset:1664
	v_mul_f32_e32 v30, v32, v1
	v_cvt_pk_bf16_f32 v30, v30, v0
	ds_write_b16 v45, v30 offset:2688
	v_mul_f32_e32 v30, v33, v40
	v_cvt_pk_bf16_f32 v30, v30, v0
	ds_write_b16 v45, v30 offset:3712
	v_cvt_pk_bf16_f32 v26, v26, v0
	ds_write_b16 v46, v26 offset:640
	v_mul_f32_e32 v26, v27, v111
	v_cvt_pk_bf16_f32 v26, v26, v0
	ds_write_b16 v46, v26 offset:1664
	v_mul_f32_e32 v26, v28, v1
	v_cvt_pk_bf16_f32 v26, v26, v0
	ds_write_b16 v46, v26 offset:2688
	v_mul_f32_e32 v26, v29, v40
	v_cvt_pk_bf16_f32 v26, v26, v0
	ds_write_b16 v46, v26 offset:3712
	v_cvt_pk_bf16_f32 v22, v22, v0
	ds_write_b16 v41, v22 offset:640
	v_mul_f32_e32 v22, v23, v111
	v_cvt_pk_bf16_f32 v22, v22, v0
	ds_write_b16 v41, v22 offset:1664
	v_mul_f32_e32 v22, v24, v1
	v_cvt_pk_bf16_f32 v22, v22, v0
	ds_write_b16 v41, v22 offset:2688
	v_mul_f32_e32 v22, v25, v40
	v_cvt_pk_bf16_f32 v22, v22, v0
	ds_write_b16 v41, v22 offset:3712
	v_cvt_pk_bf16_f32 v18, v18, v0
	ds_write_b16 v44, v18 offset:768
	v_mul_f32_e32 v18, v19, v111
	v_cvt_pk_bf16_f32 v18, v18, v0
	ds_write_b16 v44, v18 offset:1792
	v_mul_f32_e32 v18, v20, v1
	v_cvt_pk_bf16_f32 v18, v18, v0
	ds_write_b16 v44, v18 offset:2816
	v_mul_f32_e32 v18, v21, v40
	v_cvt_pk_bf16_f32 v18, v18, v0
	ds_write_b16 v44, v18 offset:3840
	v_cvt_pk_bf16_f32 v14, v14, v0
	ds_write_b16 v45, v14 offset:768
	v_mul_f32_e32 v14, v15, v111
	v_cvt_pk_bf16_f32 v14, v14, v0
	ds_write_b16 v45, v14 offset:1792
	v_mul_f32_e32 v14, v16, v1
	v_cvt_pk_bf16_f32 v14, v14, v0
	ds_write_b16 v45, v14 offset:2816
	v_mul_f32_e32 v14, v17, v40
	v_cvt_pk_bf16_f32 v14, v14, v0
	ds_write_b16 v45, v14 offset:3840
	v_mul_f32_e32 v14, v63, v110
	v_cvt_pk_bf16_f32 v14, v14, v0
	ds_write_b16 v46, v14 offset:768
	v_cvt_pk_bf16_f32 v11, v11, v0
	ds_write_b16 v46, v11 offset:1792
	v_mul_f32_e32 v11, v43, v1
	v_cvt_pk_bf16_f32 v11, v11, v0
	ds_write_b16 v46, v11 offset:2816
	v_mul_f32_e32 v11, v13, v40
	v_cvt_pk_bf16_f32 v11, v11, v0
	ds_write_b16 v46, v11 offset:3840
	v_mul_f32_e32 v11, v62, v110
	v_cvt_pk_bf16_f32 v11, v11, v0
	ds_write_b16 v41, v11 offset:768
	v_cvt_pk_bf16_f32 v10, v10, v0
	ds_write_b16 v41, v10 offset:1792
	v_mul_f32_e32 v10, v42, v1
	v_cvt_pk_bf16_f32 v10, v10, v0
	ds_write_b16 v41, v10 offset:2816
	v_mul_f32_e32 v10, v12, v40
	v_cvt_pk_bf16_f32 v10, v10, v0
; #define LAS __attribute__((address_space(3)))
; __device__ __forceinline__ bf16_t f2bf(float f) { return (bf16_t)(cvt_pk_bf16(f, 0.f) & 0xffffu); }
; #define LBAR() do { asm volatile("s_waitcnt lgkmcnt(0)" ::: "memory"); __builtin_amdgcn_s_barrier(); asm volatile("" ::: "memory"); } while (0)
; __device__ __forceinline__ void retc_stream(const int wv, LAS unsigned char* lds, unsigned ldsb, const float* __restrict__ gn_g, const float* __restrict__ gn_b, const bf16_t* __restrict__ qkvr, const bf16_t* __restrict__ grb, const bf16_t* __restrict__ kv, ...
;     ...
;                     *(LAS bf16_t*)(lds + wb + e * 1024 + co) = f2bf((acc[c][e] - mu4[e]) * rs4[e]);
;             }
;         }
;         {
;             int tq = t; asm volatile("" : "+v"(tq));
;             const int ch = tq & 63, r0 = tq >> 6;
;             const f32x4 g0 = *(const f32x4*)(gng + ch * 8), g1 = *(const f32x4*)(gng + ch * 8 + 4), b0 = *(const f32x4*)(gnb + ch * 8), b1 = *(const f32x4*)(gnb + ch * 8 + 4);
;             u32x4 gv[16];
; #pragma unroll
;             for (int k = 0; k < 16; ++k) gv[k] = *(const u32x4*)(grb + (size_t)(n * 128 + r0 + 8 * k) * 2048 + h * 512 + ch * 8);
;             LBAR();
	ds_write_b16 v41, v10 offset:3840
	v_mul_f32_e32 v10, v59, v110
	v_cvt_pk_bf16_f32 v10, v10, v0
	ds_write_b16 v44, v10 offset:896
	v_cvt_pk_bf16_f32 v7, v7, v0
	ds_write_b16 v44, v7 offset:1920
	v_mul_f32_e32 v7, v39, v1
	v_cvt_pk_bf16_f32 v7, v7, v0
	ds_write_b16 v44, v7 offset:2944
	v_mul_f32_e32 v7, v9, v40
	v_cvt_pk_bf16_f32 v7, v7, v0
	ds_write_b16 v44, v7 offset:3968
	v_mul_f32_e32 v7, v58, v110
	v_cvt_pk_bf16_f32 v7, v7, v0
	ds_write_b16 v45, v7 offset:896
	v_cvt_pk_bf16_f32 v6, v6, v0
	ds_write_b16 v45, v6 offset:1920
	v_mul_f32_e32 v6, v38, v1
	v_cvt_pk_bf16_f32 v6, v6, v0
	ds_write_b16 v45, v6 offset:2944
	v_mul_f32_e32 v6, v8, v40
	v_cvt_pk_bf16_f32 v6, v6, v0
	ds_write_b16 v45, v6 offset:3968
	v_mul_f32_e32 v6, v35, v110
	v_cvt_pk_bf16_f32 v6, v6, v0
	ds_write_b16 v46, v6 offset:896
	v_cvt_pk_bf16_f32 v3, v3, v0
	ds_write_b16 v46, v3 offset:1920
	v_mul_f32_e32 v3, v37, v1
	v_cvt_pk_bf16_f32 v3, v3, v0
	ds_write_b16 v46, v3 offset:2944
	v_mul_f32_e32 v3, v5, v40
	v_cvt_pk_bf16_f32 v3, v3, v0
	ds_write_b16 v46, v3 offset:3968
	v_mul_f32_e32 v3, v34, v110
	v_mul_f32_e32 v1, v36, v1
	v_cvt_pk_bf16_f32 v3, v3, v0
	ds_write_b16 v41, v3 offset:896
	v_cvt_pk_bf16_f32 v2, v2, v0
	ds_write_b16 v41, v2 offset:1920
	v_cvt_pk_bf16_f32 v1, v1, v0
	ds_write_b16 v41, v1 offset:2944
	v_mul_f32_e32 v1, v4, v40
	v_cvt_pk_bf16_f32 v1, v1, v0
	v_mov_b32_e32 v2, v191
	ds_write_b16 v41, v1 offset:3968
	v_mov_b32_e32 v79, v0
	v_and_b32_e32 v1, 63, v2
	v_lshlrev_b32_e32 v14, 5, v1
	v_ashrrev_i32_e32 v80, 6, v2
	global_load_dwordx4 v[2:5], v14, s[10:11] offset:16 nt
	global_load_dwordx4 v[10:13], v14, s[10:11] nt
	global_load_dwordx4 v[6:9], v14, s[0:1] offset:16 nt
	s_nop 0
	global_load_dwordx4 v[14:17], v14, s[0:1] nt
	s_lshl_b64 s[0:1], s[2:3], 1
	v_readlane_b32 s2, v254, 31
	v_add_u32_e32 v18, s29, v80
	s_add_u32 s2, s2, s0
	v_readlane_b32 s3, v254, 33
	s_addc_u32 s3, s3, s1
	v_lshlrev_b32_e32 v78, 4, v1
	v_ashrrev_i32_e32 v19, 31, v18
	v_lshl_add_u64 v[20:21], s[2:3], 0, v[78:79]
	v_lshlrev_b64 v[90:91], 12, v[18:19]
	v_lshl_add_u64 v[18:19], v[20:21], 0, v[90:91]
	global_load_dwordx4 v[82:85], v[18:19], off nt
	s_mov_b32 s2, 0x8000
	v_add_co_u32_e32 v20, vcc, s2, v18
	s_mov_b32 s2, 0x10000
	s_nop 0
	v_addc_co_u32_e32 v21, vcc, 0, v19, vcc
	global_load_dwordx4 v[74:77], v[20:21], off nt
	v_add_co_u32_e32 v20, vcc, s2, v18
	s_mov_b32 s2, 0x18000
	s_nop 0
	v_addc_co_u32_e32 v21, vcc, 0, v19, vcc
	global_load_dwordx4 v[70:73], v[20:21], off nt
	v_add_co_u32_e32 v20, vcc, s2, v18
	s_mov_b32 s2, 0x20000
	s_nop 0
	v_addc_co_u32_e32 v21, vcc, 0, v19, vcc
	global_load_dwordx4 v[66:69], v[20:21], off nt
	v_add_co_u32_e32 v20, vcc, s2, v18
	s_mov_b32 s2, 0x28000
	s_nop 0
	v_addc_co_u32_e32 v21, vcc, 0, v19, vcc
	global_load_dwordx4 v[62:65], v[20:21], off nt
	v_add_co_u32_e32 v20, vcc, s2, v18
	s_mov_b32 s2, 0x30000
	s_nop 0
	v_addc_co_u32_e32 v21, vcc, 0, v19, vcc
	global_load_dwordx4 v[58:61], v[20:21], off nt
	v_add_co_u32_e32 v20, vcc, s2, v18
	s_mov_b32 s2, 0x38000
	s_nop 0
	v_addc_co_u32_e32 v21, vcc, 0, v19, vcc
	global_load_dwordx4 v[54:57], v[20:21], off nt
	v_add_co_u32_e32 v20, vcc, s2, v18
	s_mov_b32 s2, 0x40000
	s_nop 0
	v_addc_co_u32_e32 v21, vcc, 0, v19, vcc
	global_load_dwordx4 v[50:53], v[20:21], off nt
	v_add_co_u32_e32 v20, vcc, s2, v18
	s_mov_b32 s2, 0x48000
	s_nop 0
	v_addc_co_u32_e32 v21, vcc, 0, v19, vcc
	global_load_dwordx4 v[46:49], v[20:21], off nt
	v_add_co_u32_e32 v20, vcc, s2, v18
	s_mov_b32 s2, 0x50000
	s_nop 0
	v_addc_co_u32_e32 v21, vcc, 0, v19, vcc
	global_load_dwordx4 v[42:45], v[20:21], off nt
	v_add_co_u32_e32 v20, vcc, s2, v18
	s_mov_b32 s2, 0x58000
	s_nop 0
	v_addc_co_u32_e32 v21, vcc, 0, v19, vcc
	global_load_dwordx4 v[38:41], v[20:21], off nt
	v_add_co_u32_e32 v20, vcc, s2, v18
	s_mov_b32 s2, 0x60000
	s_nop 0
	v_addc_co_u32_e32 v21, vcc, 0, v19, vcc
	global_load_dwordx4 v[34:37], v[20:21], off nt
	v_add_co_u32_e32 v20, vcc, s2, v18
	s_mov_b32 s2, 0x68000
	s_nop 0
	v_addc_co_u32_e32 v21, vcc, 0, v19, vcc
	global_load_dwordx4 v[30:33], v[20:21], off nt
	v_add_co_u32_e32 v20, vcc, s2, v18
	s_mov_b32 s2, 0x70000
	s_nop 0
	v_addc_co_u32_e32 v21, vcc, 0, v19, vcc
	global_load_dwordx4 v[26:29], v[20:21], off nt
	v_add_co_u32_e32 v20, vcc, s2, v18
	s_mov_b32 s2, 0x78000
	s_nop 0
	v_addc_co_u32_e32 v21, vcc, 0, v19, vcc
	v_lshrrev_b32_e32 v81, 1, v80
	v_add_co_u32_e32 v18, vcc, s2, v18
	v_bitop3_b32 v81, v81, v1, 6 bitop3:0x6c
	s_nop 0
	v_addc_co_u32_e32 v19, vcc, 0, v19, vcc
	v_lshlrev_b32_e32 v86, 10, v80
	v_lshlrev_b32_e32 v81, 4, v81
	global_load_dwordx4 v[22:25], v[20:21], off nt
	v_add3_u32 v86, 0, v86, v81
	global_load_dwordx4 v[18:21], v[18:19], off nt
	s_waitcnt lgkmcnt(0)
	s_barrier
; #define LAS __attribute__((address_space(3)))
; __device__ __forceinline__ unsigned cvt_pk_bf16(float lo, float hi) { unsigned r; asm volatile("v_cvt_pk_bf16_f32 %0, %1, %2" : "=v"(r) : "v"(lo), "v"(hi)); return r; }
; __device__ __forceinline__ float bflo(unsigned u) { return __uint_as_float(u << 16); }
; __device__ __forceinline__ float bfhi(unsigned u) { return __uint_as_float(u & 0xffff0000u); }
; __device__ __forceinline__ void retc_stream(const int wv, LAS unsigned char* lds, unsigned ldsb, const float* __restrict__ gn_g, const float* __restrict__ gn_b, const bf16_t* __restrict__ qkvr, const bf16_t* __restrict__ grb, const bf16_t* __restrict__ kv, ...
;     ...
; #pragma unroll
;             for (int k = 0; k < 16; ++k) {
;                 const int row = r0 + 8 * k;
;                 const u32x4 yv = *(const LAS u32x4*)(lds + row * 1024 + ((ch ^ (2 * ((row >> 2) & 3))) << 4));
;                 const u32x4 q = gv[k];
;                 u32x4 o;
;                 o.x = cvt_pk_bf16((bflo(yv.x) * g0[0] + b0[0]) * bflo(q.x), (bfhi(yv.x) * g0[1] + b0[1]) * bfhi(q.x));
;                 o.y = cvt_pk_bf16((bflo(yv.y) * g0[2] + b0[2]) * bflo(q.y), (bfhi(yv.y) * g0[3] + b0[3]) * bfhi(q.y));
;                 o.z = cvt_pk_bf16((bflo(yv.z) * g1[0] + b1[0]) * bflo(q.z), (bfhi(yv.z) * g1[1] + b1[1]) * bfhi(q.z));
;                 o.w = cvt_pk_bf16((bflo(yv.w) * g1[2] + b1[2]) * bflo(q.w), (bfhi(yv.w) * g1[3] + b1[3]) * bfhi(q.w));
;                 *(u32x4*)(orb + (size_t)(n * 128 + row) * 2048 + h * 512 + ch * 8) = o;
;             }
	ds_read_b128 v[86:89], v86
	s_waitcnt vmcnt(0)
	v_lshlrev_b32_e32 v93, 16, v82
	v_and_b32_e32 v82, 0xffff0000, v82
	v_readlane_b32 s2, v254, 35
	s_add_u32 s0, s2, s0
	s_waitcnt lgkmcnt(0)
	v_lshlrev_b32_e32 v92, 16, v86
	v_and_b32_e32 v86, 0xffff0000, v86
	v_fma_f32 v92, v10, v92, v14
	v_fma_f32 v86, v11, v86, v15
	v_mul_f32_e32 v92, v92, v93
	v_mul_f32_e32 v82, v86, v82
	v_lshlrev_b32_e32 v86, 16, v87
	v_and_b32_e32 v87, 0xffff0000, v87
	v_cvt_pk_bf16_f32 v82, v92, v82
	v_fma_f32 v86, v12, v86, v16
	v_lshlrev_b32_e32 v92, 16, v83
	v_fma_f32 v87, v13, v87, v17
	v_and_b32_e32 v83, 0xffff0000, v83
	v_mul_f32_e32 v86, v86, v92
	v_mul_f32_e32 v83, v87, v83
	v_cvt_pk_bf16_f32 v83, v86, v83
	v_lshlrev_b32_e32 v86, 16, v88
	v_fma_f32 v86, v2, v86, v6
	v_lshlrev_b32_e32 v87, 16, v84
	v_mul_f32_e32 v86, v86, v87
	v_and_b32_e32 v87, 0xffff0000, v88
	v_fma_f32 v87, v3, v87, v7
	v_and_b32_e32 v84, 0xffff0000, v84
	v_mul_f32_e32 v84, v87, v84
	v_cvt_pk_bf16_f32 v84, v86, v84
	v_lshlrev_b32_e32 v86, 16, v89
	v_fma_f32 v86, v4, v86, v8
	v_lshlrev_b32_e32 v87, 16, v85
	v_readlane_b32 s2, v254, 37
	v_mul_f32_e32 v86, v86, v87
	v_and_b32_e32 v87, 0xffff0000, v89
	s_addc_u32 s1, s2, s1
	v_fma_f32 v87, v5, v87, v9
	v_and_b32_e32 v85, 0xffff0000, v85
	v_lshl_add_u64 v[78:79], s[0:1], 0, v[78:79]
	v_mul_f32_e32 v85, v87, v85
	v_cvt_pk_bf16_f32 v85, v86, v85
	v_lshl_add_u64 v[86:87], v[78:79], 0, v[90:91]
	global_store_dwordx4 v[86:87], v[82:85], off nt
	v_add_u32_e32 v86, 8, v80
	v_lshlrev_b32_e32 v88, 16, v74
	v_lshrrev_b32_e32 v83, 1, v86
	v_bitop3_b32 v83, v83, v1, 6 bitop3:0x6c
	v_lshlrev_b32_e32 v82, 10, v86
	v_lshlrev_b32_e32 v83, 4, v83
	v_add3_u32 v82, 0, v82, v83
	ds_read_b128 v[82:85], v82
	v_and_b32_e32 v74, 0xffff0000, v74
	s_mov_b64 s[0:1], -1
	s_cmpk_gt_i32 s28, 0xff
	s_waitcnt lgkmcnt(0)
	v_lshlrev_b32_e32 v87, 16, v82
	v_and_b32_e32 v82, 0xffff0000, v82
	v_fma_f32 v87, v10, v87, v14
	v_fma_f32 v82, v11, v82, v15
	v_mul_f32_e32 v87, v87, v88
	v_mul_f32_e32 v74, v82, v74
	v_lshlrev_b32_e32 v82, 16, v83
	v_and_b32_e32 v83, 0xffff0000, v83
	v_cvt_pk_bf16_f32 v74, v87, v74
	v_fma_f32 v82, v12, v82, v16
	v_lshlrev_b32_e32 v87, 16, v75
	v_fma_f32 v83, v13, v83, v17
	v_and_b32_e32 v75, 0xffff0000, v75
	v_mul_f32_e32 v82, v82, v87
	v_mul_f32_e32 v75, v83, v75
	v_cvt_pk_bf16_f32 v75, v82, v75
	v_lshlrev_b32_e32 v82, 16, v84
	v_fma_f32 v82, v2, v82, v6
	v_lshlrev_b32_e32 v83, 16, v76
	v_mul_f32_e32 v82, v82, v83
	v_and_b32_e32 v83, 0xffff0000, v84
	v_fma_f32 v83, v3, v83, v7
	v_and_b32_e32 v76, 0xffff0000, v76
	v_mul_f32_e32 v76, v83, v76
	v_cvt_pk_bf16_f32 v76, v82, v76
	v_lshlrev_b32_e32 v82, 16, v85
	v_fma_f32 v82, v4, v82, v8
	v_lshlrev_b32_e32 v83, 16, v77
	v_mul_f32_e32 v82, v82, v83
	v_and_b32_e32 v83, 0xffff0000, v85
	v_fma_f32 v83, v5, v83, v9
	v_and_b32_e32 v77, 0xffff0000, v77
	v_mul_f32_e32 v77, v83, v77
	v_cvt_pk_bf16_f32 v77, v82, v77
	v_add_u32_e32 v82, s29, v86
	v_ashrrev_i32_e32 v83, 31, v82
	v_lshlrev_b64 v[82:83], 12, v[82:83]
	v_lshl_add_u64 v[82:83], v[78:79], 0, v[82:83]
	global_store_dwordx4 v[82:83], v[74:77], off nt
	v_add_u32_e32 v82, 16, v80
	v_lshlrev_b32_e32 v84, 16, v70
	v_lshlrev_b32_e32 v74, 10, v82
	v_add3_u32 v74, 0, v74, v81
	ds_read_b128 v[74:77], v74
	v_and_b32_e32 v70, 0xffff0000, v70
	s_waitcnt lgkmcnt(0)
	v_lshlrev_b32_e32 v83, 16, v74
	v_and_b32_e32 v74, 0xffff0000, v74
	v_fma_f32 v83, v10, v83, v14
	v_fma_f32 v74, v11, v74, v15
	v_mul_f32_e32 v83, v83, v84
	v_mul_f32_e32 v70, v74, v70
	v_lshlrev_b32_e32 v74, 16, v75
	v_and_b32_e32 v75, 0xffff0000, v75
	v_cvt_pk_bf16_f32 v70, v83, v70
	v_fma_f32 v74, v12, v74, v16
	v_lshlrev_b32_e32 v83, 16, v71
	v_fma_f32 v75, v13, v75, v17
	v_and_b32_e32 v71, 0xffff0000, v71
	v_mul_f32_e32 v74, v74, v83
	v_mul_f32_e32 v71, v75, v71
	v_cvt_pk_bf16_f32 v71, v74, v71
	v_lshlrev_b32_e32 v74, 16, v76
	v_fma_f32 v74, v2, v74, v6
	v_lshlrev_b32_e32 v75, 16, v72
	v_mul_f32_e32 v74, v74, v75
	v_and_b32_e32 v75, 0xffff0000, v76
	v_fma_f32 v75, v3, v75, v7
	v_and_b32_e32 v72, 0xffff0000, v72
	v_mul_f32_e32 v72, v75, v72
	v_cvt_pk_bf16_f32 v72, v74, v72
	v_lshlrev_b32_e32 v74, 16, v77
	v_fma_f32 v74, v4, v74, v8
	v_lshlrev_b32_e32 v75, 16, v73
	v_mul_f32_e32 v74, v74, v75
	v_and_b32_e32 v75, 0xffff0000, v77
	v_fma_f32 v75, v5, v75, v9
	v_and_b32_e32 v73, 0xffff0000, v73
	v_mul_f32_e32 v73, v75, v73
	v_cvt_pk_bf16_f32 v73, v74, v73
	v_add_u32_e32 v74, s29, v82
	v_ashrrev_i32_e32 v75, 31, v74
	v_lshlrev_b64 v[74:75], 12, v[74:75]
	v_lshl_add_u64 v[74:75], v[78:79], 0, v[74:75]
	global_store_dwordx4 v[74:75], v[70:73], off nt
	v_add_u32_e32 v74, 24, v80
	v_lshlrev_b32_e32 v76, 16, v66
	v_lshrrev_b32_e32 v71, 1, v74
	v_bitop3_b32 v71, v71, v1, 6 bitop3:0x6c
	v_lshlrev_b32_e32 v70, 10, v74
	v_lshlrev_b32_e32 v71, 4, v71
	v_add3_u32 v70, 0, v70, v71
	ds_read_b128 v[70:73], v70
	v_and_b32_e32 v66, 0xffff0000, v66
	s_waitcnt lgkmcnt(0)
	v_lshlrev_b32_e32 v75, 16, v70
	v_and_b32_e32 v70, 0xffff0000, v70
	v_fma_f32 v75, v10, v75, v14
	v_fma_f32 v70, v11, v70, v15
	v_mul_f32_e32 v75, v75, v76
	v_mul_f32_e32 v66, v70, v66
	v_lshlrev_b32_e32 v70, 16, v71
	v_and_b32_e32 v71, 0xffff0000, v71
	v_cvt_pk_bf16_f32 v66, v75, v66
	v_fma_f32 v70, v12, v70, v16
	v_lshlrev_b32_e32 v75, 16, v67
	v_fma_f32 v71, v13, v71, v17
	v_and_b32_e32 v67, 0xffff0000, v67
	v_mul_f32_e32 v70, v70, v75
	v_mul_f32_e32 v67, v71, v67
	v_cvt_pk_bf16_f32 v67, v70, v67
	v_lshlrev_b32_e32 v70, 16, v72
	v_fma_f32 v70, v2, v70, v6
	v_lshlrev_b32_e32 v71, 16, v68
	v_mul_f32_e32 v70, v70, v71
	v_and_b32_e32 v71, 0xffff0000, v72
	v_fma_f32 v71, v3, v71, v7
	v_and_b32_e32 v68, 0xffff0000, v68
	v_mul_f32_e32 v68, v71, v68
	v_cvt_pk_bf16_f32 v68, v70, v68
	v_lshlrev_b32_e32 v70, 16, v73
	v_fma_f32 v70, v4, v70, v8
	v_lshlrev_b32_e32 v71, 16, v69
	v_mul_f32_e32 v70, v70, v71
	v_and_b32_e32 v71, 0xffff0000, v73
	v_fma_f32 v71, v5, v71, v9
	v_and_b32_e32 v69, 0xffff0000, v69
	v_mul_f32_e32 v69, v71, v69
	v_cvt_pk_bf16_f32 v69, v70, v69
	v_add_u32_e32 v70, s29, v74
	v_ashrrev_i32_e32 v71, 31, v70
	v_lshlrev_b64 v[70:71], 12, v[70:71]
	v_lshl_add_u64 v[70:71], v[78:79], 0, v[70:71]
	global_store_dwordx4 v[70:71], v[66:69], off nt
	v_add_u32_e32 v70, 32, v80
	v_lshlrev_b32_e32 v72, 16, v62
	v_lshlrev_b32_e32 v66, 10, v70
	v_add3_u32 v66, 0, v66, v81
	ds_read_b128 v[66:69], v66
	v_and_b32_e32 v62, 0xffff0000, v62
	s_waitcnt lgkmcnt(0)
; #define LAS __attribute__((address_space(3)))
; __device__ __forceinline__ unsigned cvt_pk_bf16(float lo, float hi) { unsigned r; asm volatile("v_cvt_pk_bf16_f32 %0, %1, %2" : "=v"(r) : "v"(lo), "v"(hi)); return r; }
; __device__ __forceinline__ float bflo(unsigned u) { return __uint_as_float(u << 16); }
; __device__ __forceinline__ float bfhi(unsigned u) { return __uint_as_float(u & 0xffff0000u); }
; __device__ __forceinline__ void retc_stream(const int wv, LAS unsigned char* lds, unsigned ldsb, const float* __restrict__ gn_g, const float* __restrict__ gn_b, const bf16_t* __restrict__ qkvr, const bf16_t* __restrict__ grb, const bf16_t* __restrict__ kv, ...
;     ...
; #pragma unroll
;             for (int k = 0; k < 16; ++k) {
;                 const int row = r0 + 8 * k;
;                 const u32x4 yv = *(const LAS u32x4*)(lds + row * 1024 + ((ch ^ (2 * ((row >> 2) & 3))) << 4));
;                 const u32x4 q = gv[k];
;                 u32x4 o;
;                 o.x = cvt_pk_bf16((bflo(yv.x) * g0[0] + b0[0]) * bflo(q.x), (bfhi(yv.x) * g0[1] + b0[1]) * bfhi(q.x));
;                 o.y = cvt_pk_bf16((bflo(yv.y) * g0[2] + b0[2]) * bflo(q.y), (bfhi(yv.y) * g0[3] + b0[3]) * bfhi(q.y));
;                 o.z = cvt_pk_bf16((bflo(yv.z) * g1[0] + b1[0]) * bflo(q.z), (bfhi(yv.z) * g1[1] + b1[1]) * bfhi(q.z));
;                 o.w = cvt_pk_bf16((bflo(yv.w) * g1[2] + b1[2]) * bflo(q.w), (bfhi(yv.w) * g1[3] + b1[3]) * bfhi(q.w));
;                 *(u32x4*)(orb + (size_t)(n * 128 + row) * 2048 + h * 512 + ch * 8) = o;
;             }
	v_lshlrev_b32_e32 v71, 16, v66
	v_and_b32_e32 v66, 0xffff0000, v66
	v_fma_f32 v71, v10, v71, v14
	v_fma_f32 v66, v11, v66, v15
	v_mul_f32_e32 v71, v71, v72
	v_mul_f32_e32 v62, v66, v62
	v_lshlrev_b32_e32 v66, 16, v67
	v_and_b32_e32 v67, 0xffff0000, v67
	v_cvt_pk_bf16_f32 v62, v71, v62
	v_fma_f32 v66, v12, v66, v16
	v_lshlrev_b32_e32 v71, 16, v63
	v_fma_f32 v67, v13, v67, v17
	v_and_b32_e32 v63, 0xffff0000, v63
	v_mul_f32_e32 v66, v66, v71
	v_mul_f32_e32 v63, v67, v63
	v_cvt_pk_bf16_f32 v63, v66, v63
	v_lshlrev_b32_e32 v66, 16, v68
	v_fma_f32 v66, v2, v66, v6
	v_lshlrev_b32_e32 v67, 16, v64
	v_mul_f32_e32 v66, v66, v67
	v_and_b32_e32 v67, 0xffff0000, v68
	v_fma_f32 v67, v3, v67, v7
	v_and_b32_e32 v64, 0xffff0000, v64
	v_mul_f32_e32 v64, v67, v64
	v_cvt_pk_bf16_f32 v64, v66, v64
	v_lshlrev_b32_e32 v66, 16, v69
	v_fma_f32 v66, v4, v66, v8
	v_lshlrev_b32_e32 v67, 16, v65
	v_mul_f32_e32 v66, v66, v67
	v_and_b32_e32 v67, 0xffff0000, v69
	v_fma_f32 v67, v5, v67, v9
	v_and_b32_e32 v65, 0xffff0000, v65
	v_mul_f32_e32 v65, v67, v65
	v_cvt_pk_bf16_f32 v65, v66, v65
	v_add_u32_e32 v66, s29, v70
	v_ashrrev_i32_e32 v67, 31, v66
	v_lshlrev_b64 v[66:67], 12, v[66:67]
	v_lshl_add_u64 v[66:67], v[78:79], 0, v[66:67]
	global_store_dwordx4 v[66:67], v[62:65], off nt
	v_add_u32_e32 v66, 40, v80
	v_lshlrev_b32_e32 v68, 16, v58
	v_lshrrev_b32_e32 v63, 1, v66
	v_bitop3_b32 v63, v63, v1, 6 bitop3:0x6c
	v_lshlrev_b32_e32 v62, 10, v66
	v_lshlrev_b32_e32 v63, 4, v63
	v_add3_u32 v62, 0, v62, v63
	ds_read_b128 v[62:65], v62
	v_and_b32_e32 v58, 0xffff0000, v58
	s_waitcnt lgkmcnt(0)
	v_lshlrev_b32_e32 v67, 16, v62
	v_and_b32_e32 v62, 0xffff0000, v62
	v_fma_f32 v67, v10, v67, v14
	v_fma_f32 v62, v11, v62, v15
	v_mul_f32_e32 v67, v67, v68
	v_mul_f32_e32 v58, v62, v58
	v_lshlrev_b32_e32 v62, 16, v63
	v_and_b32_e32 v63, 0xffff0000, v63
	v_cvt_pk_bf16_f32 v58, v67, v58
	v_fma_f32 v62, v12, v62, v16
	v_lshlrev_b32_e32 v67, 16, v59
	v_fma_f32 v63, v13, v63, v17
	v_and_b32_e32 v59, 0xffff0000, v59
	v_mul_f32_e32 v62, v62, v67
	v_mul_f32_e32 v59, v63, v59
	v_cvt_pk_bf16_f32 v59, v62, v59
	v_lshlrev_b32_e32 v62, 16, v64
	v_fma_f32 v62, v2, v62, v6
	v_lshlrev_b32_e32 v63, 16, v60
	v_mul_f32_e32 v62, v62, v63
	v_and_b32_e32 v63, 0xffff0000, v64
	v_fma_f32 v63, v3, v63, v7
	v_and_b32_e32 v60, 0xffff0000, v60
	v_mul_f32_e32 v60, v63, v60
	v_cvt_pk_bf16_f32 v60, v62, v60
	v_lshlrev_b32_e32 v62, 16, v65
	v_fma_f32 v62, v4, v62, v8
	v_lshlrev_b32_e32 v63, 16, v61
	v_mul_f32_e32 v62, v62, v63
	v_and_b32_e32 v63, 0xffff0000, v65
	v_fma_f32 v63, v5, v63, v9
	v_and_b32_e32 v61, 0xffff0000, v61
	v_mul_f32_e32 v61, v63, v61
	v_cvt_pk_bf16_f32 v61, v62, v61
	v_add_u32_e32 v62, s29, v66
	v_ashrrev_i32_e32 v63, 31, v62
	v_lshlrev_b64 v[62:63], 12, v[62:63]
	v_lshl_add_u64 v[62:63], v[78:79], 0, v[62:63]
	global_store_dwordx4 v[62:63], v[58:61], off nt
	v_add_u32_e32 v62, 48, v80
	v_lshlrev_b32_e32 v64, 16, v54
	v_lshlrev_b32_e32 v58, 10, v62
	v_add3_u32 v58, 0, v58, v81
	ds_read_b128 v[58:61], v58
	v_and_b32_e32 v54, 0xffff0000, v54
	s_waitcnt lgkmcnt(0)
	v_lshlrev_b32_e32 v63, 16, v58
	v_and_b32_e32 v58, 0xffff0000, v58
	v_fma_f32 v63, v10, v63, v14
	v_fma_f32 v58, v11, v58, v15
	v_mul_f32_e32 v63, v63, v64
	v_mul_f32_e32 v54, v58, v54
	v_lshlrev_b32_e32 v58, 16, v59
	v_and_b32_e32 v59, 0xffff0000, v59
	v_cvt_pk_bf16_f32 v54, v63, v54
	v_fma_f32 v58, v12, v58, v16
	v_lshlrev_b32_e32 v63, 16, v55
	v_fma_f32 v59, v13, v59, v17
	v_and_b32_e32 v55, 0xffff0000, v55
	v_mul_f32_e32 v58, v58, v63
	v_mul_f32_e32 v55, v59, v55
	v_cvt_pk_bf16_f32 v55, v58, v55
	v_lshlrev_b32_e32 v58, 16, v60
	v_fma_f32 v58, v2, v58, v6
	v_lshlrev_b32_e32 v59, 16, v56
	v_mul_f32_e32 v58, v58, v59
	v_and_b32_e32 v59, 0xffff0000, v60
	v_fma_f32 v59, v3, v59, v7
	v_and_b32_e32 v56, 0xffff0000, v56
	v_mul_f32_e32 v56, v59, v56
	v_cvt_pk_bf16_f32 v56, v58, v56
	v_lshlrev_b32_e32 v58, 16, v61
	v_fma_f32 v58, v4, v58, v8
	v_lshlrev_b32_e32 v59, 16, v57
	v_mul_f32_e32 v58, v58, v59
	v_and_b32_e32 v59, 0xffff0000, v61
	v_fma_f32 v59, v5, v59, v9
	v_and_b32_e32 v57, 0xffff0000, v57
	v_mul_f32_e32 v57, v59, v57
	v_cvt_pk_bf16_f32 v57, v58, v57
	v_add_u32_e32 v58, s29, v62
	v_ashrrev_i32_e32 v59, 31, v58
	v_lshlrev_b64 v[58:59], 12, v[58:59]
	v_lshl_add_u64 v[58:59], v[78:79], 0, v[58:59]
	global_store_dwordx4 v[58:59], v[54:57], off nt
	v_add_u32_e32 v58, 56, v80
	v_lshlrev_b32_e32 v60, 16, v50
	v_lshrrev_b32_e32 v55, 1, v58
	v_bitop3_b32 v55, v55, v1, 6 bitop3:0x6c
	v_lshlrev_b32_e32 v54, 10, v58
	v_lshlrev_b32_e32 v55, 4, v55
	v_add3_u32 v54, 0, v54, v55
	ds_read_b128 v[54:57], v54
	v_and_b32_e32 v50, 0xffff0000, v50
	s_waitcnt lgkmcnt(0)
	v_lshlrev_b32_e32 v59, 16, v54
	v_and_b32_e32 v54, 0xffff0000, v54
	v_fma_f32 v59, v10, v59, v14
	v_fma_f32 v54, v11, v54, v15
	v_mul_f32_e32 v59, v59, v60
	v_mul_f32_e32 v50, v54, v50
	v_lshlrev_b32_e32 v54, 16, v55
	v_and_b32_e32 v55, 0xffff0000, v55
	v_cvt_pk_bf16_f32 v50, v59, v50
	v_fma_f32 v54, v12, v54, v16
	v_lshlrev_b32_e32 v59, 16, v51
	v_fma_f32 v55, v13, v55, v17
	v_and_b32_e32 v51, 0xffff0000, v51
	v_mul_f32_e32 v54, v54, v59
	v_mul_f32_e32 v51, v55, v51
	v_cvt_pk_bf16_f32 v51, v54, v51
	v_lshlrev_b32_e32 v54, 16, v56
	v_fma_f32 v54, v2, v54, v6
	v_lshlrev_b32_e32 v55, 16, v52
	v_mul_f32_e32 v54, v54, v55
	v_and_b32_e32 v55, 0xffff0000, v56
	v_fma_f32 v55, v3, v55, v7
	v_and_b32_e32 v52, 0xffff0000, v52
	v_mul_f32_e32 v52, v55, v52
	v_cvt_pk_bf16_f32 v52, v54, v52
	v_lshlrev_b32_e32 v54, 16, v57
	v_fma_f32 v54, v4, v54, v8
	v_lshlrev_b32_e32 v55, 16, v53
	v_mul_f32_e32 v54, v54, v55
	v_and_b32_e32 v55, 0xffff0000, v57
	v_fma_f32 v55, v5, v55, v9
	v_and_b32_e32 v53, 0xffff0000, v53
	v_mul_f32_e32 v53, v55, v53
	v_cvt_pk_bf16_f32 v53, v54, v53
	v_add_u32_e32 v54, s29, v58
	v_ashrrev_i32_e32 v55, 31, v54
	v_lshlrev_b64 v[54:55], 12, v[54:55]
	v_lshl_add_u64 v[54:55], v[78:79], 0, v[54:55]
	global_store_dwordx4 v[54:55], v[50:53], off nt
	v_add_u32_e32 v54, 64, v80
	v_lshlrev_b32_e32 v56, 16, v46
	v_lshlrev_b32_e32 v50, 10, v54
	v_add3_u32 v50, 0, v50, v81
	ds_read_b128 v[50:53], v50
	v_and_b32_e32 v46, 0xffff0000, v46
	s_waitcnt lgkmcnt(0)
; #define LAS __attribute__((address_space(3)))
; __device__ __forceinline__ unsigned cvt_pk_bf16(float lo, float hi) { unsigned r; asm volatile("v_cvt_pk_bf16_f32 %0, %1, %2" : "=v"(r) : "v"(lo), "v"(hi)); return r; }
; __device__ __forceinline__ float bflo(unsigned u) { return __uint_as_float(u << 16); }
; __device__ __forceinline__ float bfhi(unsigned u) { return __uint_as_float(u & 0xffff0000u); }
; __device__ __forceinline__ void retc_stream(const int wv, LAS unsigned char* lds, unsigned ldsb, const float* __restrict__ gn_g, const float* __restrict__ gn_b, const bf16_t* __restrict__ qkvr, const bf16_t* __restrict__ grb, const bf16_t* __restrict__ kv, ...
;     ...
; #pragma unroll
;             for (int k = 0; k < 16; ++k) {
;                 const int row = r0 + 8 * k;
;                 const u32x4 yv = *(const LAS u32x4*)(lds + row * 1024 + ((ch ^ (2 * ((row >> 2) & 3))) << 4));
;                 const u32x4 q = gv[k];
;                 u32x4 o;
;                 o.x = cvt_pk_bf16((bflo(yv.x) * g0[0] + b0[0]) * bflo(q.x), (bfhi(yv.x) * g0[1] + b0[1]) * bfhi(q.x));
;                 o.y = cvt_pk_bf16((bflo(yv.y) * g0[2] + b0[2]) * bflo(q.y), (bfhi(yv.y) * g0[3] + b0[3]) * bfhi(q.y));
;                 o.z = cvt_pk_bf16((bflo(yv.z) * g1[0] + b1[0]) * bflo(q.z), (bfhi(yv.z) * g1[1] + b1[1]) * bfhi(q.z));
;                 o.w = cvt_pk_bf16((bflo(yv.w) * g1[2] + b1[2]) * bflo(q.w), (bfhi(yv.w) * g1[3] + b1[3]) * bfhi(q.w));
;                 *(u32x4*)(orb + (size_t)(n * 128 + row) * 2048 + h * 512 + ch * 8) = o;
;             }
	v_lshlrev_b32_e32 v55, 16, v50
	v_and_b32_e32 v50, 0xffff0000, v50
	v_fma_f32 v55, v10, v55, v14
	v_fma_f32 v50, v11, v50, v15
	v_mul_f32_e32 v55, v55, v56
	v_mul_f32_e32 v46, v50, v46
	v_lshlrev_b32_e32 v50, 16, v51
	v_and_b32_e32 v51, 0xffff0000, v51
	v_cvt_pk_bf16_f32 v46, v55, v46
	v_fma_f32 v50, v12, v50, v16
	v_lshlrev_b32_e32 v55, 16, v47
	v_fma_f32 v51, v13, v51, v17
	v_and_b32_e32 v47, 0xffff0000, v47
	v_mul_f32_e32 v50, v50, v55
	v_mul_f32_e32 v47, v51, v47
	v_cvt_pk_bf16_f32 v47, v50, v47
	v_lshlrev_b32_e32 v50, 16, v52
	v_fma_f32 v50, v2, v50, v6
	v_lshlrev_b32_e32 v51, 16, v48
	v_mul_f32_e32 v50, v50, v51
	v_and_b32_e32 v51, 0xffff0000, v52
	v_fma_f32 v51, v3, v51, v7
	v_and_b32_e32 v48, 0xffff0000, v48
	v_mul_f32_e32 v48, v51, v48
	v_cvt_pk_bf16_f32 v48, v50, v48
	v_lshlrev_b32_e32 v50, 16, v53
	v_fma_f32 v50, v4, v50, v8
	v_lshlrev_b32_e32 v51, 16, v49
	v_mul_f32_e32 v50, v50, v51
	v_and_b32_e32 v51, 0xffff0000, v53
	v_fma_f32 v51, v5, v51, v9
	v_and_b32_e32 v49, 0xffff0000, v49
	v_mul_f32_e32 v49, v51, v49
	v_cvt_pk_bf16_f32 v49, v50, v49
	v_add_u32_e32 v50, s29, v54
	v_ashrrev_i32_e32 v51, 31, v50
	v_lshlrev_b64 v[50:51], 12, v[50:51]
	v_lshl_add_u64 v[50:51], v[78:79], 0, v[50:51]
	global_store_dwordx4 v[50:51], v[46:49], off nt
	v_add_u32_e32 v50, 0x48, v80
	v_lshlrev_b32_e32 v52, 16, v42
	v_lshrrev_b32_e32 v47, 1, v50
	v_bitop3_b32 v47, v47, v1, 6 bitop3:0x6c
	v_lshlrev_b32_e32 v46, 10, v50
	v_lshlrev_b32_e32 v47, 4, v47
	v_add3_u32 v46, 0, v46, v47
	ds_read_b128 v[46:49], v46
	v_and_b32_e32 v42, 0xffff0000, v42
	s_waitcnt lgkmcnt(0)
	v_lshlrev_b32_e32 v51, 16, v46
	v_and_b32_e32 v46, 0xffff0000, v46
	v_fma_f32 v51, v10, v51, v14
	v_fma_f32 v46, v11, v46, v15
	v_mul_f32_e32 v51, v51, v52
	v_mul_f32_e32 v42, v46, v42
	v_lshlrev_b32_e32 v46, 16, v47
	v_and_b32_e32 v47, 0xffff0000, v47
	v_cvt_pk_bf16_f32 v42, v51, v42
	v_fma_f32 v46, v12, v46, v16
	v_lshlrev_b32_e32 v51, 16, v43
	v_fma_f32 v47, v13, v47, v17
	v_and_b32_e32 v43, 0xffff0000, v43
	v_mul_f32_e32 v46, v46, v51
	v_mul_f32_e32 v43, v47, v43
	v_cvt_pk_bf16_f32 v43, v46, v43
	v_lshlrev_b32_e32 v46, 16, v48
	v_fma_f32 v46, v2, v46, v6
	v_lshlrev_b32_e32 v47, 16, v44
	v_mul_f32_e32 v46, v46, v47
	v_and_b32_e32 v47, 0xffff0000, v48
	v_fma_f32 v47, v3, v47, v7
	v_and_b32_e32 v44, 0xffff0000, v44
	v_mul_f32_e32 v44, v47, v44
	v_cvt_pk_bf16_f32 v44, v46, v44
	v_lshlrev_b32_e32 v46, 16, v49
	v_fma_f32 v46, v4, v46, v8
	v_lshlrev_b32_e32 v47, 16, v45
	v_mul_f32_e32 v46, v46, v47
	v_and_b32_e32 v47, 0xffff0000, v49
	v_fma_f32 v47, v5, v47, v9
	v_and_b32_e32 v45, 0xffff0000, v45
	v_mul_f32_e32 v45, v47, v45
	v_cvt_pk_bf16_f32 v45, v46, v45
	v_add_u32_e32 v46, s29, v50
	v_ashrrev_i32_e32 v47, 31, v46
	v_lshlrev_b64 v[46:47], 12, v[46:47]
	v_lshl_add_u64 v[46:47], v[78:79], 0, v[46:47]
	global_store_dwordx4 v[46:47], v[42:45], off nt
	v_add_u32_e32 v46, 0x50, v80
	v_lshlrev_b32_e32 v48, 16, v38
	v_lshlrev_b32_e32 v42, 10, v46
	v_add3_u32 v42, 0, v42, v81
	ds_read_b128 v[42:45], v42
	v_and_b32_e32 v38, 0xffff0000, v38
	s_waitcnt lgkmcnt(0)
	v_lshlrev_b32_e32 v47, 16, v42
	v_and_b32_e32 v42, 0xffff0000, v42
	v_fma_f32 v47, v10, v47, v14
	v_fma_f32 v42, v11, v42, v15
	v_mul_f32_e32 v47, v47, v48
	v_mul_f32_e32 v38, v42, v38
	v_lshlrev_b32_e32 v42, 16, v43
	v_and_b32_e32 v43, 0xffff0000, v43
	v_cvt_pk_bf16_f32 v38, v47, v38
	v_fma_f32 v42, v12, v42, v16
	v_lshlrev_b32_e32 v47, 16, v39
	v_fma_f32 v43, v13, v43, v17
	v_and_b32_e32 v39, 0xffff0000, v39
	v_mul_f32_e32 v42, v42, v47
	v_mul_f32_e32 v39, v43, v39
	v_cvt_pk_bf16_f32 v39, v42, v39
	v_lshlrev_b32_e32 v42, 16, v44
	v_fma_f32 v42, v2, v42, v6
	v_lshlrev_b32_e32 v43, 16, v40
	v_mul_f32_e32 v42, v42, v43
	v_and_b32_e32 v43, 0xffff0000, v44
	v_fma_f32 v43, v3, v43, v7
	v_and_b32_e32 v40, 0xffff0000, v40
	v_mul_f32_e32 v40, v43, v40
	v_cvt_pk_bf16_f32 v40, v42, v40
	v_lshlrev_b32_e32 v42, 16, v45
	v_fma_f32 v42, v4, v42, v8
	v_lshlrev_b32_e32 v43, 16, v41
	v_mul_f32_e32 v42, v42, v43
	v_and_b32_e32 v43, 0xffff0000, v45
	v_fma_f32 v43, v5, v43, v9
	v_and_b32_e32 v41, 0xffff0000, v41
	v_mul_f32_e32 v41, v43, v41
	v_cvt_pk_bf16_f32 v41, v42, v41
	v_add_u32_e32 v42, s29, v46
	v_ashrrev_i32_e32 v43, 31, v42
	v_lshlrev_b64 v[42:43], 12, v[42:43]
	v_lshl_add_u64 v[42:43], v[78:79], 0, v[42:43]
	global_store_dwordx4 v[42:43], v[38:41], off nt
	v_add_u32_e32 v42, 0x58, v80
	v_lshlrev_b32_e32 v44, 16, v34
	v_lshrrev_b32_e32 v39, 1, v42
	v_bitop3_b32 v39, v39, v1, 6 bitop3:0x6c
	v_lshlrev_b32_e32 v38, 10, v42
	v_lshlrev_b32_e32 v39, 4, v39
	v_add3_u32 v38, 0, v38, v39
	ds_read_b128 v[38:41], v38
	v_and_b32_e32 v34, 0xffff0000, v34
	s_waitcnt lgkmcnt(0)
	v_lshlrev_b32_e32 v43, 16, v38
	v_and_b32_e32 v38, 0xffff0000, v38
	v_fma_f32 v43, v10, v43, v14
	v_fma_f32 v38, v11, v38, v15
	v_mul_f32_e32 v43, v43, v44
	v_mul_f32_e32 v34, v38, v34
	v_lshlrev_b32_e32 v38, 16, v39
	v_and_b32_e32 v39, 0xffff0000, v39
	v_cvt_pk_bf16_f32 v34, v43, v34
	v_fma_f32 v38, v12, v38, v16
	v_lshlrev_b32_e32 v43, 16, v35
	v_fma_f32 v39, v13, v39, v17
	v_and_b32_e32 v35, 0xffff0000, v35
	v_mul_f32_e32 v38, v38, v43
	v_mul_f32_e32 v35, v39, v35
	v_cvt_pk_bf16_f32 v35, v38, v35
	v_lshlrev_b32_e32 v38, 16, v40
	v_fma_f32 v38, v2, v38, v6
	v_lshlrev_b32_e32 v39, 16, v36
	v_mul_f32_e32 v38, v38, v39
	v_and_b32_e32 v39, 0xffff0000, v40
	v_fma_f32 v39, v3, v39, v7
	v_and_b32_e32 v36, 0xffff0000, v36
	v_mul_f32_e32 v36, v39, v36
	v_cvt_pk_bf16_f32 v36, v38, v36
	v_lshlrev_b32_e32 v38, 16, v41
	v_fma_f32 v38, v4, v38, v8
	v_lshlrev_b32_e32 v39, 16, v37
	v_mul_f32_e32 v38, v38, v39
	v_and_b32_e32 v39, 0xffff0000, v41
	v_fma_f32 v39, v5, v39, v9
	v_and_b32_e32 v37, 0xffff0000, v37
	v_mul_f32_e32 v37, v39, v37
	v_cvt_pk_bf16_f32 v37, v38, v37
	v_add_u32_e32 v38, s29, v42
	v_ashrrev_i32_e32 v39, 31, v38
	v_lshlrev_b64 v[38:39], 12, v[38:39]
	v_lshl_add_u64 v[38:39], v[78:79], 0, v[38:39]
	global_store_dwordx4 v[38:39], v[34:37], off nt
	v_add_u32_e32 v38, 0x60, v80
	v_lshlrev_b32_e32 v40, 16, v30
	v_lshlrev_b32_e32 v34, 10, v38
	v_add3_u32 v34, 0, v34, v81
	ds_read_b128 v[34:37], v34
	v_and_b32_e32 v30, 0xffff0000, v30
	s_waitcnt lgkmcnt(0)
; #define LAS __attribute__((address_space(3)))
; __device__ __forceinline__ unsigned cvt_pk_bf16(float lo, float hi) { unsigned r; asm volatile("v_cvt_pk_bf16_f32 %0, %1, %2" : "=v"(r) : "v"(lo), "v"(hi)); return r; }
; __device__ __forceinline__ float bflo(unsigned u) { return __uint_as_float(u << 16); }
; __device__ __forceinline__ float bfhi(unsigned u) { return __uint_as_float(u & 0xffff0000u); }
; __device__ __forceinline__ void retc_stream(const int wv, LAS unsigned char* lds, unsigned ldsb, const float* __restrict__ gn_g, const float* __restrict__ gn_b, const bf16_t* __restrict__ qkvr, const bf16_t* __restrict__ grb, const bf16_t* __restrict__ kv, ...
;     ...
; #pragma unroll
;             for (int k = 0; k < 16; ++k) {
;                 const int row = r0 + 8 * k;
;                 const u32x4 yv = *(const LAS u32x4*)(lds + row * 1024 + ((ch ^ (2 * ((row >> 2) & 3))) << 4));
;                 const u32x4 q = gv[k];
;                 u32x4 o;
;                 o.x = cvt_pk_bf16((bflo(yv.x) * g0[0] + b0[0]) * bflo(q.x), (bfhi(yv.x) * g0[1] + b0[1]) * bfhi(q.x));
;                 o.y = cvt_pk_bf16((bflo(yv.y) * g0[2] + b0[2]) * bflo(q.y), (bfhi(yv.y) * g0[3] + b0[3]) * bfhi(q.y));
;                 o.z = cvt_pk_bf16((bflo(yv.z) * g1[0] + b1[0]) * bflo(q.z), (bfhi(yv.z) * g1[1] + b1[1]) * bfhi(q.z));
;                 o.w = cvt_pk_bf16((bflo(yv.w) * g1[2] + b1[2]) * bflo(q.w), (bfhi(yv.w) * g1[3] + b1[3]) * bfhi(q.w));
;                 *(u32x4*)(orb + (size_t)(n * 128 + row) * 2048 + h * 512 + ch * 8) = o;
;             }
;         }
;         if (inext >= count) break;
	v_lshlrev_b32_e32 v39, 16, v34
	v_and_b32_e32 v34, 0xffff0000, v34
	v_fma_f32 v39, v10, v39, v14
	v_fma_f32 v34, v11, v34, v15
	v_mul_f32_e32 v39, v39, v40
	v_mul_f32_e32 v30, v34, v30
	v_lshlrev_b32_e32 v34, 16, v35
	v_and_b32_e32 v35, 0xffff0000, v35
	v_cvt_pk_bf16_f32 v30, v39, v30
	v_fma_f32 v34, v12, v34, v16
	v_lshlrev_b32_e32 v39, 16, v31
	v_fma_f32 v35, v13, v35, v17
	v_and_b32_e32 v31, 0xffff0000, v31
	v_mul_f32_e32 v34, v34, v39
	v_mul_f32_e32 v31, v35, v31
	v_cvt_pk_bf16_f32 v31, v34, v31
	v_lshlrev_b32_e32 v34, 16, v36
	v_fma_f32 v34, v2, v34, v6
	v_lshlrev_b32_e32 v35, 16, v32
	v_mul_f32_e32 v34, v34, v35
	v_and_b32_e32 v35, 0xffff0000, v36
	v_fma_f32 v35, v3, v35, v7
	v_and_b32_e32 v32, 0xffff0000, v32
	v_mul_f32_e32 v32, v35, v32
	v_cvt_pk_bf16_f32 v32, v34, v32
	v_lshlrev_b32_e32 v34, 16, v37
	v_fma_f32 v34, v4, v34, v8
	v_lshlrev_b32_e32 v35, 16, v33
	v_mul_f32_e32 v34, v34, v35
	v_and_b32_e32 v35, 0xffff0000, v37
	v_fma_f32 v35, v5, v35, v9
	v_and_b32_e32 v33, 0xffff0000, v33
	v_mul_f32_e32 v33, v35, v33
	v_cvt_pk_bf16_f32 v33, v34, v33
	v_add_u32_e32 v34, s29, v38
	v_ashrrev_i32_e32 v35, 31, v34
	v_lshlrev_b64 v[34:35], 12, v[34:35]
	v_lshl_add_u64 v[34:35], v[78:79], 0, v[34:35]
	global_store_dwordx4 v[34:35], v[30:33], off nt
	v_add_u32_e32 v34, 0x68, v80
	v_lshlrev_b32_e32 v36, 16, v26
	v_lshrrev_b32_e32 v31, 1, v34
	v_bitop3_b32 v31, v31, v1, 6 bitop3:0x6c
	v_lshlrev_b32_e32 v30, 10, v34
	v_lshlrev_b32_e32 v31, 4, v31
	v_add3_u32 v30, 0, v30, v31
	ds_read_b128 v[30:33], v30
	v_and_b32_e32 v26, 0xffff0000, v26
	s_waitcnt lgkmcnt(0)
	v_lshlrev_b32_e32 v35, 16, v30
	v_and_b32_e32 v30, 0xffff0000, v30
	v_fma_f32 v35, v10, v35, v14
	v_fma_f32 v30, v11, v30, v15
	v_mul_f32_e32 v35, v35, v36
	v_mul_f32_e32 v26, v30, v26
	v_lshlrev_b32_e32 v30, 16, v31
	v_and_b32_e32 v31, 0xffff0000, v31
	v_cvt_pk_bf16_f32 v26, v35, v26
	v_fma_f32 v30, v12, v30, v16
	v_lshlrev_b32_e32 v35, 16, v27
	v_fma_f32 v31, v13, v31, v17
	v_and_b32_e32 v27, 0xffff0000, v27
	v_mul_f32_e32 v30, v30, v35
	v_mul_f32_e32 v27, v31, v27
	v_cvt_pk_bf16_f32 v27, v30, v27
	v_lshlrev_b32_e32 v30, 16, v32
	v_fma_f32 v30, v2, v30, v6
	v_lshlrev_b32_e32 v31, 16, v28
	v_mul_f32_e32 v30, v30, v31
	v_and_b32_e32 v31, 0xffff0000, v32
	v_fma_f32 v31, v3, v31, v7
	v_and_b32_e32 v28, 0xffff0000, v28
	v_mul_f32_e32 v28, v31, v28
	v_cvt_pk_bf16_f32 v28, v30, v28
	v_lshlrev_b32_e32 v30, 16, v33
	v_fma_f32 v30, v4, v30, v8
	v_lshlrev_b32_e32 v31, 16, v29
	v_mul_f32_e32 v30, v30, v31
	v_and_b32_e32 v31, 0xffff0000, v33
	v_fma_f32 v31, v5, v31, v9
	v_and_b32_e32 v29, 0xffff0000, v29
	v_mul_f32_e32 v29, v31, v29
	v_cvt_pk_bf16_f32 v29, v30, v29
	v_add_u32_e32 v30, s29, v34
	v_ashrrev_i32_e32 v31, 31, v30
	v_lshlrev_b64 v[30:31], 12, v[30:31]
	v_lshl_add_u64 v[30:31], v[78:79], 0, v[30:31]
	global_store_dwordx4 v[30:31], v[26:29], off nt
	v_add_u32_e32 v30, 0x70, v80
	v_lshlrev_b32_e32 v32, 16, v22
	v_lshlrev_b32_e32 v26, 10, v30
	v_add3_u32 v26, 0, v26, v81
	ds_read_b128 v[26:29], v26
	v_and_b32_e32 v22, 0xffff0000, v22
	s_waitcnt lgkmcnt(0)
	v_lshlrev_b32_e32 v31, 16, v26
	v_and_b32_e32 v26, 0xffff0000, v26
	v_fma_f32 v31, v10, v31, v14
	v_fma_f32 v26, v11, v26, v15
	v_mul_f32_e32 v31, v31, v32
	v_mul_f32_e32 v22, v26, v22
	v_lshlrev_b32_e32 v26, 16, v27
	v_and_b32_e32 v27, 0xffff0000, v27
	v_cvt_pk_bf16_f32 v22, v31, v22
	v_fma_f32 v26, v12, v26, v16
	v_lshlrev_b32_e32 v31, 16, v23
	v_fma_f32 v27, v13, v27, v17
	v_and_b32_e32 v23, 0xffff0000, v23
	v_mul_f32_e32 v26, v26, v31
	v_mul_f32_e32 v23, v27, v23
	v_cvt_pk_bf16_f32 v23, v26, v23
	v_lshlrev_b32_e32 v26, 16, v28
	v_fma_f32 v26, v2, v26, v6
	v_lshlrev_b32_e32 v27, 16, v24
	v_mul_f32_e32 v26, v26, v27
	v_and_b32_e32 v27, 0xffff0000, v28
	v_fma_f32 v27, v3, v27, v7
	v_and_b32_e32 v24, 0xffff0000, v24
	v_mul_f32_e32 v24, v27, v24
	v_cvt_pk_bf16_f32 v24, v26, v24
	v_lshlrev_b32_e32 v26, 16, v29
	v_fma_f32 v26, v4, v26, v8
	v_lshlrev_b32_e32 v27, 16, v25
	v_mul_f32_e32 v26, v26, v27
	v_and_b32_e32 v27, 0xffff0000, v29
	v_fma_f32 v27, v5, v27, v9
	v_and_b32_e32 v25, 0xffff0000, v25
	v_mul_f32_e32 v25, v27, v25
	v_cvt_pk_bf16_f32 v25, v26, v25
	v_add_u32_e32 v26, s29, v30
	v_ashrrev_i32_e32 v27, 31, v26
	v_lshlrev_b64 v[26:27], 12, v[26:27]
	v_lshl_add_u64 v[26:27], v[78:79], 0, v[26:27]
	global_store_dwordx4 v[26:27], v[22:25], off nt
	v_add_u32_e32 v26, 0x78, v80
	s_nop 0
	v_lshrrev_b32_e32 v23, 1, v26
	v_bitop3_b32 v1, v23, v1, 6 bitop3:0x6c
	v_lshlrev_b32_e32 v22, 10, v26
	v_lshlrev_b32_e32 v1, 4, v1
	v_add3_u32 v1, 0, v22, v1
	ds_read_b128 v[22:25], v1
	s_waitcnt lgkmcnt(0)
	v_lshlrev_b32_e32 v1, 16, v22
	v_fma_f32 v1, v10, v1, v14
	v_lshlrev_b32_e32 v10, 16, v18
	v_mul_f32_e32 v1, v1, v10
	v_and_b32_e32 v10, 0xffff0000, v22
	v_fma_f32 v10, v11, v10, v15
	v_and_b32_e32 v11, 0xffff0000, v18
	v_mul_f32_e32 v10, v10, v11
	v_cvt_pk_bf16_f32 v10, v1, v10
	v_lshlrev_b32_e32 v1, 16, v23
	v_fma_f32 v1, v12, v1, v16
	v_lshlrev_b32_e32 v11, 16, v19
	v_mul_f32_e32 v1, v1, v11
	v_and_b32_e32 v11, 0xffff0000, v23
	v_fmac_f32_e32 v17, v13, v11
	v_and_b32_e32 v11, 0xffff0000, v19
	v_mul_f32_e32 v11, v17, v11
	v_cvt_pk_bf16_f32 v11, v1, v11
	v_lshlrev_b32_e32 v1, 16, v24
	v_fma_f32 v1, v2, v1, v6
	v_lshlrev_b32_e32 v2, 16, v20
	v_mul_f32_e32 v1, v1, v2
	v_and_b32_e32 v2, 0xffff0000, v24
	v_fma_f32 v2, v3, v2, v7
	v_and_b32_e32 v3, 0xffff0000, v20
	v_mul_f32_e32 v2, v2, v3
	v_cvt_pk_bf16_f32 v12, v1, v2
	v_lshlrev_b32_e32 v1, 16, v25
	v_fma_f32 v1, v4, v1, v8
	v_lshlrev_b32_e32 v2, 16, v21
	v_mul_f32_e32 v1, v1, v2
	v_and_b32_e32 v2, 0xffff0000, v25
	v_fmac_f32_e32 v9, v5, v2
	v_and_b32_e32 v2, 0xffff0000, v21
	v_mul_f32_e32 v2, v9, v2
	v_cvt_pk_bf16_f32 v13, v1, v2
	v_add_u32_e32 v2, s29, v26
	v_ashrrev_i32_e32 v3, 31, v2
	v_lshlrev_b64 v[2:3], 12, v[2:3]
	v_lshl_add_u64 v[2:3], v[78:79], 0, v[2:3]
	global_store_dwordx4 v[2:3], v[10:13], off nt
	s_cbranch_scc1 .LBB0_468
; #define LBAR() do { asm volatile("s_waitcnt lgkmcnt(0)" ::: "memory"); __builtin_amdgcn_s_barrier(); asm volatile("" ::: "memory"); } while (0)
; __device__ __forceinline__ void retc_stream(const int wv, LAS unsigned char* lds, unsigned ldsb, const float* __restrict__ gn_g, const float* __restrict__ gn_b, const bf16_t* __restrict__ qkvr, const bf16_t* __restrict__ grb, const bf16_t* __restrict__ kv, ...
;     ...
;         if (inext >= count) break;
;         LBAR();
;         RETC_ISSUE(inext, 0);
;         item = inext;
	s_and_b32 s1, s60, 0x1f80
	s_and_b32 s0, s61, 0xffffff00
	s_mulk_i32 s1, 0x4400
	s_add_u32 s2, s82, s1
	s_addc_u32 s3, s39, 0
	s_ashr_i32 s1, s0, 31
	s_lshl_b64 s[0:1], s[0:1], 1
	s_add_u32 s0, s2, s0
	s_addc_u32 s1, s3, s1
	v_lshl_add_u64 v[2:3], s[0:1], 0, v[180:181]
	s_mov_b64 s[0:1], 0x2400
	s_mov_b32 m0, s58
	s_waitcnt lgkmcnt(0)
	s_barrier
	v_lshl_add_u64 v[4:5], v[2:3], 0, s[0:1]
	s_mov_b64 s[0:1], 0x46400
	global_load_lds_dwordx4 v[4:5], off nt
	v_lshl_add_u64 v[4:5], v[2:3], 0, s[0:1]
	s_mov_b32 m0, s47
	s_mov_b64 s[0:1], 0x8a400
	global_load_lds_dwordx4 v[4:5], off nt
	v_lshl_add_u64 v[4:5], v[2:3], 0, s[0:1]
	s_mov_b32 m0, s24
	s_mov_b64 s[0:1], 0xce400
	global_load_lds_dwordx4 v[4:5], off nt
	v_lshl_add_u64 v[4:5], v[2:3], 0, s[0:1]
	s_mov_b32 m0, s25
	s_mov_b64 s[0:1], 0x112400
	global_load_lds_dwordx4 v[4:5], off nt
	v_lshl_add_u64 v[4:5], v[2:3], 0, s[0:1]
	s_mov_b32 m0, s48
	s_mov_b64 s[0:1], 0x156400
	global_load_lds_dwordx4 v[4:5], off nt
	v_lshl_add_u64 v[4:5], v[2:3], 0, s[0:1]
	s_mov_b32 m0, s49
	s_mov_b64 s[0:1], 0x19a400
	global_load_lds_dwordx4 v[4:5], off nt
	v_lshl_add_u64 v[4:5], v[2:3], 0, s[0:1]
	s_mov_b32 m0, s50
	s_mov_b64 s[0:1], 0x1de400
	global_load_lds_dwordx4 v[4:5], off nt
	v_lshl_add_u64 v[2:3], v[2:3], 0, s[0:1]
	s_mov_b32 m0, s51
	v_readlane_b32 s0, v253, 62
	global_load_lds_dwordx4 v[2:3], off nt
	v_readlane_b32 s1, v253, 63
	s_nop 1
	v_lshl_add_u64 v[182:183], v[182:183], 0, s[0:1]
	v_readlane_b32 s0, v253, 55
	s_add_i32 s61, s61, s0
	v_readlane_b32 s0, v253, 57
	s_add_i32 s60, s60, s0
	s_mov_b64 s[0:1], 0
	s_branch .LBB0_468

; __device__ __forceinline__ unsigned cvt_pk_bf16(float lo, float hi) { unsigned r; asm volatile("v_cvt_pk_bf16_f32 %0, %1, %2" : "=v"(r) : "v"(lo), "v"(hi)); return r; }
; __device__ __forceinline__ float bflo(unsigned u) { return __uint_as_float(u << 16); }
; __device__ __forceinline__ float bfhi(unsigned u) { return __uint_as_float(u & 0xffff0000u); }
; __device__ __forceinline__ void attn_combine(const int wv, const bf16_t* __restrict__ og, const float* __restrict__ lse, bf16_t* __restrict__ oa  ) {
;     ...
;     for (int idx0 = blockIdx.x * 512 + tc_; idx0 < TB * 64; idx0 += 4 * stride) {
;         float l[4][3]; u32x4 v[4][3];
; #pragma unroll
;         for (int q = 0; q < 4; ++q) {
;             const int idx = idx0 + q * stride;
;             if (idx < TB * 64) {
;                 const int tok = idx >> 6, hs = (idx >> 4) & 3, c = idx & 15;
; #pragma unroll
;                 for (int gi = 0; gi < 3; ++gi) { l[q][gi] = lse[tok * 12 + 4 * gi + hs]; v[q][gi] = *(const u32x4*)(og + (size_t)tok * 1536 + (4 * gi + hs) * 128 + c * 8); }
;             }
;         }
; #pragma unroll
;         for (int q = 0; q < 4; ++q) {
;             const int idx = idx0 + q * stride;
;             if (idx < TB * 64) {
;                 const int tok = idx >> 6, hs = (idx >> 4) & 3, c = idx & 15;
;                 const float m = fmaxf(l[q][0], fmaxf(l[q][1], l[q][2]));
;                 float a0 = __expf(l[q][0] - m), a1 = __expf(l[q][1] - m), a2 = __expf(l[q][2] - m);
;                 const float inv = __builtin_amdgcn_rcpf(a0 + a1 + a2); a0 *= inv; a1 *= inv; a2 *= inv;
;                 const u32x4 v0 = v[q][0], v1 = v[q][1], v2 = v[q][2];
;                 u32x4 o;
;                 o.x = cvt_pk_bf16(a0 * bflo(v0.x) + a1 * bflo(v1.x) + a2 * bflo(v2.x), a0 * bfhi(v0.x) + a1 * bfhi(v1.x) + a2 * bfhi(v2.x));
;                 o.y = cvt_pk_bf16(a0 * bflo(v0.y) + a1 * bflo(v1.y) + a2 * bflo(v2.y), a0 * bfhi(v0.y) + a1 * bfhi(v1.y) + a2 * bfhi(v2.y));
;                 o.z = cvt_pk_bf16(a0 * bflo(v0.z) + a1 * bflo(v1.z) + a2 * bflo(v2.z), a0 * bfhi(v0.z) + a1 * bfhi(v1.z) + a2 * bfhi(v2.z));
;                 o.w = cvt_pk_bf16(a0 * bflo(v0.w) + a1 * bflo(v1.w) + a2 * bflo(v2.w), a0 * bfhi(v0.w) + a1 * bfhi(v1.w) + a2 * bfhi(v2.w));
;                 *(u32x4*)(oa + (size_t)tok * 512 + hs * 128 + c * 8) = o;
.LBB0_507:
	v_and_b32_e32 v38, 0x78, v1
	v_ashrrev_i32_e32 v58, 6, v50
	v_bfe_u32 v57, v50, 4, 2
	v_lshlrev_b32_e32 v54, 1, v38
	v_mul_lo_u32 v38, v58, 12
	v_mov_b32_e32 v55, v0
	v_or_b32_e32 v38, v38, v57
	v_lshl_add_u64 v[60:61], s[6:7], 0, v[54:55]
	v_ashrrev_i32_e32 v39, 31, v38
	v_mad_i64_i32 v[40:41], s[0:1], v58, s92, v[60:61]
	v_lshl_add_u64 v[42:43], v[38:39], 2, s[8:9]
	v_lshlrev_b32_e32 v38, 8, v57
	v_mov_b32_e32 v39, v0
	v_lshl_add_u64 v[44:45], v[40:41], 0, v[38:39]
	global_load_dword v55, v[42:43], off nt
	global_load_dwordx4 v[38:41], v[44:45], off nt
	global_load_dword v53, v[42:43], off offset:16 nt
	global_load_dword v51, v[42:43], off offset:32 nt
	global_load_dwordx4 v[46:49], v[44:45], off offset:1024 nt
	s_nop 0
	global_load_dwordx4 v[42:45], v[44:45], off offset:2048 nt
	v_lshlrev_b32_e32 v52, 7, v57
	v_add_u32_e32 v73, s68, v50
	v_cmp_gt_i32_e64 s[2:3], s78, v73
	v_ashrrev_i32_e32 v56, 6, v73
	v_lshlrev_b32_e32 v62, 1, v52
	s_and_saveexec_b64 s[0:1], s[2:3]
	s_cbranch_execz .LBB0_509
	v_mul_lo_u32 v18, v56, 12
	v_or_b32_e32 v18, v18, v57
	v_mad_i64_i32 v[20:21], s[14:15], v56, s92, v[60:61]
	v_ashrrev_i32_e32 v19, 31, v18
	v_mov_b32_e32 v63, v0
	v_lshl_add_u64 v[30:31], v[18:19], 2, s[8:9]
	v_lshl_add_u64 v[32:33], v[20:21], 0, v[62:63]
	global_load_dword v70, v[30:31], off nt
	global_load_dwordx4 v[18:21], v[32:33], off nt
	global_load_dword v71, v[30:31], off offset:16 nt
	global_load_dword v72, v[30:31], off offset:32 nt
	global_load_dwordx4 v[34:37], v[32:33], off offset:1024 nt
	s_nop 0
	global_load_dwordx4 v[30:33], v[32:33], off offset:2048 nt
.LBB0_509:
	s_or_b64 exec, exec, s[0:1]
	v_add_u32_e32 v52, s31, v50
	v_cmp_gt_i32_e64 s[0:1], s78, v52
	v_ashrrev_i32_e32 v52, 6, v52
	s_and_saveexec_b64 s[14:15], s[0:1]
	s_cbranch_execz .LBB0_511
	v_mul_lo_u32 v6, v52, 12
	v_or_b32_e32 v6, v6, v57
	v_mad_i64_i32 v[8:9], s[16:17], v52, s92, v[60:61]
	v_ashrrev_i32_e32 v7, 31, v6
	v_mov_b32_e32 v63, v0
	v_lshl_add_u64 v[22:23], v[6:7], 2, s[8:9]
	v_lshl_add_u64 v[24:25], v[8:9], 0, v[62:63]
	global_load_dword v67, v[22:23], off nt
	global_load_dwordx4 v[6:9], v[24:25], off nt
	global_load_dword v68, v[22:23], off offset:16 nt
	global_load_dword v69, v[22:23], off offset:32 nt
	global_load_dwordx4 v[26:29], v[24:25], off offset:1024 nt
	s_nop 0
	global_load_dwordx4 v[22:25], v[24:25], off offset:2048 nt
.LBB0_511:
	s_or_b64 exec, exec, s[14:15]
	s_mul_i32 s14, s54, 0x600
	v_add_u32_e32 v50, s14, v50
	v_cmp_gt_i32_e32 vcc, s78, v50
	v_ashrrev_i32_e32 v50, 6, v50
	s_and_saveexec_b64 s[14:15], vcc
	s_cbranch_execz .LBB0_513
	v_mul_lo_u32 v2, v50, 12
	v_or_b32_e32 v2, v2, v57
	v_mad_i64_i32 v[4:5], s[16:17], v50, s92, v[60:61]
	v_ashrrev_i32_e32 v3, 31, v2
	v_mov_b32_e32 v63, v0
	v_lshl_add_u64 v[10:11], v[2:3], 2, s[8:9]
	v_lshl_add_u64 v[12:13], v[4:5], 0, v[62:63]
	global_load_dword v64, v[10:11], off nt
	global_load_dwordx4 v[2:5], v[12:13], off nt
	global_load_dword v65, v[10:11], off offset:16 nt
	global_load_dword v66, v[10:11], off offset:32 nt
	global_load_dwordx4 v[14:17], v[12:13], off offset:1024 nt
	s_nop 0
	global_load_dwordx4 v[10:13], v[12:13], off offset:2048 nt
.LBB0_513:
	s_or_b64 exec, exec, s[14:15]
	s_waitcnt vmcnt(2)
	v_max3_f32 v60, v55, v53, v51
	v_sub_f32_e32 v55, v55, v60
	v_sub_f32_e32 v53, v53, v60
	v_mul_f32_e32 v55, 0x3fb8aa3b, v55
	v_mul_f32_e32 v53, 0x3fb8aa3b, v53
	v_sub_f32_e32 v51, v51, v60
	v_exp_f32_e32 v61, v55
	v_exp_f32_e32 v53, v53
	v_mul_f32_e32 v51, 0x3fb8aa3b, v51
	v_exp_f32_e32 v60, v51
	v_and_b32_e32 v57, 0x180, v1
	v_add_f32_e32 v51, v61, v53
	v_lshlrev_b32_e32 v62, 1, v57
	v_add_f32_e32 v51, v60, v51
	v_rcp_f32_e32 v74, v51
	v_mov_b32_e32 v63, v0
	v_lshl_add_u64 v[62:63], s[10:11], 0, v[62:63]
	v_mov_b32_e32 v55, v0
	s_waitcnt vmcnt(1)
	v_lshlrev_b32_e32 v75, 16, v48
	v_lshl_add_u64 v[54:55], v[62:63], 0, v[54:55]
	v_mul_f32_e32 v51, v53, v74
	v_lshlrev_b32_e32 v53, 16, v46
	v_and_b32_e32 v57, 0xffff0000, v46
	v_lshlrev_b32_e32 v62, 16, v47
	v_and_b32_e32 v63, 0xffff0000, v47
	v_pk_mul_f32 v[46:47], v[60:61], v[74:75] op_sel_hi:[1,0]
	v_lshlrev_b32_e32 v61, 16, v38
	s_waitcnt vmcnt(0)
	v_lshlrev_b32_e32 v60, 16, v42
	v_pk_mul_f32 v[60:61], v[46:47], v[60:61]
	v_and_b32_e32 v48, 0xffff0000, v48
	v_fma_f32 v53, v51, v53, v61
	v_add_f32_e32 v53, v60, v53
	v_and_b32_e32 v61, 0xffff0000, v38
	v_and_b32_e32 v60, 0xffff0000, v42
	v_pk_mul_f32 v[60:61], v[46:47], v[60:61]
	v_lshlrev_b32_e32 v76, 16, v49
	v_fma_f32 v38, v51, v57, v61
	v_add_f32_e32 v38, v60, v38
	v_lshlrev_b32_e32 v61, 16, v39
	v_lshlrev_b32_e32 v60, 16, v43
	v_pk_mul_f32 v[60:61], v[46:47], v[60:61]
	v_cvt_pk_bf16_f32 v38, v53, v38
	v_ashrrev_i32_e32 v59, 31, v58
	v_fma_f32 v42, v51, v62, v61
	v_add_f32_e32 v53, v60, v42
	v_and_b32_e32 v61, 0xffff0000, v39
	v_and_b32_e32 v60, 0xffff0000, v43
	v_pk_mul_f32 v[42:43], v[46:47], v[60:61]
	s_nop 0
	v_fma_f32 v39, v51, v63, v43
	v_add_f32_e32 v39, v42, v39
	v_lshlrev_b32_e32 v43, 16, v40
	v_lshlrev_b32_e32 v42, 16, v44
	v_pk_mul_f32 v[42:43], v[46:47], v[42:43]
	v_cvt_pk_bf16_f32 v39, v53, v39
	s_nop 0
	v_fma_f32 v43, v51, v75, v43
	v_add_f32_e32 v53, v42, v43
	v_and_b32_e32 v43, 0xffff0000, v40
	v_and_b32_e32 v42, 0xffff0000, v44
	v_pk_mul_f32 v[42:43], v[46:47], v[42:43]
	s_nop 0
	v_fma_f32 v40, v51, v48, v43
	v_add_f32_e32 v40, v42, v40
	v_lshlrev_b32_e32 v43, 16, v41
	v_lshlrev_b32_e32 v42, 16, v45
	v_pk_mul_f32 v[42:43], v[46:47], v[42:43]
	v_and_b32_e32 v48, 0xffff0000, v49
	v_fma_f32 v43, v51, v76, v43
	v_add_f32_e32 v44, v42, v43
	v_and_b32_e32 v43, 0xffff0000, v41
	v_and_b32_e32 v42, 0xffff0000, v45
	v_pk_mul_f32 v[42:43], v[46:47], v[42:43]
	v_cvt_pk_bf16_f32 v40, v53, v40
	s_nop 0
	v_fma_f32 v41, v51, v48, v43
	v_add_f32_e32 v41, v42, v41
	v_lshlrev_b64 v[42:43], 10, v[58:59]
	v_lshl_add_u64 v[42:43], v[54:55], 0, v[42:43]
	v_cvt_pk_bf16_f32 v41, v44, v41
	global_store_dwordx4 v[42:43], v[38:41], off nt
	s_and_saveexec_b64 s[14:15], s[2:3]
	s_cbranch_execnz .LBB0_516
	s_or_b64 exec, exec, s[14:15]
	s_and_saveexec_b64 s[2:3], s[0:1]
	s_cbranch_execnz .LBB0_517

; __device__ __forceinline__ unsigned cvt_pk_bf16(float lo, float hi) { unsigned r; asm volatile("v_cvt_pk_bf16_f32 %0, %1, %2" : "=v"(r) : "v"(lo), "v"(hi)); return r; }
; __device__ __forceinline__ float bflo(unsigned u) { return __uint_as_float(u << 16); }
; __device__ __forceinline__ float bfhi(unsigned u) { return __uint_as_float(u & 0xffff0000u); }
; __device__ __forceinline__ void attn_combine(const int wv, const bf16_t* __restrict__ og, const float* __restrict__ lse, bf16_t* __restrict__ oa  ) {
;     ...
;         for (int q = 0; q < 4; ++q) {
;             const int idx = idx0 + q * stride;
;             if (idx < TB * 64) {
;                 const int tok = idx >> 6, hs = (idx >> 4) & 3, c = idx & 15;
;                 const float m = fmaxf(l[q][0], fmaxf(l[q][1], l[q][2]));
;                 float a0 = __expf(l[q][0] - m), a1 = __expf(l[q][1] - m), a2 = __expf(l[q][2] - m);
;                 const float inv = __builtin_amdgcn_rcpf(a0 + a1 + a2); a0 *= inv; a1 *= inv; a2 *= inv;
;                 const u32x4 v0 = v[q][0], v1 = v[q][1], v2 = v[q][2];
;                 u32x4 o;
;                 o.x = cvt_pk_bf16(a0 * bflo(v0.x) + a1 * bflo(v1.x) + a2 * bflo(v2.x), a0 * bfhi(v0.x) + a1 * bfhi(v1.x) + a2 * bfhi(v2.x));
;                 o.y = cvt_pk_bf16(a0 * bflo(v0.y) + a1 * bflo(v1.y) + a2 * bflo(v2.y), a0 * bfhi(v0.y) + a1 * bfhi(v1.y) + a2 * bfhi(v2.y));
;                 o.z = cvt_pk_bf16(a0 * bflo(v0.z) + a1 * bflo(v1.z) + a2 * bflo(v2.z), a0 * bfhi(v0.z) + a1 * bfhi(v1.z) + a2 * bfhi(v2.z));
;                 o.w = cvt_pk_bf16(a0 * bflo(v0.w) + a1 * bflo(v1.w) + a2 * bflo(v2.w), a0 * bfhi(v0.w) + a1 * bfhi(v1.w) + a2 * bfhi(v2.w));
;                 *(u32x4*)(oa + (size_t)tok * 512 + hs * 128 + c * 8) = o;
.LBB0_516:
	v_max3_f32 v38, v70, v71, v72
	v_sub_f32_e32 v39, v70, v38
	v_sub_f32_e32 v40, v71, v38
	v_mul_f32_e32 v39, 0x3fb8aa3b, v39
	v_mul_f32_e32 v40, 0x3fb8aa3b, v40
	v_sub_f32_e32 v38, v72, v38
	v_exp_f32_e32 v39, v39
	v_exp_f32_e32 v41, v40
	v_mul_f32_e32 v38, 0x3fb8aa3b, v38
	v_exp_f32_e32 v38, v38
	v_and_b32_e32 v44, 0xffff0000, v34
	v_add_f32_e32 v40, v39, v41
	v_lshlrev_b32_e32 v45, 16, v35
	v_add_f32_e32 v40, v38, v40
	v_rcp_f32_e32 v40, v40
	v_and_b32_e32 v47, 0xffff0000, v35
	v_lshlrev_b32_e32 v48, 16, v36
	v_and_b32_e32 v49, 0xffff0000, v36
	v_mul_f32_e32 v46, v41, v40
	v_lshlrev_b32_e32 v41, 16, v34
	v_pk_mul_f32 v[42:43], v[38:39], v[40:41] op_sel_hi:[1,0]
	v_lshlrev_b32_e32 v39, 16, v18
	v_lshlrev_b32_e32 v38, 16, v30
	v_pk_mul_f32 v[38:39], v[42:43], v[38:39]
	v_lshlrev_b32_e32 v51, 16, v37
	v_fma_f32 v39, v46, v41, v39
	v_add_f32_e32 v40, v38, v39
	v_and_b32_e32 v39, 0xffff0000, v18
	v_and_b32_e32 v38, 0xffff0000, v30
	v_pk_mul_f32 v[38:39], v[42:43], v[38:39]
	v_lshlrev_b32_e32 v41, 16, v19
	v_fma_f32 v39, v46, v44, v39
	v_add_f32_e32 v38, v38, v39
	v_cvt_pk_bf16_f32 v38, v40, v38
	v_lshlrev_b32_e32 v40, 16, v31
	v_pk_mul_f32 v[40:41], v[42:43], v[40:41]
	v_ashrrev_i32_e32 v57, 31, v56
	v_fma_f32 v39, v46, v45, v41
	v_add_f32_e32 v39, v40, v39
	v_and_b32_e32 v41, 0xffff0000, v19
	v_and_b32_e32 v40, 0xffff0000, v31
	v_pk_mul_f32 v[40:41], v[42:43], v[40:41]
	v_lshlrev_b32_e32 v45, 16, v21
	v_fma_f32 v41, v46, v47, v41
	v_add_f32_e32 v40, v40, v41
	v_cvt_pk_bf16_f32 v39, v39, v40
	v_lshlrev_b32_e32 v41, 16, v20
	v_lshlrev_b32_e32 v40, 16, v32
	v_pk_mul_f32 v[40:41], v[42:43], v[40:41]
	v_and_b32_e32 v47, 0xffff0000, v37
	v_fma_f32 v41, v46, v48, v41
	v_add_f32_e32 v44, v40, v41
	v_and_b32_e32 v41, 0xffff0000, v20
	v_and_b32_e32 v40, 0xffff0000, v32
	v_pk_mul_f32 v[40:41], v[42:43], v[40:41]
	s_nop 0
	v_fma_f32 v41, v46, v49, v41
	v_add_f32_e32 v40, v40, v41
	v_cvt_pk_bf16_f32 v40, v44, v40
	v_lshlrev_b32_e32 v44, 16, v33
	v_pk_mul_f32 v[44:45], v[42:43], v[44:45]
	s_nop 0
	v_fma_f32 v41, v46, v51, v45
	v_add_f32_e32 v41, v44, v41
	v_and_b32_e32 v45, 0xffff0000, v21
	v_and_b32_e32 v44, 0xffff0000, v33
	v_pk_mul_f32 v[42:43], v[42:43], v[44:45]
	s_nop 0
	v_fma_f32 v43, v46, v47, v43
	v_add_f32_e32 v42, v42, v43
	v_cvt_pk_bf16_f32 v41, v41, v42
	v_lshlrev_b64 v[42:43], 10, v[56:57]
	v_lshl_add_u64 v[42:43], v[54:55], 0, v[42:43]
	global_store_dwordx4 v[42:43], v[38:41], off nt
	s_or_b64 exec, exec, s[14:15]
	s_and_saveexec_b64 s[2:3], s[0:1]
	s_cbranch_execz .LBB0_515
; __device__ __forceinline__ unsigned cvt_pk_bf16(float lo, float hi) { unsigned r; asm volatile("v_cvt_pk_bf16_f32 %0, %1, %2" : "=v"(r) : "v"(lo), "v"(hi)); return r; }
; __device__ __forceinline__ float bflo(unsigned u) { return __uint_as_float(u << 16); }
; __device__ __forceinline__ float bfhi(unsigned u) { return __uint_as_float(u & 0xffff0000u); }
; __device__ __forceinline__ void attn_combine(const int wv, const bf16_t* __restrict__ og, const float* __restrict__ lse, bf16_t* __restrict__ oa  ) {
;     ...
;         for (int q = 0; q < 4; ++q) {
;             const int idx = idx0 + q * stride;
;             if (idx < TB * 64) {
;                 const int tok = idx >> 6, hs = (idx >> 4) & 3, c = idx & 15;
;                 const float m = fmaxf(l[q][0], fmaxf(l[q][1], l[q][2]));
;                 float a0 = __expf(l[q][0] - m), a1 = __expf(l[q][1] - m), a2 = __expf(l[q][2] - m);
;                 const float inv = __builtin_amdgcn_rcpf(a0 + a1 + a2); a0 *= inv; a1 *= inv; a2 *= inv;
;                 const u32x4 v0 = v[q][0], v1 = v[q][1], v2 = v[q][2];
;                 u32x4 o;
;                 o.x = cvt_pk_bf16(a0 * bflo(v0.x) + a1 * bflo(v1.x) + a2 * bflo(v2.x), a0 * bfhi(v0.x) + a1 * bfhi(v1.x) + a2 * bfhi(v2.x));
;                 o.y = cvt_pk_bf16(a0 * bflo(v0.y) + a1 * bflo(v1.y) + a2 * bflo(v2.y), a0 * bfhi(v0.y) + a1 * bfhi(v1.y) + a2 * bfhi(v2.y));
;                 o.z = cvt_pk_bf16(a0 * bflo(v0.z) + a1 * bflo(v1.z) + a2 * bflo(v2.z), a0 * bfhi(v0.z) + a1 * bfhi(v1.z) + a2 * bfhi(v2.z));
;                 o.w = cvt_pk_bf16(a0 * bflo(v0.w) + a1 * bflo(v1.w) + a2 * bflo(v2.w), a0 * bfhi(v0.w) + a1 * bfhi(v1.w) + a2 * bfhi(v2.w));
;                 *(u32x4*)(oa + (size_t)tok * 512 + hs * 128 + c * 8) = o;
.LBB0_517:
	v_max3_f32 v38, v67, v68, v69
	v_sub_f32_e32 v39, v67, v38
	v_sub_f32_e32 v40, v68, v38
	v_mul_f32_e32 v39, 0x3fb8aa3b, v39
	v_mul_f32_e32 v40, 0x3fb8aa3b, v40
	v_sub_f32_e32 v38, v69, v38
	v_exp_f32_e32 v39, v39
	v_exp_f32_e32 v41, v40
	v_mul_f32_e32 v38, 0x3fb8aa3b, v38
	v_exp_f32_e32 v38, v38
	v_and_b32_e32 v44, 0xffff0000, v26
	v_add_f32_e32 v40, v39, v41
	v_lshlrev_b32_e32 v45, 16, v27
	v_add_f32_e32 v40, v38, v40
	v_rcp_f32_e32 v40, v40
	v_and_b32_e32 v47, 0xffff0000, v27
	v_lshlrev_b32_e32 v48, 16, v28
	v_and_b32_e32 v49, 0xffff0000, v28
	v_mul_f32_e32 v46, v41, v40
	v_lshlrev_b32_e32 v41, 16, v26
	v_pk_mul_f32 v[42:43], v[38:39], v[40:41] op_sel_hi:[1,0]
	v_lshlrev_b32_e32 v39, 16, v6
	v_lshlrev_b32_e32 v38, 16, v22
	v_pk_mul_f32 v[38:39], v[42:43], v[38:39]
	v_lshlrev_b32_e32 v51, 16, v29
	v_fma_f32 v39, v46, v41, v39
	v_add_f32_e32 v40, v38, v39
	v_and_b32_e32 v39, 0xffff0000, v6
	v_and_b32_e32 v38, 0xffff0000, v22
	v_pk_mul_f32 v[38:39], v[42:43], v[38:39]
	v_lshlrev_b32_e32 v41, 16, v7
	v_fma_f32 v39, v46, v44, v39
	v_add_f32_e32 v38, v38, v39
	v_cvt_pk_bf16_f32 v38, v40, v38
	v_lshlrev_b32_e32 v40, 16, v23
	v_pk_mul_f32 v[40:41], v[42:43], v[40:41]
	v_ashrrev_i32_e32 v53, 31, v52
	v_fma_f32 v39, v46, v45, v41
	v_add_f32_e32 v39, v40, v39
	v_and_b32_e32 v41, 0xffff0000, v7
	v_and_b32_e32 v40, 0xffff0000, v23
	v_pk_mul_f32 v[40:41], v[42:43], v[40:41]
	v_lshlrev_b32_e32 v45, 16, v9
	v_fma_f32 v41, v46, v47, v41
	v_add_f32_e32 v40, v40, v41
	v_cvt_pk_bf16_f32 v39, v39, v40
	v_lshlrev_b32_e32 v41, 16, v8
	v_lshlrev_b32_e32 v40, 16, v24
	v_pk_mul_f32 v[40:41], v[42:43], v[40:41]
	v_and_b32_e32 v47, 0xffff0000, v29
	v_fma_f32 v41, v46, v48, v41
	v_add_f32_e32 v44, v40, v41
	v_and_b32_e32 v41, 0xffff0000, v8
	v_and_b32_e32 v40, 0xffff0000, v24
	v_pk_mul_f32 v[40:41], v[42:43], v[40:41]
	s_nop 0
	v_fma_f32 v41, v46, v49, v41
	v_add_f32_e32 v40, v40, v41
	v_cvt_pk_bf16_f32 v40, v44, v40
	v_lshlrev_b32_e32 v44, 16, v25
	v_pk_mul_f32 v[44:45], v[42:43], v[44:45]
	s_nop 0
	v_fma_f32 v41, v46, v51, v45
	v_add_f32_e32 v41, v44, v41
	v_and_b32_e32 v45, 0xffff0000, v9
	v_and_b32_e32 v44, 0xffff0000, v25
	v_pk_mul_f32 v[42:43], v[42:43], v[44:45]
	s_nop 0
	v_fma_f32 v43, v46, v47, v43
	v_add_f32_e32 v42, v42, v43
	v_cvt_pk_bf16_f32 v41, v41, v42
	v_lshlrev_b64 v[42:43], 10, v[52:53]
	v_lshl_add_u64 v[42:43], v[54:55], 0, v[42:43]
	global_store_dwordx4 v[42:43], v[38:41], off nt
	s_or_b64 exec, exec, s[2:3]
	s_and_saveexec_b64 s[0:1], vcc
	s_cbranch_execz .LBB0_506
.LBB0_518:
	v_max3_f32 v38, v64, v65, v66
	v_sub_f32_e32 v39, v64, v38
	v_sub_f32_e32 v40, v65, v38
	v_mul_f32_e32 v39, 0x3fb8aa3b, v39
	v_mul_f32_e32 v40, 0x3fb8aa3b, v40
	v_sub_f32_e32 v38, v66, v38
	v_exp_f32_e32 v39, v39
	v_exp_f32_e32 v41, v40
	v_mul_f32_e32 v38, 0x3fb8aa3b, v38
	v_exp_f32_e32 v38, v38
	v_and_b32_e32 v44, 0xffff0000, v14
	v_add_f32_e32 v40, v39, v41
	v_lshlrev_b32_e32 v45, 16, v15
	v_add_f32_e32 v40, v38, v40
	v_rcp_f32_e32 v40, v40
	v_and_b32_e32 v47, 0xffff0000, v15
	v_lshlrev_b32_e32 v48, 16, v16
	v_and_b32_e32 v49, 0xffff0000, v16
	v_mul_f32_e32 v46, v41, v40
	v_lshlrev_b32_e32 v41, 16, v14
	v_pk_mul_f32 v[42:43], v[38:39], v[40:41] op_sel_hi:[1,0]
	v_lshlrev_b32_e32 v39, 16, v2
	v_lshlrev_b32_e32 v38, 16, v10
	v_pk_mul_f32 v[38:39], v[42:43], v[38:39]
	v_lshlrev_b32_e32 v51, 16, v17
	v_fma_f32 v39, v46, v41, v39
	v_add_f32_e32 v40, v38, v39
	v_and_b32_e32 v39, 0xffff0000, v2
	v_and_b32_e32 v38, 0xffff0000, v10
	v_pk_mul_f32 v[38:39], v[42:43], v[38:39]
	v_lshlrev_b32_e32 v41, 16, v3
	v_fma_f32 v39, v46, v44, v39
	v_add_f32_e32 v38, v38, v39
	v_cvt_pk_bf16_f32 v38, v40, v38
	v_lshlrev_b32_e32 v40, 16, v11
	v_pk_mul_f32 v[40:41], v[42:43], v[40:41]
	s_nop 0
	v_fma_f32 v39, v46, v45, v41
	v_add_f32_e32 v39, v40, v39
	v_and_b32_e32 v41, 0xffff0000, v3
	v_and_b32_e32 v40, 0xffff0000, v11
	v_pk_mul_f32 v[40:41], v[42:43], v[40:41]
	v_lshlrev_b32_e32 v45, 16, v5
	v_fma_f32 v41, v46, v47, v41
	v_add_f32_e32 v40, v40, v41
	v_cvt_pk_bf16_f32 v39, v39, v40
	v_lshlrev_b32_e32 v41, 16, v4
	v_lshlrev_b32_e32 v40, 16, v12
	v_pk_mul_f32 v[40:41], v[42:43], v[40:41]
	v_and_b32_e32 v47, 0xffff0000, v17
	v_fma_f32 v41, v46, v48, v41
	v_add_f32_e32 v44, v40, v41
	v_and_b32_e32 v41, 0xffff0000, v4
	v_and_b32_e32 v40, 0xffff0000, v12
	v_pk_mul_f32 v[40:41], v[42:43], v[40:41]
	s_nop 0
	v_fma_f32 v41, v46, v49, v41
	v_add_f32_e32 v40, v40, v41
	v_cvt_pk_bf16_f32 v40, v44, v40
	v_lshlrev_b32_e32 v44, 16, v13
	v_pk_mul_f32 v[44:45], v[42:43], v[44:45]
	s_nop 0
	v_fma_f32 v41, v46, v51, v45
	v_add_f32_e32 v41, v44, v41
	v_and_b32_e32 v45, 0xffff0000, v5
	v_and_b32_e32 v44, 0xffff0000, v13
	v_pk_mul_f32 v[42:43], v[42:43], v[44:45]
	v_ashrrev_i32_e32 v51, 31, v50
	v_fma_f32 v43, v46, v47, v43
	v_add_f32_e32 v42, v42, v43
	v_cvt_pk_bf16_f32 v41, v41, v42
	v_lshlrev_b64 v[42:43], 10, v[50:51]
	v_lshl_add_u64 v[42:43], v[54:55], 0, v[42:43]
	global_store_dwordx4 v[42:43], v[38:41], off nt
	s_branch .LBB0_506

;     __device__ bool next(int i, Unit& u) const {
;         const long L = (long)i * G + c; if (L >= nwg) return false;
;         int wgid = (int)L; { const int q = nwg / NXCD, r = nwg % NXCD, xcd = wgid % NXCD, off = wgid / NXCD; wgid = (xcd < r ? xcd * (q + 1) : r * (q + 1) + (xcd - r) * q) + off; }
;         const int nig = WGM * nN, gid = wgid / nig, fm = gid * WGM, gsz = (nM - fm) < WGM ? (nM - fm) : WGM;
;         u.pm = fm + ((wgid % nig) % gsz); u.pn = (wgid % nig) / gsz; return true;
; template <class Epi, class Sched>
; __device__ __forceinline__ void gemm_phase(const int wv, LAS unsigned char* lds, const Gemm g, const Sched& S, const Epi& E) {
;     ...
;     for (int i = 0; i < 2; ++i) { int R, C; stage_rc(tid * 16 + i * 8192, R, C); const int Rb = Epi::PERM ? ((R & ~31) + perm32(R & 31)) : R;
;         voffA[i] = (unsigned)(R * (g.atile ? BK : g.lda) + C) * 2u; voffB[i] = (unsigned)(Rb * g.ldb + C) * 2u; }
;     const size_t kstep = (size_t)(BK * 2);
;     const int ldaE = g.atile ? BK : g.lda;
;     const size_t kstepA = g.atile ? (size_t)BM * BK * 2 : kstep;
;     const size_t hstepA = (size_t)HALF * ldaE * 2, hstepB = (size_t)HALF * g.ldb * 2;
;     const size_t tstepA = g.atile ? (size_t)(g.K / BK) * BM * BK * 2 : 2 * hstepA, tstepB = 2 * hstepB;
;     const unsigned ldsw = (unsigned)wid * 1024u;
;     const int aoff = lds_byte(wr * 64 + fr, fq * 8), boff = lds_byte(wc * 32 + fr, fq * 8);
;     ...
;     Unit cur, nxt; int ui = 0;
;     if (!S.next(0, cur)) return;
;     f32x4 acc[2][2][4][2];
; #pragma unroll
;     for (int a = 0; a < 2; ++a)
; #pragma unroll
;         for (int b = 0; b < 2; ++b)
; #pragma unroll
;             for (int m = 0; m < 4; ++m)
; #pragma unroll
;                 for (int n = 0; n < 2; ++n) acc[a][b][m][n] = (f32x4){0.f, 0.f, 0.f, 0.f};
;     bf16x8 At[4][2], B0[2][2], B1[2][2];
;     const char* cA = (const char*)g.A + (size_t)cur.pm * tstepA; const char* cB = (const char*)g.Bt + (size_t)cur.pn * tstepB;
;     S.a_ready(cur);
;     PG8_STAGE(PG8_SB(0, 0), cB, voffB); PG8_STAGE(PG8_SA(0, 0), cA, voffA); PG8_STAGE(PG8_SB(0, 1), cB + hstepB, voffB); PG8_STAGE(PG8_SA(0, 1), cA + hstepA, voffA);
;     if (wr == 1) PG8_BAR;
;     PG8_WAIT_V(4); PG8_BAR;
;     PG8_STAGE(PG8_SB(1, 0), cB + kstep, voffB); PG8_STAGE(PG8_SA(1, 0), cA + kstepA, voffA); PG8_STAGE(PG8_SB(1, 1), cB + hstepB + kstep, voffB);
.LBB0_779:
	v_ashrrev_i32_e32 v1, 31, v4
	v_lshrrev_b32_e32 v1, 26, v1
	v_add_u32_e32 v1, v4, v1
	v_ashrrev_i32_e32 v5, 6, v1
	v_bfe_i32 v1, v4, 27, 1
	v_lshlrev_b32_e32 v0, 4, v4
	v_lshrrev_b32_e32 v1, 22, v1
	v_add_u32_e32 v1, v0, v1
	v_and_b32_e32 v1, 0xfffffc00, v1
	v_sub_u32_e32 v1, v0, v1
	v_lshrrev_b32_e32 v2, 4, v1
	v_bitop3_b32 v1, v2, v1, 32 bitop3:0x6c
	v_ashrrev_i32_e32 v3, 31, v1
	v_lshrrev_b32_e32 v3, 26, v3
	v_add_u32_e32 v3, v1, v3
	v_ashrrev_i32_e32 v6, 6, v3
	v_and_b32_e32 v3, 0xc0, v3
	v_lshlrev_b32_e32 v2, 3, v5
	v_sub_u32_e32 v1, v1, v3
	v_mov_b32_e32 v3, 1
	v_and_b32_e32 v2, -16, v2
	v_lshlrev_b32_e32 v7, 5, v5
	v_ashrrev_i16_sdwa v1, v3, sext(v1) dst_sel:DWORD dst_unused:UNUSED_PAD src0_sel:DWORD src1_sel:BYTE_0
	v_add_u32_e32 v2, v6, v2
	v_and_b32_e32 v8, 32, v7
	v_bfe_i32 v7, v1, 0, 16
	v_add_u32_e32 v1, v8, v7
	v_lshlrev_b32_e32 v8, 7, v2
	v_add_u32_e32 v0, 0x2000, v0
	v_lshl_add_u32 v128, v1, 1, v8
	v_ashrrev_i32_e32 v1, 31, v0
	v_lshrrev_b32_e32 v1, 22, v1
	v_add_u32_e32 v1, v0, v1
	v_ashrrev_i32_e32 v8, 10, v1
	v_mul_i32_i24_e32 v1, 0x400, v8
	v_sub_u32_e32 v0, v0, v1
	v_lshrrev_b32_e32 v1, 4, v0
	s_movk_i32 s0, 0x1f80
	v_bitop3_b32 v0, v1, v0, 32 bitop3:0x6c
	v_mad_u64_u32 v[130:131], s[8:9], v2, s0, v[128:129]
	v_ashrrev_i32_e32 v2, 31, v0
	v_lshrrev_b32_e32 v2, 26, v2
	v_add_u32_e32 v2, v0, v2
	v_ashrrev_i32_e32 v9, 6, v2
	v_and_b32_e32 v2, 0xc0, v2
	v_lshlrev_b32_e32 v1, 3, v8
	v_sub_u32_e32 v0, v0, v2
	v_and_b32_e32 v1, -16, v1
	v_lshlrev_b32_e32 v10, 5, v8
	v_ashrrev_i16_sdwa v0, v3, sext(v0) dst_sel:DWORD dst_unused:UNUSED_PAD src0_sel:DWORD src1_sel:BYTE_0
	s_waitcnt lgkmcnt(0)
	s_add_u32 s27, s6, 0xcc00000
	v_add_u32_e32 v1, v9, v1
	v_and_b32_e32 v11, 32, v10
	v_bfe_i32 v10, v0, 0, 16
	s_addc_u32 s28, s7, 0
	v_add_u32_e32 v0, v11, v10
	v_lshlrev_b32_e32 v2, 7, v1
	s_add_u32 s29, s6, 0x2800000
	v_lshl_add_u32 v132, v0, 1, v2
	s_addc_u32 s30, s7, 0
	v_mad_u64_u32 v[134:135], s[8:9], v1, s0, v[132:133]
	s_add_i32 s0, s2, s52
	s_ashr_i32 s2, s0, 31
	s_lshr_b32 s2, s2, 27
	s_add_i32 s2, s0, s2
	s_ashr_i32 s3, s2, 5
	s_and_b32 s2, s2, 0xffe0
	s_sub_i32 s2, s0, s2
	s_bfe_i32 s0, s2, 0x80000
	s_bfe_u32 s0, s0, 0x3000c
	s_add_i32 s9, s2, s0
	s_bfe_i32 s0, s9, 0x80000
	s_and_b32 s9, s9, 0xf8
	s_sub_i32 s2, s2, s9
	s_lshl_b32 s3, s3, 3
	s_sext_i32_i16 s0, s0
	s_sext_i32_i8 s2, s2
	s_ashr_i32 s1, s26, 8
	s_lshr_b32 s0, s0, 3
	s_add_i32 s16, s3, s2
	s_sub_i32 s16, 0x7f, s16
	s_ashr_i32 s8, s26, 6
	s_ashr_i32 s17, s16, 31
	s_bfe_i64 s[10:11], s[0:1], 0x100000
	s_lshl_b32 s31, s8, 10
	s_lshl_b64 s[2:3], s[16:17], 21
	s_lshl_b64 s[10:11], s[10:11], 21
	s_add_u32 s18, s29, s10
	s_addc_u32 s19, s30, s11
	s_add_i32 s17, s31, 0
	s_add_i32 m0, s17, 0x10000
	v_mov_b32_e32 v131, 0
	global_load_lds_dwordx4 v130, s[18:19]
	s_add_i32 m0, s17, 0x12000
	s_add_u32 s20, s27, s2
	global_load_lds_dwordx4 v134, s[18:19]
	s_addc_u32 s21, s28, s3
	s_mov_b32 m0, s17
	s_add_i32 s33, s17, 0x2000
	global_load_lds_dwordx4 v128, s[20:21]
	s_mov_b32 m0, s33
	s_add_u32 s2, s18, 0x100000
	global_load_lds_dwordx4 v132, s[20:21]
	s_addc_u32 s3, s19, 0
	s_add_i32 m0, s17, 0x14000
	v_mov_b32_e32 v135, v131
	global_load_lds_dwordx4 v130, s[2:3]
	s_add_i32 m0, s17, 0x16000
	s_mov_b32 s36, 0
	global_load_lds_dwordx4 v134, s[2:3]
	s_add_u32 s2, s20, 0x4000
	s_addc_u32 s3, s21, 0
	s_add_i32 s34, s17, 0x4000
	s_mov_b32 m0, s34
	s_add_i32 s35, s17, 0x6000
	global_load_lds_dwordx4 v128, s[2:3]
	s_mov_b32 m0, s35
	v_lshl_add_u64 v[2:3], s[18:19], 0, v[130:131]
	global_load_lds_dwordx4 v132, s[2:3]
	v_lshl_add_u64 v[0:1], s[18:19], 0, v[134:135]
	v_mov_b32_e32 v129, v131
	s_cmp_lg_u32 s1, 1
	v_mov_b32_e32 v133, v131
	s_cbranch_scc1 .LBB0_781
	s_barrier

; template <class Epi, class Sched>
; __device__ __forceinline__ void gemm_phase(const int wv, LAS unsigned char* lds, const Gemm g, const Sched& S, const Epi& E) {
;     ...
;         const bool has_next = S.next(ui + 1, nxt);
;         const char* nA = has_next ? (const char*)g.A + (size_t)nxt.pm * tstepA : cA; const char* nB = has_next ? (const char*)g.Bt + (size_t)nxt.pn * tstepB : cB;
;     ...
; #pragma unroll
;         for (int a = 0; a < 2; ++a)
; #pragma unroll
;             for (int b = 0; b < 2; ++b)
; #pragma unroll
;                 for (int m = 0; m < 4; ++m)
; #pragma unroll
;                     for (int n = 0; n < 2; ++n) acc[a][b][m][n] = (f32x4){0.f, 0.f, 0.f, 0.f};
;         cur = nxt; cA = nA; cB = nB; ++ui;
.LBB0_788:
	s_sub_i32 s10, 0x7f, s10
	s_ashr_i32 s11, s10, 31
	v_cmp_lt_i64_e32 vcc, s[12:13], v[140:141]
	s_lshl_b64 s[12:13], s[10:11], 21
	s_add_u32 s12, s27, s12
	s_addc_u32 s13, s28, s13
	s_and_b64 s[14:15], vcc, exec
	s_cselect_b32 s11, s13, s21
	s_cselect_b32 s42, s12, s20
	s_ashr_i32 s9, s8, 31
	s_lshl_b64 s[14:15], s[8:9], 21
	s_add_u32 s14, s29, s14
	s_addc_u32 s15, s30, s15
	s_and_b64 s[22:23], vcc, exec
	s_cselect_b32 s9, s15, s19
	s_cselect_b32 s43, s14, s18
	s_add_u32 s44, s18, 0x100
	s_addc_u32 s45, s19, 0
	s_add_u32 s18, s20, 0xc000
	v_mov_b32_e32 v0, 0
	s_addc_u32 s19, s21, 0
	s_mov_b32 s46, -2
	v_mov_b32_e32 v1, v0
	v_mov_b32_e32 v2, v0
	v_mov_b32_e32 v3, v0
	v_mov_b32_e32 v4, v0
	v_mov_b32_e32 v5, v0
	v_mov_b32_e32 v6, v0
	v_mov_b32_e32 v7, v0
	v_mov_b32_e32 v12, v0
	v_mov_b32_e32 v13, v0
	v_mov_b32_e32 v14, v0
	v_mov_b32_e32 v15, v0
	v_mov_b32_e32 v20, v0
	v_mov_b32_e32 v21, v0
	v_mov_b32_e32 v22, v0
	v_mov_b32_e32 v23, v0
	v_mov_b32_e32 v28, v0
	v_mov_b32_e32 v29, v0
	v_mov_b32_e32 v30, v0
	v_mov_b32_e32 v31, v0
	v_mov_b32_e32 v36, v0
	v_mov_b32_e32 v37, v0
	v_mov_b32_e32 v38, v0
	v_mov_b32_e32 v39, v0
	v_mov_b32_e32 v44, v0
	v_mov_b32_e32 v45, v0
	v_mov_b32_e32 v46, v0
	v_mov_b32_e32 v47, v0
	v_mov_b32_e32 v52, v0
	v_mov_b32_e32 v53, v0
	v_mov_b32_e32 v54, v0
	v_mov_b32_e32 v55, v0
	v_mov_b32_e32 v8, v0
	v_mov_b32_e32 v9, v0
	v_mov_b32_e32 v10, v0
	v_mov_b32_e32 v11, v0
	v_mov_b32_e32 v16, v0
	v_mov_b32_e32 v17, v0
	v_mov_b32_e32 v18, v0
	v_mov_b32_e32 v19, v0
	v_mov_b32_e32 v24, v0
	v_mov_b32_e32 v25, v0
	v_mov_b32_e32 v26, v0
	v_mov_b32_e32 v27, v0
	v_mov_b32_e32 v32, v0
	v_mov_b32_e32 v33, v0
	v_mov_b32_e32 v34, v0
	v_mov_b32_e32 v35, v0
	v_mov_b32_e32 v40, v0
	v_mov_b32_e32 v41, v0
	v_mov_b32_e32 v42, v0
	v_mov_b32_e32 v43, v0
	v_mov_b32_e32 v48, v0
	v_mov_b32_e32 v49, v0
	v_mov_b32_e32 v50, v0
	v_mov_b32_e32 v51, v0
	v_mov_b32_e32 v56, v0
	v_mov_b32_e32 v57, v0
	v_mov_b32_e32 v58, v0
	v_mov_b32_e32 v59, v0
	v_mov_b32_e32 v60, v0
	v_mov_b32_e32 v61, v0
	v_mov_b32_e32 v62, v0
	v_mov_b32_e32 v63, v0
	v_mov_b32_e32 v64, v0
	v_mov_b32_e32 v65, v0
	v_mov_b32_e32 v66, v0
	v_mov_b32_e32 v67, v0
	v_mov_b32_e32 v68, v0
	v_mov_b32_e32 v69, v0
	v_mov_b32_e32 v70, v0
	v_mov_b32_e32 v71, v0
	v_mov_b32_e32 v76, v0
	v_mov_b32_e32 v77, v0
	v_mov_b32_e32 v78, v0
	v_mov_b32_e32 v79, v0
	v_mov_b32_e32 v84, v0
	v_mov_b32_e32 v85, v0
	v_mov_b32_e32 v86, v0
	v_mov_b32_e32 v87, v0
	v_mov_b32_e32 v92, v0
	v_mov_b32_e32 v93, v0
	v_mov_b32_e32 v94, v0
	v_mov_b32_e32 v95, v0
	v_mov_b32_e32 v100, v0
	v_mov_b32_e32 v101, v0
	v_mov_b32_e32 v102, v0
	v_mov_b32_e32 v103, v0
	v_mov_b32_e32 v108, v0
	v_mov_b32_e32 v109, v0
	v_mov_b32_e32 v110, v0
	v_mov_b32_e32 v111, v0
	v_mov_b32_e32 v116, v0
	v_mov_b32_e32 v117, v0
	v_mov_b32_e32 v118, v0
	v_mov_b32_e32 v119, v0
	v_mov_b32_e32 v72, v0
	v_mov_b32_e32 v73, v0
	v_mov_b32_e32 v74, v0
	v_mov_b32_e32 v75, v0
	v_mov_b32_e32 v80, v0
	v_mov_b32_e32 v81, v0
	v_mov_b32_e32 v82, v0
	v_mov_b32_e32 v83, v0
	v_mov_b32_e32 v88, v0
	v_mov_b32_e32 v89, v0
	v_mov_b32_e32 v90, v0
	v_mov_b32_e32 v91, v0
	v_mov_b32_e32 v96, v0
	v_mov_b32_e32 v97, v0
	v_mov_b32_e32 v98, v0
	v_mov_b32_e32 v99, v0
	v_mov_b32_e32 v104, v0
	v_mov_b32_e32 v105, v0
	v_mov_b32_e32 v106, v0
	v_mov_b32_e32 v107, v0
	v_mov_b32_e32 v112, v0
	v_mov_b32_e32 v113, v0
	v_mov_b32_e32 v114, v0
	v_mov_b32_e32 v115, v0
	v_mov_b32_e32 v120, v0
	v_mov_b32_e32 v121, v0
	v_mov_b32_e32 v122, v0
	v_mov_b32_e32 v123, v0
	v_mov_b32_e32 v124, v0
	v_mov_b32_e32 v125, v0
	v_mov_b32_e32 v126, v0
	v_mov_b32_e32 v127, v0
